# GEMM K-loops: hipcc's per-cluster s_setprio 1/0 toggles removed (288 instructions); everything else unchanged
# speedup vs baseline: 1.0102x; 1.0029x over previous
.LBB0_159:
	ds_read_b128 v[180:183], v171
	ds_read_b128 v[184:187], v171 offset:1024
	ds_read_b128 v[188:191], v171 offset:2048
	ds_read_b128 v[192:195], v171 offset:3072
	v_add_u32_e32 v177, 0xc000, v152
	v_lshl_add_u64 v[244:245], s[6:7], 0, v[144:145]
	v_readfirstlane_b32 s47, v177
	v_add_u32_e32 v178, 0xe000, v152
	v_lshl_add_u64 v[172:173], v[244:245], 0, s[18:19]
	s_mov_b32 m0, s47
	v_lshl_add_u64 v[246:247], s[6:7], 0, v[142:143]
	v_readfirstlane_b32 s47, v178
	ds_read_b128 v[196:199], v163
	ds_read_b128 v[200:203], v163 offset:1024
	ds_read_b128 v[204:207], v162
	ds_read_b128 v[208:211], v162 offset:1024
	ds_read_b128 v[212:215], v161
	ds_read_b128 v[216:219], v161 offset:1024
	ds_read_b128 v[220:223], v160
	ds_read_b128 v[224:227], v160 offset:1024
	global_load_lds_dwordx4 v[172:173], off
	v_lshl_add_u64 v[172:173], v[246:247], 0, s[18:19]
	s_mov_b32 m0, s47
	s_nop 0
	global_load_lds_dwordx4 v[172:173], off
	s_waitcnt lgkmcnt(8)
	s_barrier
	s_waitcnt lgkmcnt(0)
	s_waitcnt lgkmcnt(0)
	v_mfma_f32_16x16x32_bf16 v[124:127], v[180:183], v[196:199], v[124:127]
	v_mfma_f32_16x16x32_bf16 v[120:123], v[188:191], v[196:199], v[120:123]
	v_mfma_f32_16x16x32_bf16 v[116:119], v[180:183], v[204:207], v[116:119]
	v_mfma_f32_16x16x32_bf16 v[112:115], v[188:191], v[204:207], v[112:115]
	v_mfma_f32_16x16x32_bf16 v[108:111], v[180:183], v[212:215], v[108:111]
	v_mfma_f32_16x16x32_bf16 v[104:107], v[188:191], v[212:215], v[104:107]
	v_mfma_f32_16x16x32_bf16 v[100:103], v[180:183], v[220:223], v[100:103]
	v_mfma_f32_16x16x32_bf16 v[96:99], v[188:191], v[220:223], v[96:99]
	v_mfma_f32_16x16x32_bf16 v[124:127], v[184:187], v[200:203], v[124:127]
	v_mfma_f32_16x16x32_bf16 v[120:123], v[192:195], v[200:203], v[120:123]
	v_mfma_f32_16x16x32_bf16 v[116:119], v[184:187], v[208:211], v[116:119]
	v_mfma_f32_16x16x32_bf16 v[112:115], v[192:195], v[208:211], v[112:115]
	v_mfma_f32_16x16x32_bf16 v[108:111], v[184:187], v[216:219], v[108:111]
	v_mfma_f32_16x16x32_bf16 v[104:107], v[192:195], v[216:219], v[104:107]
	v_mfma_f32_16x16x32_bf16 v[100:103], v[184:187], v[224:227], v[100:103]
	v_mfma_f32_16x16x32_bf16 v[96:99], v[192:195], v[224:227], v[96:99]
	s_barrier
	v_lshl_add_u64 v[248:249], s[6:7], 0, v[148:149]
	v_readfirstlane_b32 s47, v153
	v_lshl_add_u64 v[172:173], v[248:249], 0, s[20:21]
	s_mov_b32 m0, s47
	ds_read_b128 v[228:231], v169
	ds_read_b128 v[232:235], v169 offset:1024
	ds_read_b128 v[236:239], v169 offset:2048
	ds_read_b128 v[240:243], v169 offset:3072
	global_load_lds_dwordx4 v[172:173], off
	v_add_u32_e32 v172, 0x2000, v153
	v_lshl_add_u64 v[250:251], s[6:7], 0, v[146:147]
	v_readfirstlane_b32 s47, v172
	v_lshl_add_u64 v[174:175], v[250:251], 0, s[20:21]
	s_mov_b32 m0, s47
	s_nop 0
	global_load_lds_dwordx4 v[174:175], off
	s_barrier
	s_waitcnt lgkmcnt(0)
	s_waitcnt lgkmcnt(0)
	v_mfma_f32_16x16x32_bf16 v[92:95], v[228:231], v[196:199], v[92:95]
	v_mfma_f32_16x16x32_bf16 v[88:91], v[236:239], v[196:199], v[88:91]
	v_mfma_f32_16x16x32_bf16 v[84:87], v[228:231], v[204:207], v[84:87]
	v_mfma_f32_16x16x32_bf16 v[80:83], v[236:239], v[204:207], v[80:83]
	v_mfma_f32_16x16x32_bf16 v[76:79], v[228:231], v[212:215], v[76:79]
	v_mfma_f32_16x16x32_bf16 v[72:75], v[236:239], v[212:215], v[72:75]
	v_mfma_f32_16x16x32_bf16 v[68:71], v[228:231], v[220:223], v[68:71]
	v_mfma_f32_16x16x32_bf16 v[64:67], v[236:239], v[220:223], v[64:67]
	v_mfma_f32_16x16x32_bf16 v[92:95], v[232:235], v[200:203], v[92:95]
	v_mfma_f32_16x16x32_bf16 v[88:91], v[240:243], v[200:203], v[88:91]
	v_mfma_f32_16x16x32_bf16 v[84:87], v[232:235], v[208:211], v[84:87]
	v_mfma_f32_16x16x32_bf16 v[80:83], v[240:243], v[208:211], v[80:83]
	v_mfma_f32_16x16x32_bf16 v[76:79], v[232:235], v[216:219], v[76:79]
	v_mfma_f32_16x16x32_bf16 v[72:75], v[240:243], v[216:219], v[72:75]
	v_mfma_f32_16x16x32_bf16 v[68:71], v[232:235], v[224:227], v[68:71]
	v_mfma_f32_16x16x32_bf16 v[64:67], v[240:243], v[224:227], v[64:67]
	v_readfirstlane_b32 s47, v152
	v_add_u32_e32 v173, 0x2000, v152
	v_lshl_add_u64 v[174:175], v[244:245], 0, s[22:23]
	s_mov_b32 m0, s47
	v_readfirstlane_b32 s47, v173
	s_barrier
	ds_read_b128 v[196:199], v163 offset:16384
	ds_read_b128 v[200:203], v163 offset:17408
	ds_read_b128 v[204:207], v162 offset:16384
	ds_read_b128 v[208:211], v162 offset:17408
	ds_read_b128 v[212:215], v161 offset:16384
	ds_read_b128 v[216:219], v161 offset:17408
	ds_read_b128 v[220:223], v160 offset:16384
	ds_read_b128 v[224:227], v160 offset:17408
	global_load_lds_dwordx4 v[174:175], off
	v_lshl_add_u64 v[174:175], v[246:247], 0, s[22:23]
	s_mov_b32 m0, s47
	s_nop 0
	global_load_lds_dwordx4 v[174:175], off
	s_barrier
	s_waitcnt lgkmcnt(0)
	s_waitcnt lgkmcnt(0)
	v_mfma_f32_16x16x32_bf16 v[60:63], v[180:183], v[196:199], v[60:63]
	v_mfma_f32_16x16x32_bf16 v[56:59], v[188:191], v[196:199], v[56:59]
	v_mfma_f32_16x16x32_bf16 v[52:55], v[180:183], v[204:207], v[52:55]
	v_mfma_f32_16x16x32_bf16 v[48:51], v[188:191], v[204:207], v[48:51]
	v_mfma_f32_16x16x32_bf16 v[44:47], v[180:183], v[212:215], v[44:47]
	v_mfma_f32_16x16x32_bf16 v[40:43], v[188:191], v[212:215], v[40:43]
	v_mfma_f32_16x16x32_bf16 v[36:39], v[180:183], v[220:223], v[36:39]
	v_mfma_f32_16x16x32_bf16 v[32:35], v[188:191], v[220:223], v[32:35]
	v_mfma_f32_16x16x32_bf16 v[60:63], v[184:187], v[200:203], v[60:63]
	v_mfma_f32_16x16x32_bf16 v[56:59], v[192:195], v[200:203], v[56:59]
	v_mfma_f32_16x16x32_bf16 v[52:55], v[184:187], v[208:211], v[52:55]
	v_mfma_f32_16x16x32_bf16 v[48:51], v[192:195], v[208:211], v[48:51]
	v_mfma_f32_16x16x32_bf16 v[44:47], v[184:187], v[216:219], v[44:47]
	v_mfma_f32_16x16x32_bf16 v[40:43], v[192:195], v[216:219], v[40:43]
	v_mfma_f32_16x16x32_bf16 v[36:39], v[184:187], v[224:227], v[36:39]
	v_mfma_f32_16x16x32_bf16 v[32:35], v[192:195], v[224:227], v[32:35]
	s_barrier
	v_readfirstlane_b32 s47, v151
	v_lshl_add_u64 v[174:175], v[248:249], 0, s[24:25]
	s_mov_b32 m0, s47
	v_lshl_add_u64 v[180:181], v[250:251], 0, s[24:25]
	global_load_lds_dwordx4 v[174:175], off
	v_add_u32_e32 v174, 0x2000, v151
	s_nop 0
	v_readfirstlane_b32 s47, v174
	s_mov_b32 m0, s47
	s_nop 0
	global_load_lds_dwordx4 v[180:181], off
	s_waitcnt vmcnt(6)
	s_barrier
	v_mfma_f32_16x16x32_bf16 v[28:31], v[228:231], v[196:199], v[28:31]
	v_mfma_f32_16x16x32_bf16 v[24:27], v[236:239], v[196:199], v[24:27]
	v_mfma_f32_16x16x32_bf16 v[20:23], v[228:231], v[204:207], v[20:23]
	v_mfma_f32_16x16x32_bf16 v[16:19], v[236:239], v[204:207], v[16:19]
	v_mfma_f32_16x16x32_bf16 v[12:15], v[228:231], v[212:215], v[12:15]
	v_mfma_f32_16x16x32_bf16 v[8:11], v[236:239], v[212:215], v[8:11]
	v_mfma_f32_16x16x32_bf16 v[4:7], v[228:231], v[220:223], v[4:7]
	v_mfma_f32_16x16x32_bf16 v[0:3], v[236:239], v[220:223], v[0:3]
	v_mfma_f32_16x16x32_bf16 v[28:31], v[232:235], v[200:203], v[28:31]
	v_mfma_f32_16x16x32_bf16 v[24:27], v[240:243], v[200:203], v[24:27]
	v_mfma_f32_16x16x32_bf16 v[20:23], v[232:235], v[208:211], v[20:23]
	v_mfma_f32_16x16x32_bf16 v[16:19], v[240:243], v[208:211], v[16:19]
	v_mfma_f32_16x16x32_bf16 v[12:15], v[232:235], v[216:219], v[12:15]
	v_mfma_f32_16x16x32_bf16 v[8:11], v[240:243], v[216:219], v[8:11]
	v_mfma_f32_16x16x32_bf16 v[4:7], v[232:235], v[224:227], v[4:7]
	v_mfma_f32_16x16x32_bf16 v[0:3], v[240:243], v[224:227], v[0:3]
	s_barrier
	ds_read_b128 v[180:183], v165
	ds_read_b128 v[184:187], v165 offset:1024
	ds_read_b128 v[188:191], v165 offset:2048
	ds_read_b128 v[192:195], v165 offset:3072
	v_add_u32_e32 v175, 0x4000, v152
	v_add_u32_e32 v176, 0x6000, v152
	v_readfirstlane_b32 s47, v175
	v_lshl_add_u64 v[228:229], v[244:245], 0, s[28:29]
	s_mov_b32 m0, s47
	v_readfirstlane_b32 s47, v176
	ds_read_b128 v[196:199], v163 offset:32768
	ds_read_b128 v[200:203], v163 offset:33792
	ds_read_b128 v[204:207], v162 offset:32768
	ds_read_b128 v[208:211], v162 offset:33792
	ds_read_b128 v[212:215], v161 offset:32768
	ds_read_b128 v[216:219], v161 offset:33792
	ds_read_b128 v[220:223], v160 offset:32768
	ds_read_b128 v[224:227], v160 offset:33792
	global_load_lds_dwordx4 v[228:229], off
	v_lshl_add_u64 v[228:229], v[246:247], 0, s[28:29]
	s_mov_b32 m0, s47
	s_nop 0
	global_load_lds_dwordx4 v[228:229], off
	s_waitcnt lgkmcnt(8)
	s_barrier
	s_waitcnt lgkmcnt(0)
	s_waitcnt lgkmcnt(0)
	v_mfma_f32_16x16x32_bf16 v[124:127], v[180:183], v[196:199], v[124:127]
	v_mfma_f32_16x16x32_bf16 v[120:123], v[188:191], v[196:199], v[120:123]
	v_mfma_f32_16x16x32_bf16 v[116:119], v[180:183], v[204:207], v[116:119]
	v_mfma_f32_16x16x32_bf16 v[112:115], v[188:191], v[204:207], v[112:115]
	v_mfma_f32_16x16x32_bf16 v[108:111], v[180:183], v[212:215], v[108:111]
	v_mfma_f32_16x16x32_bf16 v[104:107], v[188:191], v[212:215], v[104:107]
	v_mfma_f32_16x16x32_bf16 v[100:103], v[180:183], v[220:223], v[100:103]
	v_mfma_f32_16x16x32_bf16 v[96:99], v[188:191], v[220:223], v[96:99]
	v_mfma_f32_16x16x32_bf16 v[124:127], v[184:187], v[200:203], v[124:127]
	v_mfma_f32_16x16x32_bf16 v[120:123], v[192:195], v[200:203], v[120:123]
	v_mfma_f32_16x16x32_bf16 v[116:119], v[184:187], v[208:211], v[116:119]
	v_mfma_f32_16x16x32_bf16 v[112:115], v[192:195], v[208:211], v[112:115]
	v_mfma_f32_16x16x32_bf16 v[108:111], v[184:187], v[216:219], v[108:111]
	v_mfma_f32_16x16x32_bf16 v[104:107], v[192:195], v[216:219], v[104:107]
	v_mfma_f32_16x16x32_bf16 v[100:103], v[184:187], v[224:227], v[100:103]
	v_mfma_f32_16x16x32_bf16 v[96:99], v[192:195], v[224:227], v[96:99]
	s_barrier
	v_readfirstlane_b32 s47, v166
	v_add_u32_e32 v179, 0x2000, v166
	v_lshl_add_u64 v[252:253], v[248:249], 0, s[30:31]
	s_mov_b32 m0, s47
	v_readfirstlane_b32 s47, v179
	ds_read_b128 v[228:231], v164
	ds_read_b128 v[232:235], v164 offset:1024
	ds_read_b128 v[236:239], v164 offset:2048
	ds_read_b128 v[240:243], v164 offset:3072
	global_load_lds_dwordx4 v[252:253], off
	v_lshl_add_u64 v[252:253], v[250:251], 0, s[30:31]
	s_mov_b32 m0, s47
	s_nop 0
	global_load_lds_dwordx4 v[252:253], off
	s_barrier
	s_waitcnt lgkmcnt(0)
	s_waitcnt lgkmcnt(0)
	v_mfma_f32_16x16x32_bf16 v[92:95], v[228:231], v[196:199], v[92:95]
	v_mfma_f32_16x16x32_bf16 v[88:91], v[236:239], v[196:199], v[88:91]
	v_mfma_f32_16x16x32_bf16 v[84:87], v[228:231], v[204:207], v[84:87]
	v_mfma_f32_16x16x32_bf16 v[80:83], v[236:239], v[204:207], v[80:83]
	v_mfma_f32_16x16x32_bf16 v[76:79], v[228:231], v[212:215], v[76:79]
	v_mfma_f32_16x16x32_bf16 v[72:75], v[236:239], v[212:215], v[72:75]
	v_mfma_f32_16x16x32_bf16 v[68:71], v[228:231], v[220:223], v[68:71]
	v_mfma_f32_16x16x32_bf16 v[64:67], v[236:239], v[220:223], v[64:67]
	v_mfma_f32_16x16x32_bf16 v[92:95], v[232:235], v[200:203], v[92:95]
	v_mfma_f32_16x16x32_bf16 v[88:91], v[240:243], v[200:203], v[88:91]
	v_mfma_f32_16x16x32_bf16 v[84:87], v[232:235], v[208:211], v[84:87]
	v_mfma_f32_16x16x32_bf16 v[80:83], v[240:243], v[208:211], v[80:83]
	v_mfma_f32_16x16x32_bf16 v[76:79], v[232:235], v[216:219], v[76:79]
	v_mfma_f32_16x16x32_bf16 v[72:75], v[240:243], v[216:219], v[72:75]
	v_mfma_f32_16x16x32_bf16 v[68:71], v[232:235], v[224:227], v[68:71]
	v_mfma_f32_16x16x32_bf16 v[64:67], v[240:243], v[224:227], v[64:67]
	v_readfirstlane_b32 s47, v167
	v_lshl_add_u64 v[244:245], v[244:245], 0, s[38:39]
	s_mov_b32 m0, s47
	v_readfirstlane_b32 s47, v168
	s_barrier
	ds_read_b128 v[196:199], v163 offset:49152
	ds_read_b128 v[200:203], v163 offset:50176
	ds_read_b128 v[204:207], v162 offset:49152
	ds_read_b128 v[208:211], v162 offset:50176
	ds_read_b128 v[212:215], v161 offset:49152
	ds_read_b128 v[216:219], v161 offset:50176
	ds_read_b128 v[220:223], v160 offset:49152
	ds_read_b128 v[224:227], v160 offset:50176
	global_load_lds_dwordx4 v[244:245], off
	v_lshl_add_u64 v[244:245], v[246:247], 0, s[38:39]
	s_mov_b32 m0, s47
	s_nop 0
	global_load_lds_dwordx4 v[244:245], off
	s_barrier
	s_waitcnt lgkmcnt(0)
	s_waitcnt lgkmcnt(0)
	v_mfma_f32_16x16x32_bf16 v[60:63], v[180:183], v[196:199], v[60:63]
	v_mfma_f32_16x16x32_bf16 v[56:59], v[188:191], v[196:199], v[56:59]
	v_mfma_f32_16x16x32_bf16 v[52:55], v[180:183], v[204:207], v[52:55]
	v_mfma_f32_16x16x32_bf16 v[48:51], v[188:191], v[204:207], v[48:51]
	v_mfma_f32_16x16x32_bf16 v[44:47], v[180:183], v[212:215], v[44:47]
	v_mfma_f32_16x16x32_bf16 v[40:43], v[188:191], v[212:215], v[40:43]
	v_mfma_f32_16x16x32_bf16 v[36:39], v[180:183], v[220:223], v[36:39]
	v_mfma_f32_16x16x32_bf16 v[32:35], v[188:191], v[220:223], v[32:35]
	v_mfma_f32_16x16x32_bf16 v[60:63], v[184:187], v[200:203], v[60:63]
	v_mfma_f32_16x16x32_bf16 v[56:59], v[192:195], v[200:203], v[56:59]
	v_mfma_f32_16x16x32_bf16 v[52:55], v[184:187], v[208:211], v[52:55]
	v_mfma_f32_16x16x32_bf16 v[48:51], v[192:195], v[208:211], v[48:51]
	v_mfma_f32_16x16x32_bf16 v[44:47], v[184:187], v[216:219], v[44:47]
	v_mfma_f32_16x16x32_bf16 v[40:43], v[192:195], v[216:219], v[40:43]
	v_mfma_f32_16x16x32_bf16 v[36:39], v[184:187], v[224:227], v[36:39]
	v_mfma_f32_16x16x32_bf16 v[32:35], v[192:195], v[224:227], v[32:35]
	s_barrier
	v_readfirstlane_b32 s47, v170
	v_add_u32_e32 v179, 0x2000, v170
	v_lshl_add_u64 v[180:181], v[248:249], 0, s[40:41]
	s_mov_b32 m0, s47
	v_readfirstlane_b32 s47, v179
	global_load_lds_dwordx4 v[180:181], off
	v_lshl_add_u64 v[180:181], v[250:251], 0, s[40:41]
	s_mov_b32 m0, s47
	s_nop 0
	global_load_lds_dwordx4 v[180:181], off
	s_waitcnt vmcnt(6)
	s_barrier
	v_mfma_f32_16x16x32_bf16 v[28:31], v[228:231], v[196:199], v[28:31]
	v_mfma_f32_16x16x32_bf16 v[24:27], v[236:239], v[196:199], v[24:27]
	v_mfma_f32_16x16x32_bf16 v[20:23], v[228:231], v[204:207], v[20:23]
	v_mfma_f32_16x16x32_bf16 v[16:19], v[236:239], v[204:207], v[16:19]
	v_mfma_f32_16x16x32_bf16 v[12:15], v[228:231], v[212:215], v[12:15]
	v_mfma_f32_16x16x32_bf16 v[8:11], v[236:239], v[212:215], v[8:11]
	v_mfma_f32_16x16x32_bf16 v[4:7], v[228:231], v[220:223], v[4:7]
	v_mfma_f32_16x16x32_bf16 v[0:3], v[236:239], v[220:223], v[0:3]
	v_mfma_f32_16x16x32_bf16 v[28:31], v[232:235], v[200:203], v[28:31]
	v_mfma_f32_16x16x32_bf16 v[24:27], v[240:243], v[200:203], v[24:27]
	v_mfma_f32_16x16x32_bf16 v[20:23], v[232:235], v[208:211], v[20:23]
	v_mfma_f32_16x16x32_bf16 v[16:19], v[240:243], v[208:211], v[16:19]
	v_mfma_f32_16x16x32_bf16 v[12:15], v[232:235], v[216:219], v[12:15]
	v_mfma_f32_16x16x32_bf16 v[8:11], v[240:243], v[216:219], v[8:11]
	v_mfma_f32_16x16x32_bf16 v[4:7], v[232:235], v[224:227], v[4:7]
	v_mfma_f32_16x16x32_bf16 v[0:3], v[240:243], v[224:227], v[0:3]
	s_add_i32 s14, s14, 2
	v_lshl_add_u64 v[142:143], v[142:143], 0, s[42:43]
	v_lshl_add_u64 v[144:145], v[144:145], 0, s[42:43]
	v_lshl_add_u64 v[146:147], v[146:147], 0, s[42:43]
	s_cmp_lt_u32 s14, 12
	v_lshl_add_u64 v[148:149], v[148:149], 0, s[42:43]
	s_barrier
	s_cbranch_scc1 .LBB0_159
	s_or_b32 s50, s48, 0x80
	s_ashr_i32 s51, s50, 31
	s_lshl_b64 s[50:51], s[50:51], 11
	s_add_u32 s50, s8, s50
	s_addc_u32 s51, s33, s51
	v_lshl_add_u64 v[166:167], s[50:51], 0, v[130:131]
	v_lshl_add_u64 v[138:139], v[138:139], 1, v[166:167]
	v_readfirstlane_b32 s14, v177
	v_lshl_add_u64 v[138:139], v[138:139], 0, s[44:45]
	s_mov_b32 m0, s14
	ds_read_b128 v[142:145], v171
	ds_read_b128 v[146:149], v171 offset:1024
	ds_read_b128 v[180:183], v171 offset:2048
	ds_read_b128 v[184:187], v171 offset:3072
	ds_read_b128 v[188:191], v163
	ds_read_b128 v[192:195], v163 offset:1024
	ds_read_b128 v[196:199], v162
	ds_read_b128 v[200:203], v162 offset:1024
	ds_read_b128 v[204:207], v161
	ds_read_b128 v[208:211], v161 offset:1024
	ds_read_b128 v[212:215], v160
	ds_read_b128 v[216:219], v160 offset:1024
	global_load_lds_dwordx4 v[138:139], off
	v_lshl_add_u64 v[138:139], s[50:51], 0, v[134:135]
	v_lshl_add_u64 v[138:139], v[140:141], 1, v[138:139]
	v_readfirstlane_b32 s14, v178
	v_lshl_add_u64 v[138:139], v[138:139], 0, s[44:45]
	s_mov_b32 m0, s14
	s_nop 0
	global_load_lds_dwordx4 v[138:139], off
	s_barrier
	s_waitcnt lgkmcnt(0)
	s_waitcnt lgkmcnt(0)
	v_mfma_f32_16x16x32_bf16 v[124:127], v[142:145], v[188:191], v[124:127]
	v_mfma_f32_16x16x32_bf16 v[120:123], v[180:183], v[188:191], v[120:123]
	v_mfma_f32_16x16x32_bf16 v[116:119], v[142:145], v[196:199], v[116:119]
	v_mfma_f32_16x16x32_bf16 v[112:115], v[180:183], v[196:199], v[112:115]
	v_mfma_f32_16x16x32_bf16 v[108:111], v[142:145], v[204:207], v[108:111]
	v_mfma_f32_16x16x32_bf16 v[104:107], v[180:183], v[204:207], v[104:107]
	v_mfma_f32_16x16x32_bf16 v[100:103], v[142:145], v[212:215], v[100:103]
	v_mfma_f32_16x16x32_bf16 v[124:127], v[146:149], v[192:195], v[124:127]
	v_mfma_f32_16x16x32_bf16 v[120:123], v[184:187], v[192:195], v[120:123]
	v_mfma_f32_16x16x32_bf16 v[116:119], v[146:149], v[200:203], v[116:119]
	v_mfma_f32_16x16x32_bf16 v[112:115], v[184:187], v[200:203], v[112:115]
	v_mfma_f32_16x16x32_bf16 v[108:111], v[146:149], v[208:211], v[108:111]
	v_mfma_f32_16x16x32_bf16 v[104:107], v[184:187], v[208:211], v[104:107]
	v_mfma_f32_16x16x32_bf16 v[100:103], v[146:149], v[216:219], v[100:103]
	v_mfma_f32_16x16x32_bf16 v[96:99], v[180:183], v[212:215], v[96:99]
	v_mfma_f32_16x16x32_bf16 v[138:141], v[184:187], v[216:219], v[96:99]
	s_barrier
	s_nop 4
	ds_read_b128 v[96:99], v169
	ds_read_b128 v[220:223], v169 offset:1024
	ds_read_b128 v[224:227], v169 offset:2048
	ds_read_b128 v[166:169], v169 offset:3072
	s_barrier
	s_waitcnt lgkmcnt(0)
	s_waitcnt lgkmcnt(0)
	v_mfma_f32_16x16x32_bf16 v[92:95], v[96:99], v[188:191], v[92:95]
	v_mfma_f32_16x16x32_bf16 v[88:91], v[224:227], v[188:191], v[88:91]
	v_mfma_f32_16x16x32_bf16 v[80:83], v[224:227], v[196:199], v[80:83]
	v_mfma_f32_16x16x32_bf16 v[76:79], v[96:99], v[204:207], v[76:79]
	v_mfma_f32_16x16x32_bf16 v[64:67], v[224:227], v[212:215], v[64:67]
	v_mfma_f32_16x16x32_bf16 v[92:95], v[220:223], v[192:195], v[92:95]
	v_mfma_f32_16x16x32_bf16 v[88:91], v[166:169], v[192:195], v[88:91]
	v_mfma_f32_16x16x32_bf16 v[84:87], v[96:99], v[196:199], v[84:87]
	v_mfma_f32_16x16x32_bf16 v[80:83], v[166:169], v[200:203], v[80:83]
	v_mfma_f32_16x16x32_bf16 v[76:79], v[220:223], v[208:211], v[76:79]
	v_mfma_f32_16x16x32_bf16 v[72:75], v[224:227], v[204:207], v[72:75]
	v_mfma_f32_16x16x32_bf16 v[68:71], v[96:99], v[212:215], v[68:71]
	v_mfma_f32_16x16x32_bf16 v[64:67], v[166:169], v[216:219], v[64:67]
	v_mfma_f32_16x16x32_bf16 v[188:191], v[220:223], v[200:203], v[84:87]
	v_mfma_f32_16x16x32_bf16 v[192:195], v[166:169], v[208:211], v[72:75]
	v_mfma_f32_16x16x32_bf16 v[196:199], v[220:223], v[216:219], v[68:71]
	s_barrier
	s_nop 1
	ds_read_b128 v[68:71], v163 offset:16384
	ds_read_b128 v[72:75], v163 offset:17408
	ds_read_b128 v[84:87], v162 offset:16384
	ds_read_b128 v[200:203], v162 offset:17408
	ds_read_b128 v[204:207], v161 offset:16384
	ds_read_b128 v[208:211], v161 offset:17408
	ds_read_b128 v[212:215], v160 offset:16384
	ds_read_b128 v[216:219], v160 offset:17408
	s_waitcnt vmcnt(4)
	s_barrier
	s_waitcnt lgkmcnt(0)
	s_waitcnt lgkmcnt(0)
	v_mfma_f32_16x16x32_bf16 v[56:59], v[180:183], v[68:71], v[56:59]
	v_mfma_f32_16x16x32_bf16 v[48:51], v[180:183], v[84:87], v[48:51]
	v_mfma_f32_16x16x32_bf16 v[44:47], v[142:145], v[204:207], v[44:47]
	v_mfma_f32_16x16x32_bf16 v[40:43], v[180:183], v[204:207], v[40:43]
	v_mfma_f32_16x16x32_bf16 v[36:39], v[142:145], v[212:215], v[36:39]
	v_mfma_f32_16x16x32_bf16 v[32:35], v[180:183], v[212:215], v[32:35]
	v_mfma_f32_16x16x32_bf16 v[60:63], v[142:145], v[68:71], v[60:63]
	v_mfma_f32_16x16x32_bf16 v[56:59], v[184:187], v[72:75], v[56:59]
	v_mfma_f32_16x16x32_bf16 v[52:55], v[142:145], v[84:87], v[52:55]
	v_mfma_f32_16x16x32_bf16 v[48:51], v[184:187], v[200:203], v[48:51]
	v_mfma_f32_16x16x32_bf16 v[44:47], v[146:149], v[208:211], v[44:47]
	v_mfma_f32_16x16x32_bf16 v[40:43], v[184:187], v[208:211], v[40:43]
	v_mfma_f32_16x16x32_bf16 v[36:39], v[146:149], v[216:219], v[36:39]
	v_mfma_f32_16x16x32_bf16 v[32:35], v[184:187], v[216:219], v[32:35]
	v_mfma_f32_16x16x32_bf16 v[228:231], v[146:149], v[72:75], v[60:63]
	v_mfma_f32_16x16x32_bf16 v[232:235], v[146:149], v[200:203], v[52:55]
	v_mfma_f32_16x16x32_bf16 v[28:31], v[96:99], v[68:71], v[28:31]
	v_mfma_f32_16x16x32_bf16 v[24:27], v[224:227], v[68:71], v[24:27]
	v_mfma_f32_16x16x32_bf16 v[20:23], v[96:99], v[84:87], v[20:23]
	v_mfma_f32_16x16x32_bf16 v[16:19], v[224:227], v[84:87], v[16:19]
	v_mfma_f32_16x16x32_bf16 v[12:15], v[96:99], v[204:207], v[12:15]
	v_mfma_f32_16x16x32_bf16 v[8:11], v[224:227], v[204:207], v[8:11]
	v_mfma_f32_16x16x32_bf16 v[4:7], v[96:99], v[212:215], v[4:7]
	v_mfma_f32_16x16x32_bf16 v[0:3], v[224:227], v[212:215], v[0:3]
	v_mfma_f32_16x16x32_bf16 v[28:31], v[220:223], v[72:75], v[28:31]
	v_mfma_f32_16x16x32_bf16 v[24:27], v[166:169], v[72:75], v[24:27]
	v_mfma_f32_16x16x32_bf16 v[20:23], v[220:223], v[200:203], v[20:23]
	v_mfma_f32_16x16x32_bf16 v[16:19], v[166:169], v[200:203], v[16:19]
	v_mfma_f32_16x16x32_bf16 v[12:15], v[220:223], v[208:211], v[12:15]
	v_mfma_f32_16x16x32_bf16 v[8:11], v[166:169], v[208:211], v[8:11]
	v_mfma_f32_16x16x32_bf16 v[4:7], v[220:223], v[216:219], v[4:7]
	v_mfma_f32_16x16x32_bf16 v[0:3], v[166:169], v[216:219], v[0:3]
	s_barrier
	ds_read_b128 v[142:145], v165
	ds_read_b128 v[146:149], v165 offset:1024
	ds_read_b128 v[166:169], v165 offset:2048
	ds_read_b128 v[178:181], v165 offset:3072
	ds_read_b128 v[52:55], v163 offset:32768
	ds_read_b128 v[60:63], v163 offset:33792
	ds_read_b128 v[68:71], v162 offset:32768
	ds_read_b128 v[72:75], v162 offset:33792
	ds_read_b128 v[182:185], v161 offset:32768
	ds_read_b128 v[200:203], v161 offset:33792
	ds_read_b128 v[204:207], v160 offset:32768
	ds_read_b128 v[208:211], v160 offset:33792
	s_waitcnt vmcnt(2)
	s_barrier
	s_waitcnt lgkmcnt(0)
	s_waitcnt lgkmcnt(0)
	v_mfma_f32_16x16x32_bf16 v[84:87], v[142:145], v[52:55], v[124:127]
	v_mfma_f32_16x16x32_bf16 v[124:127], v[146:149], v[60:63], v[84:87]
	v_mfma_f32_16x16x32_bf16 v[84:87], v[166:169], v[52:55], v[120:123]
	v_mfma_f32_16x16x32_bf16 v[120:123], v[178:181], v[60:63], v[84:87]
	v_mfma_f32_16x16x32_bf16 v[84:87], v[142:145], v[68:71], v[116:119]
	v_mfma_f32_16x16x32_bf16 v[116:119], v[146:149], v[72:75], v[84:87]
	v_mfma_f32_16x16x32_bf16 v[84:87], v[166:169], v[68:71], v[112:115]
	v_mfma_f32_16x16x32_bf16 v[112:115], v[178:181], v[72:75], v[84:87]
	v_mfma_f32_16x16x32_bf16 v[84:87], v[142:145], v[182:185], v[108:111]
	v_mfma_f32_16x16x32_bf16 v[108:111], v[146:149], v[200:203], v[84:87]
	v_mfma_f32_16x16x32_bf16 v[84:87], v[166:169], v[182:185], v[104:107]
	v_mfma_f32_16x16x32_bf16 v[104:107], v[178:181], v[200:203], v[84:87]
	v_mfma_f32_16x16x32_bf16 v[84:87], v[142:145], v[204:207], v[100:103]
	v_mfma_f32_16x16x32_bf16 v[96:99], v[146:149], v[208:211], v[84:87]
	v_mfma_f32_16x16x32_bf16 v[84:87], v[166:169], v[204:207], v[138:141]
	v_mfma_f32_16x16x32_bf16 v[84:87], v[178:181], v[208:211], v[84:87]
	s_barrier
	ds_read_b128 v[138:141], v164
	ds_read_b128 v[212:215], v164 offset:1024
	ds_read_b128 v[216:219], v164 offset:2048
	ds_read_b128 v[220:223], v164 offset:3072
	s_waitcnt vmcnt(0)
	s_barrier
	s_waitcnt lgkmcnt(0)
	s_waitcnt lgkmcnt(0)
	v_mfma_f32_16x16x32_bf16 v[92:95], v[138:141], v[52:55], v[92:95]
	v_mfma_f32_16x16x32_bf16 v[52:55], v[216:219], v[52:55], v[88:91]
	v_mfma_f32_16x16x32_bf16 v[100:103], v[212:215], v[60:63], v[92:95]
	v_mfma_f32_16x16x32_bf16 v[92:95], v[220:223], v[60:63], v[52:55]
	v_mfma_f32_16x16x32_bf16 v[52:55], v[138:141], v[68:71], v[188:191]
	v_mfma_f32_16x16x32_bf16 v[88:91], v[212:215], v[72:75], v[52:55]
	v_mfma_f32_16x16x32_bf16 v[52:55], v[216:219], v[68:71], v[80:83]
	v_mfma_f32_16x16x32_bf16 v[80:83], v[220:223], v[72:75], v[52:55]
	v_mfma_f32_16x16x32_bf16 v[52:55], v[138:141], v[182:185], v[76:79]
	v_mfma_f32_16x16x32_bf16 v[72:75], v[212:215], v[200:203], v[52:55]
	v_mfma_f32_16x16x32_bf16 v[52:55], v[216:219], v[182:185], v[192:195]
	v_mfma_f32_16x16x32_bf16 v[68:71], v[220:223], v[200:203], v[52:55]
	v_mfma_f32_16x16x32_bf16 v[52:55], v[138:141], v[204:207], v[196:199]
	v_mfma_f32_16x16x32_bf16 v[60:63], v[212:215], v[208:211], v[52:55]
	v_mfma_f32_16x16x32_bf16 v[52:55], v[216:219], v[204:207], v[64:67]
	v_mfma_f32_16x16x32_bf16 v[52:55], v[220:223], v[208:211], v[52:55]
	s_barrier
	ds_read_b128 v[182:185], v163 offset:49152
	ds_read_b128 v[186:189], v163 offset:50176
	ds_read_b128 v[190:193], v162 offset:49152
	ds_read_b128 v[162:165], v162 offset:50176
	ds_read_b128 v[194:197], v161 offset:49152
	ds_read_b128 v[198:201], v161 offset:50176
	ds_read_b128 v[202:205], v160 offset:49152
	ds_read_b128 v[206:209], v160 offset:50176
	s_barrier
	s_waitcnt lgkmcnt(0)
	s_waitcnt lgkmcnt(0)
	v_mfma_f32_16x16x32_bf16 v[64:67], v[142:145], v[182:185], v[228:231]
	v_mfma_f32_16x16x32_bf16 v[56:59], v[166:169], v[182:185], v[56:59]
	v_mfma_f32_16x16x32_bf16 v[76:79], v[146:149], v[186:189], v[64:67]
	v_mfma_f32_16x16x32_bf16 v[64:67], v[178:181], v[186:189], v[56:59]
	v_mfma_f32_16x16x32_bf16 v[56:59], v[142:145], v[190:193], v[232:235]
	v_mfma_f32_16x16x32_bf16 v[48:51], v[166:169], v[190:193], v[48:51]
	v_mfma_f32_16x16x32_bf16 v[44:47], v[142:145], v[194:197], v[44:47]
	v_mfma_f32_16x16x32_bf16 v[40:43], v[166:169], v[194:197], v[40:43]
	v_mfma_f32_16x16x32_bf16 v[36:39], v[142:145], v[202:205], v[36:39]
	v_mfma_f32_16x16x32_bf16 v[32:35], v[166:169], v[202:205], v[32:35]
	v_mfma_f32_16x16x32_bf16 v[56:59], v[146:149], v[162:165], v[56:59]
	v_mfma_f32_16x16x32_bf16 v[48:51], v[178:181], v[162:165], v[48:51]
	v_mfma_f32_16x16x32_bf16 v[44:47], v[146:149], v[198:201], v[44:47]
	v_mfma_f32_16x16x32_bf16 v[40:43], v[178:181], v[198:201], v[40:43]
	v_mfma_f32_16x16x32_bf16 v[36:39], v[146:149], v[206:209], v[36:39]
	v_mfma_f32_16x16x32_bf16 v[32:35], v[178:181], v[206:209], v[32:35]
	v_mfma_f32_16x16x32_bf16 v[28:31], v[138:141], v[182:185], v[28:31]
	v_mfma_f32_16x16x32_bf16 v[24:27], v[216:219], v[182:185], v[24:27]
	v_mfma_f32_16x16x32_bf16 v[20:23], v[138:141], v[190:193], v[20:23]
	v_mfma_f32_16x16x32_bf16 v[16:19], v[216:219], v[190:193], v[16:19]
	v_mfma_f32_16x16x32_bf16 v[12:15], v[138:141], v[194:197], v[12:15]
	v_mfma_f32_16x16x32_bf16 v[8:11], v[216:219], v[194:197], v[8:11]
	v_mfma_f32_16x16x32_bf16 v[4:7], v[138:141], v[202:205], v[4:7]
	v_mfma_f32_16x16x32_bf16 v[0:3], v[216:219], v[202:205], v[0:3]
	v_mfma_f32_16x16x32_bf16 v[28:31], v[212:215], v[186:189], v[28:31]
	v_mfma_f32_16x16x32_bf16 v[24:27], v[220:223], v[186:189], v[24:27]
	v_mfma_f32_16x16x32_bf16 v[20:23], v[212:215], v[162:165], v[20:23]
	v_mfma_f32_16x16x32_bf16 v[16:19], v[220:223], v[162:165], v[16:19]
	v_mfma_f32_16x16x32_bf16 v[12:15], v[212:215], v[198:201], v[12:15]
	v_mfma_f32_16x16x32_bf16 v[8:11], v[220:223], v[198:201], v[8:11]
	v_mfma_f32_16x16x32_bf16 v[4:7], v[212:215], v[206:209], v[4:7]
	v_mfma_f32_16x16x32_bf16 v[0:3], v[220:223], v[206:209], v[0:3]
	v_cmp_gt_u32_e32 vcc, s59, v155
	s_barrier
	s_and_saveexec_b64 s[50:51], vcc
	s_cbranch_execz .LBB0_162
	s_barrier

.LBB0_186:
	ds_read_b128 v[170:173], v167
	ds_read_b128 v[174:177], v167 offset:1024
	ds_read_b128 v[178:181], v167 offset:2048
	ds_read_b128 v[182:185], v167 offset:3072
	v_add_u32_e32 v168, 0xc000, v153
	v_lshl_add_u64 v[234:235], s[6:7], 0, v[136:137]
	v_readfirstlane_b32 s53, v168
	v_add_u32_e32 v169, 0xe000, v153
	v_lshl_add_u64 v[218:219], v[234:235], 0, s[10:11]
	s_mov_b32 m0, s53
	v_lshl_add_u64 v[236:237], s[6:7], 0, v[134:135]
	v_readfirstlane_b32 s53, v169
	ds_read_b128 v[186:189], v151
	ds_read_b128 v[190:193], v151 offset:1024
	ds_read_b128 v[194:197], v150
	ds_read_b128 v[198:201], v150 offset:1024
	ds_read_b128 v[202:205], v149
	ds_read_b128 v[206:209], v149 offset:1024
	ds_read_b128 v[210:213], v148
	ds_read_b128 v[214:217], v148 offset:1024
	global_load_lds_dwordx4 v[218:219], off
	v_lshl_add_u64 v[218:219], v[236:237], 0, s[10:11]
	s_mov_b32 m0, s53
	s_nop 0
	global_load_lds_dwordx4 v[218:219], off
	s_waitcnt lgkmcnt(8)
	s_barrier
	s_waitcnt lgkmcnt(0)
	s_waitcnt lgkmcnt(0)
	v_mfma_f32_16x16x32_bf16 v[124:127], v[170:173], v[186:189], v[124:127]
	v_mfma_f32_16x16x32_bf16 v[120:123], v[178:181], v[186:189], v[120:123]
	v_mfma_f32_16x16x32_bf16 v[116:119], v[170:173], v[194:197], v[116:119]
	v_mfma_f32_16x16x32_bf16 v[112:115], v[178:181], v[194:197], v[112:115]
	v_mfma_f32_16x16x32_bf16 v[108:111], v[170:173], v[202:205], v[108:111]
	v_mfma_f32_16x16x32_bf16 v[104:107], v[178:181], v[202:205], v[104:107]
	v_mfma_f32_16x16x32_bf16 v[100:103], v[170:173], v[210:213], v[100:103]
	v_mfma_f32_16x16x32_bf16 v[96:99], v[178:181], v[210:213], v[96:99]
	v_mfma_f32_16x16x32_bf16 v[124:127], v[174:177], v[190:193], v[124:127]
	v_mfma_f32_16x16x32_bf16 v[120:123], v[182:185], v[190:193], v[120:123]
	v_mfma_f32_16x16x32_bf16 v[116:119], v[174:177], v[198:201], v[116:119]
	v_mfma_f32_16x16x32_bf16 v[112:115], v[182:185], v[198:201], v[112:115]
	v_mfma_f32_16x16x32_bf16 v[108:111], v[174:177], v[206:209], v[108:111]
	v_mfma_f32_16x16x32_bf16 v[104:107], v[182:185], v[206:209], v[104:107]
	v_mfma_f32_16x16x32_bf16 v[100:103], v[174:177], v[214:217], v[100:103]
	v_mfma_f32_16x16x32_bf16 v[96:99], v[182:185], v[214:217], v[96:99]
	s_barrier
	v_lshl_add_u64 v[238:239], s[6:7], 0, v[140:141]
	v_readfirstlane_b32 s53, v147
	v_lshl_add_u64 v[240:241], v[238:239], 0, s[12:13]
	s_mov_b32 m0, s53
	v_add_u32_e32 v244, 0x2000, v147
	ds_read_b128 v[218:221], v165
	ds_read_b128 v[222:225], v165 offset:1024
	ds_read_b128 v[226:229], v165 offset:2048
	ds_read_b128 v[230:233], v165 offset:3072
	global_load_lds_dwordx4 v[240:241], off
	v_lshl_add_u64 v[240:241], s[6:7], 0, v[138:139]
	v_readfirstlane_b32 s53, v244
	v_lshl_add_u64 v[242:243], v[240:241], 0, s[12:13]
	s_mov_b32 m0, s53
	s_nop 0
	global_load_lds_dwordx4 v[242:243], off
	s_barrier
	s_waitcnt lgkmcnt(0)
	s_waitcnt lgkmcnt(0)
	v_mfma_f32_16x16x32_bf16 v[92:95], v[218:221], v[186:189], v[92:95]
	v_mfma_f32_16x16x32_bf16 v[88:91], v[226:229], v[186:189], v[88:91]
	v_mfma_f32_16x16x32_bf16 v[84:87], v[218:221], v[194:197], v[84:87]
	v_mfma_f32_16x16x32_bf16 v[80:83], v[226:229], v[194:197], v[80:83]
	v_mfma_f32_16x16x32_bf16 v[76:79], v[218:221], v[202:205], v[76:79]
	v_mfma_f32_16x16x32_bf16 v[72:75], v[226:229], v[202:205], v[72:75]
	v_mfma_f32_16x16x32_bf16 v[68:71], v[218:221], v[210:213], v[68:71]
	v_mfma_f32_16x16x32_bf16 v[64:67], v[226:229], v[210:213], v[64:67]
	v_mfma_f32_16x16x32_bf16 v[92:95], v[222:225], v[190:193], v[92:95]
	v_mfma_f32_16x16x32_bf16 v[88:91], v[230:233], v[190:193], v[88:91]
	v_mfma_f32_16x16x32_bf16 v[84:87], v[222:225], v[198:201], v[84:87]
	v_mfma_f32_16x16x32_bf16 v[80:83], v[230:233], v[198:201], v[80:83]
	v_mfma_f32_16x16x32_bf16 v[76:79], v[222:225], v[206:209], v[76:79]
	v_mfma_f32_16x16x32_bf16 v[72:75], v[230:233], v[206:209], v[72:75]
	v_mfma_f32_16x16x32_bf16 v[68:71], v[222:225], v[214:217], v[68:71]
	v_mfma_f32_16x16x32_bf16 v[64:67], v[230:233], v[214:217], v[64:67]
	v_readfirstlane_b32 s53, v153
	v_lshl_add_u64 v[242:243], v[234:235], 0, s[14:15]
	s_mov_b32 m0, s53
	v_readfirstlane_b32 s53, v155
	s_barrier
	ds_read_b128 v[186:189], v151 offset:16384
	ds_read_b128 v[190:193], v151 offset:17408
	ds_read_b128 v[194:197], v150 offset:16384
	ds_read_b128 v[198:201], v150 offset:17408
	ds_read_b128 v[202:205], v149 offset:16384
	ds_read_b128 v[206:209], v149 offset:17408
	ds_read_b128 v[210:213], v148 offset:16384
	ds_read_b128 v[214:217], v148 offset:17408
	global_load_lds_dwordx4 v[242:243], off
	v_lshl_add_u64 v[242:243], v[236:237], 0, s[14:15]
	s_mov_b32 m0, s53
	s_nop 0
	global_load_lds_dwordx4 v[242:243], off
	s_barrier
	s_waitcnt lgkmcnt(0)
	s_waitcnt lgkmcnt(0)
	v_mfma_f32_16x16x32_bf16 v[60:63], v[170:173], v[186:189], v[60:63]
	v_mfma_f32_16x16x32_bf16 v[56:59], v[178:181], v[186:189], v[56:59]
	v_mfma_f32_16x16x32_bf16 v[52:55], v[170:173], v[194:197], v[52:55]
	v_mfma_f32_16x16x32_bf16 v[48:51], v[178:181], v[194:197], v[48:51]
	v_mfma_f32_16x16x32_bf16 v[44:47], v[170:173], v[202:205], v[44:47]
	v_mfma_f32_16x16x32_bf16 v[40:43], v[178:181], v[202:205], v[40:43]
	v_mfma_f32_16x16x32_bf16 v[36:39], v[170:173], v[210:213], v[36:39]
	v_mfma_f32_16x16x32_bf16 v[32:35], v[178:181], v[210:213], v[32:35]
	v_mfma_f32_16x16x32_bf16 v[60:63], v[174:177], v[190:193], v[60:63]
	v_mfma_f32_16x16x32_bf16 v[56:59], v[182:185], v[190:193], v[56:59]
	v_mfma_f32_16x16x32_bf16 v[52:55], v[174:177], v[198:201], v[52:55]
	v_mfma_f32_16x16x32_bf16 v[48:51], v[182:185], v[198:201], v[48:51]
	v_mfma_f32_16x16x32_bf16 v[44:47], v[174:177], v[206:209], v[44:47]
	v_mfma_f32_16x16x32_bf16 v[40:43], v[182:185], v[206:209], v[40:43]
	v_mfma_f32_16x16x32_bf16 v[36:39], v[174:177], v[214:217], v[36:39]
	v_mfma_f32_16x16x32_bf16 v[32:35], v[182:185], v[214:217], v[32:35]
	s_barrier
	v_readfirstlane_b32 s53, v156
	v_add_u32_e32 v172, 0x2000, v156
	v_lshl_add_u64 v[170:171], v[238:239], 0, s[16:17]
	s_mov_b32 m0, s53
	v_readfirstlane_b32 s53, v172
	global_load_lds_dwordx4 v[170:171], off
	v_lshl_add_u64 v[170:171], v[240:241], 0, s[16:17]
	s_mov_b32 m0, s53
	s_nop 0
	global_load_lds_dwordx4 v[170:171], off
	s_waitcnt vmcnt(6)
	s_barrier
	v_mfma_f32_16x16x32_bf16 v[28:31], v[218:221], v[186:189], v[28:31]
	v_mfma_f32_16x16x32_bf16 v[24:27], v[226:229], v[186:189], v[24:27]
	v_mfma_f32_16x16x32_bf16 v[20:23], v[218:221], v[194:197], v[20:23]
	v_mfma_f32_16x16x32_bf16 v[16:19], v[226:229], v[194:197], v[16:19]
	v_mfma_f32_16x16x32_bf16 v[12:15], v[218:221], v[202:205], v[12:15]
	v_mfma_f32_16x16x32_bf16 v[8:11], v[226:229], v[202:205], v[8:11]
	v_mfma_f32_16x16x32_bf16 v[4:7], v[218:221], v[210:213], v[4:7]
	v_mfma_f32_16x16x32_bf16 v[0:3], v[226:229], v[210:213], v[0:3]
	v_mfma_f32_16x16x32_bf16 v[28:31], v[222:225], v[190:193], v[28:31]
	v_mfma_f32_16x16x32_bf16 v[24:27], v[230:233], v[190:193], v[24:27]
	v_mfma_f32_16x16x32_bf16 v[20:23], v[222:225], v[198:201], v[20:23]
	v_mfma_f32_16x16x32_bf16 v[16:19], v[230:233], v[198:201], v[16:19]
	v_mfma_f32_16x16x32_bf16 v[12:15], v[222:225], v[206:209], v[12:15]
	v_mfma_f32_16x16x32_bf16 v[8:11], v[230:233], v[206:209], v[8:11]
	v_mfma_f32_16x16x32_bf16 v[4:7], v[222:225], v[214:217], v[4:7]
	v_mfma_f32_16x16x32_bf16 v[0:3], v[230:233], v[214:217], v[0:3]
	s_barrier
	ds_read_b128 v[170:173], v157
	ds_read_b128 v[174:177], v157 offset:1024
	ds_read_b128 v[178:181], v157 offset:2048
	ds_read_b128 v[182:185], v157 offset:3072
	v_readfirstlane_b32 s53, v158
	v_lshl_add_u64 v[218:219], v[234:235], 0, s[18:19]
	s_mov_b32 m0, s53
	v_readfirstlane_b32 s53, v159
	ds_read_b128 v[186:189], v151 offset:32768
	ds_read_b128 v[190:193], v151 offset:33792
	ds_read_b128 v[194:197], v150 offset:32768
	ds_read_b128 v[198:201], v150 offset:33792
	ds_read_b128 v[202:205], v149 offset:32768
	ds_read_b128 v[206:209], v149 offset:33792
	ds_read_b128 v[210:213], v148 offset:32768
	ds_read_b128 v[214:217], v148 offset:33792
	global_load_lds_dwordx4 v[218:219], off
	v_lshl_add_u64 v[218:219], v[236:237], 0, s[18:19]
	s_mov_b32 m0, s53
	s_nop 0
	global_load_lds_dwordx4 v[218:219], off
	s_waitcnt lgkmcnt(8)
	s_barrier
	s_waitcnt lgkmcnt(0)
	s_waitcnt lgkmcnt(0)
	v_mfma_f32_16x16x32_bf16 v[124:127], v[170:173], v[186:189], v[124:127]
	v_mfma_f32_16x16x32_bf16 v[120:123], v[178:181], v[186:189], v[120:123]
	v_mfma_f32_16x16x32_bf16 v[116:119], v[170:173], v[194:197], v[116:119]
	v_mfma_f32_16x16x32_bf16 v[112:115], v[178:181], v[194:197], v[112:115]
	v_mfma_f32_16x16x32_bf16 v[108:111], v[170:173], v[202:205], v[108:111]
	v_mfma_f32_16x16x32_bf16 v[104:107], v[178:181], v[202:205], v[104:107]
	v_mfma_f32_16x16x32_bf16 v[100:103], v[170:173], v[210:213], v[100:103]
	v_mfma_f32_16x16x32_bf16 v[96:99], v[178:181], v[210:213], v[96:99]
	v_mfma_f32_16x16x32_bf16 v[124:127], v[174:177], v[190:193], v[124:127]
	v_mfma_f32_16x16x32_bf16 v[120:123], v[182:185], v[190:193], v[120:123]
	v_mfma_f32_16x16x32_bf16 v[116:119], v[174:177], v[198:201], v[116:119]
	v_mfma_f32_16x16x32_bf16 v[112:115], v[182:185], v[198:201], v[112:115]
	v_mfma_f32_16x16x32_bf16 v[108:111], v[174:177], v[206:209], v[108:111]
	v_mfma_f32_16x16x32_bf16 v[104:107], v[182:185], v[206:209], v[104:107]
	v_mfma_f32_16x16x32_bf16 v[100:103], v[174:177], v[214:217], v[100:103]
	v_mfma_f32_16x16x32_bf16 v[96:99], v[182:185], v[214:217], v[96:99]
	s_barrier
	v_readfirstlane_b32 s53, v160
	v_lshl_add_u64 v[242:243], v[238:239], 0, s[20:21]
	s_mov_b32 m0, s53
	v_readfirstlane_b32 s53, v161
	ds_read_b128 v[218:221], v152
	ds_read_b128 v[222:225], v152 offset:1024
	ds_read_b128 v[226:229], v152 offset:2048
	ds_read_b128 v[230:233], v152 offset:3072
	global_load_lds_dwordx4 v[242:243], off
	v_lshl_add_u64 v[242:243], v[240:241], 0, s[20:21]
	s_mov_b32 m0, s53
	s_nop 0
	global_load_lds_dwordx4 v[242:243], off
	s_barrier
	s_waitcnt lgkmcnt(0)
	s_waitcnt lgkmcnt(0)
	v_mfma_f32_16x16x32_bf16 v[92:95], v[218:221], v[186:189], v[92:95]
	v_mfma_f32_16x16x32_bf16 v[88:91], v[226:229], v[186:189], v[88:91]
	v_mfma_f32_16x16x32_bf16 v[84:87], v[218:221], v[194:197], v[84:87]
	v_mfma_f32_16x16x32_bf16 v[80:83], v[226:229], v[194:197], v[80:83]
	v_mfma_f32_16x16x32_bf16 v[76:79], v[218:221], v[202:205], v[76:79]
	v_mfma_f32_16x16x32_bf16 v[72:75], v[226:229], v[202:205], v[72:75]
	v_mfma_f32_16x16x32_bf16 v[68:71], v[218:221], v[210:213], v[68:71]
	v_mfma_f32_16x16x32_bf16 v[64:67], v[226:229], v[210:213], v[64:67]
	v_mfma_f32_16x16x32_bf16 v[92:95], v[222:225], v[190:193], v[92:95]
	v_mfma_f32_16x16x32_bf16 v[88:91], v[230:233], v[190:193], v[88:91]
	v_mfma_f32_16x16x32_bf16 v[84:87], v[222:225], v[198:201], v[84:87]
	v_mfma_f32_16x16x32_bf16 v[80:83], v[230:233], v[198:201], v[80:83]
	v_mfma_f32_16x16x32_bf16 v[76:79], v[222:225], v[206:209], v[76:79]
	v_mfma_f32_16x16x32_bf16 v[72:75], v[230:233], v[206:209], v[72:75]
	v_mfma_f32_16x16x32_bf16 v[68:71], v[222:225], v[214:217], v[68:71]
	v_mfma_f32_16x16x32_bf16 v[64:67], v[230:233], v[214:217], v[64:67]
	v_readfirstlane_b32 s53, v162
	v_lshl_add_u64 v[234:235], v[234:235], 0, s[22:23]
	s_mov_b32 m0, s53
	v_readfirstlane_b32 s53, v163
	s_barrier
	ds_read_b128 v[186:189], v151 offset:49152
	ds_read_b128 v[190:193], v151 offset:50176
	ds_read_b128 v[194:197], v150 offset:49152
	ds_read_b128 v[198:201], v150 offset:50176
	ds_read_b128 v[202:205], v149 offset:49152
	ds_read_b128 v[206:209], v149 offset:50176
	ds_read_b128 v[210:213], v148 offset:49152
	ds_read_b128 v[214:217], v148 offset:50176
	global_load_lds_dwordx4 v[234:235], off
	v_lshl_add_u64 v[234:235], v[236:237], 0, s[22:23]
	s_mov_b32 m0, s53
	s_nop 0
	global_load_lds_dwordx4 v[234:235], off
	s_barrier
	s_waitcnt lgkmcnt(0)
	s_waitcnt lgkmcnt(0)
	v_mfma_f32_16x16x32_bf16 v[60:63], v[170:173], v[186:189], v[60:63]
	v_mfma_f32_16x16x32_bf16 v[56:59], v[178:181], v[186:189], v[56:59]
	v_mfma_f32_16x16x32_bf16 v[52:55], v[170:173], v[194:197], v[52:55]
	v_mfma_f32_16x16x32_bf16 v[48:51], v[178:181], v[194:197], v[48:51]
	v_mfma_f32_16x16x32_bf16 v[44:47], v[170:173], v[202:205], v[44:47]
	v_mfma_f32_16x16x32_bf16 v[40:43], v[178:181], v[202:205], v[40:43]
	v_mfma_f32_16x16x32_bf16 v[36:39], v[170:173], v[210:213], v[36:39]
	v_mfma_f32_16x16x32_bf16 v[32:35], v[178:181], v[210:213], v[32:35]
	v_mfma_f32_16x16x32_bf16 v[60:63], v[174:177], v[190:193], v[60:63]
	v_mfma_f32_16x16x32_bf16 v[56:59], v[182:185], v[190:193], v[56:59]
	v_mfma_f32_16x16x32_bf16 v[52:55], v[174:177], v[198:201], v[52:55]
	v_mfma_f32_16x16x32_bf16 v[48:51], v[182:185], v[198:201], v[48:51]
	v_mfma_f32_16x16x32_bf16 v[44:47], v[174:177], v[206:209], v[44:47]
	v_mfma_f32_16x16x32_bf16 v[40:43], v[182:185], v[206:209], v[40:43]
	v_mfma_f32_16x16x32_bf16 v[36:39], v[174:177], v[214:217], v[36:39]
	v_mfma_f32_16x16x32_bf16 v[32:35], v[182:185], v[214:217], v[32:35]
	s_barrier
	v_readfirstlane_b32 s53, v164
	v_lshl_add_u64 v[170:171], v[238:239], 0, s[24:25]
	s_mov_b32 m0, s53
	v_readfirstlane_b32 s53, v166
	global_load_lds_dwordx4 v[170:171], off
	v_lshl_add_u64 v[170:171], v[240:241], 0, s[24:25]
	s_mov_b32 m0, s53
	s_nop 0
	global_load_lds_dwordx4 v[170:171], off
	s_waitcnt vmcnt(6)
	s_barrier
	v_mfma_f32_16x16x32_bf16 v[28:31], v[218:221], v[186:189], v[28:31]
	v_mfma_f32_16x16x32_bf16 v[24:27], v[226:229], v[186:189], v[24:27]
	v_mfma_f32_16x16x32_bf16 v[20:23], v[218:221], v[194:197], v[20:23]
	v_mfma_f32_16x16x32_bf16 v[16:19], v[226:229], v[194:197], v[16:19]
	v_mfma_f32_16x16x32_bf16 v[12:15], v[218:221], v[202:205], v[12:15]
	v_mfma_f32_16x16x32_bf16 v[8:11], v[226:229], v[202:205], v[8:11]
	v_mfma_f32_16x16x32_bf16 v[4:7], v[218:221], v[210:213], v[4:7]
	v_mfma_f32_16x16x32_bf16 v[0:3], v[226:229], v[210:213], v[0:3]
	v_mfma_f32_16x16x32_bf16 v[28:31], v[222:225], v[190:193], v[28:31]
	v_mfma_f32_16x16x32_bf16 v[24:27], v[230:233], v[190:193], v[24:27]
	v_mfma_f32_16x16x32_bf16 v[20:23], v[222:225], v[198:201], v[20:23]
	v_mfma_f32_16x16x32_bf16 v[16:19], v[230:233], v[198:201], v[16:19]
	v_mfma_f32_16x16x32_bf16 v[12:15], v[222:225], v[206:209], v[12:15]
	v_mfma_f32_16x16x32_bf16 v[8:11], v[230:233], v[206:209], v[8:11]
	v_mfma_f32_16x16x32_bf16 v[4:7], v[222:225], v[214:217], v[4:7]
	v_mfma_f32_16x16x32_bf16 v[0:3], v[230:233], v[214:217], v[0:3]
	s_add_i32 s1, s1, 2
	v_lshl_add_u64 v[134:135], v[134:135], 0, s[28:29]
	v_lshl_add_u64 v[136:137], v[136:137], 0, s[28:29]
	v_lshl_add_u64 v[138:139], v[138:139], 0, s[28:29]
	s_cmp_lt_u32 s1, 12
	v_lshl_add_u64 v[140:141], v[140:141], 0, s[28:29]
	s_barrier
	s_cbranch_scc1 .LBB0_186
	v_readfirstlane_b32 s1, v168
	v_lshl_add_u64 v[130:131], v[130:131], 0, s[30:31]
	s_mov_b32 m0, s1
	v_readfirstlane_b32 s1, v169
	ds_read_b128 v[134:137], v167
	ds_read_b128 v[138:141], v167 offset:1024
	ds_read_b128 v[158:161], v167 offset:2048
	ds_read_b128 v[170:173], v167 offset:3072
	ds_read_b128 v[174:177], v151
	ds_read_b128 v[178:181], v151 offset:1024
	ds_read_b128 v[182:185], v150
	ds_read_b128 v[186:189], v150 offset:1024
	ds_read_b128 v[190:193], v149
	ds_read_b128 v[194:197], v149 offset:1024
	ds_read_b128 v[198:201], v148
	ds_read_b128 v[202:205], v148 offset:1024
	global_load_lds_dwordx4 v[130:131], off
	v_lshl_add_u64 v[130:131], v[132:133], 0, s[30:31]
	s_mov_b32 m0, s1
	s_nop 0
	global_load_lds_dwordx4 v[130:131], off
	s_barrier
	s_waitcnt lgkmcnt(0)
	s_waitcnt lgkmcnt(0)
	v_mfma_f32_16x16x32_bf16 v[124:127], v[134:137], v[174:177], v[124:127]
	v_mfma_f32_16x16x32_bf16 v[120:123], v[158:161], v[174:177], v[120:123]
	v_mfma_f32_16x16x32_bf16 v[116:119], v[134:137], v[182:185], v[116:119]
	v_mfma_f32_16x16x32_bf16 v[112:115], v[158:161], v[182:185], v[112:115]
	v_mfma_f32_16x16x32_bf16 v[108:111], v[134:137], v[190:193], v[108:111]
	v_mfma_f32_16x16x32_bf16 v[104:107], v[158:161], v[190:193], v[104:107]
	v_mfma_f32_16x16x32_bf16 v[100:103], v[134:137], v[198:201], v[100:103]
	v_mfma_f32_16x16x32_bf16 v[96:99], v[158:161], v[198:201], v[96:99]
	v_mfma_f32_16x16x32_bf16 v[124:127], v[138:141], v[178:181], v[124:127]
	v_mfma_f32_16x16x32_bf16 v[120:123], v[170:173], v[178:181], v[120:123]
	v_mfma_f32_16x16x32_bf16 v[116:119], v[138:141], v[186:189], v[116:119]
	v_mfma_f32_16x16x32_bf16 v[112:115], v[170:173], v[186:189], v[112:115]
	v_mfma_f32_16x16x32_bf16 v[108:111], v[138:141], v[194:197], v[108:111]
	v_mfma_f32_16x16x32_bf16 v[104:107], v[170:173], v[194:197], v[104:107]
	v_mfma_f32_16x16x32_bf16 v[100:103], v[138:141], v[202:205], v[100:103]
	v_mfma_f32_16x16x32_bf16 v[96:99], v[170:173], v[202:205], v[96:99]
	s_barrier
	ds_read_b128 v[130:133], v165
	ds_read_b128 v[166:169], v165 offset:1024
	ds_read_b128 v[206:209], v165 offset:2048
	ds_read_b128 v[162:165], v165 offset:3072
	s_barrier
	s_waitcnt lgkmcnt(0)
	s_waitcnt lgkmcnt(0)
	v_mfma_f32_16x16x32_bf16 v[92:95], v[130:133], v[174:177], v[92:95]
	v_mfma_f32_16x16x32_bf16 v[88:91], v[206:209], v[174:177], v[88:91]
	v_mfma_f32_16x16x32_bf16 v[84:87], v[130:133], v[182:185], v[84:87]
	v_mfma_f32_16x16x32_bf16 v[80:83], v[206:209], v[182:185], v[80:83]
	v_mfma_f32_16x16x32_bf16 v[76:79], v[130:133], v[190:193], v[76:79]
	v_mfma_f32_16x16x32_bf16 v[72:75], v[206:209], v[190:193], v[72:75]
	v_mfma_f32_16x16x32_bf16 v[68:71], v[130:133], v[198:201], v[68:71]
	v_mfma_f32_16x16x32_bf16 v[64:67], v[206:209], v[198:201], v[64:67]
	v_mfma_f32_16x16x32_bf16 v[92:95], v[166:169], v[178:181], v[92:95]
	v_mfma_f32_16x16x32_bf16 v[88:91], v[162:165], v[178:181], v[88:91]
	v_mfma_f32_16x16x32_bf16 v[84:87], v[166:169], v[186:189], v[84:87]
	v_mfma_f32_16x16x32_bf16 v[80:83], v[162:165], v[186:189], v[80:83]
	v_mfma_f32_16x16x32_bf16 v[76:79], v[166:169], v[194:197], v[76:79]
	v_mfma_f32_16x16x32_bf16 v[72:75], v[162:165], v[194:197], v[72:75]
	v_mfma_f32_16x16x32_bf16 v[68:71], v[166:169], v[202:205], v[68:71]
	v_mfma_f32_16x16x32_bf16 v[64:67], v[162:165], v[202:205], v[64:67]
	s_barrier
	ds_read_b128 v[174:177], v151 offset:16384
	ds_read_b128 v[178:181], v151 offset:17408
	ds_read_b128 v[182:185], v150 offset:16384
	ds_read_b128 v[186:189], v150 offset:17408
	ds_read_b128 v[190:193], v149 offset:16384
	ds_read_b128 v[194:197], v149 offset:17408
	ds_read_b128 v[198:201], v148 offset:16384
	ds_read_b128 v[202:205], v148 offset:17408
	s_waitcnt vmcnt(4)
	s_barrier
	s_waitcnt lgkmcnt(0)
	s_waitcnt lgkmcnt(0)
	v_mfma_f32_16x16x32_bf16 v[60:63], v[134:137], v[174:177], v[60:63]
	v_mfma_f32_16x16x32_bf16 v[56:59], v[158:161], v[174:177], v[56:59]
	v_mfma_f32_16x16x32_bf16 v[52:55], v[134:137], v[182:185], v[52:55]
	v_mfma_f32_16x16x32_bf16 v[48:51], v[158:161], v[182:185], v[48:51]
	v_mfma_f32_16x16x32_bf16 v[44:47], v[134:137], v[190:193], v[44:47]
	v_mfma_f32_16x16x32_bf16 v[40:43], v[158:161], v[190:193], v[40:43]
	v_mfma_f32_16x16x32_bf16 v[36:39], v[134:137], v[198:201], v[36:39]
	v_mfma_f32_16x16x32_bf16 v[32:35], v[158:161], v[198:201], v[32:35]
	v_mfma_f32_16x16x32_bf16 v[60:63], v[138:141], v[178:181], v[60:63]
	v_mfma_f32_16x16x32_bf16 v[56:59], v[170:173], v[178:181], v[56:59]
	v_mfma_f32_16x16x32_bf16 v[52:55], v[138:141], v[186:189], v[52:55]
	v_mfma_f32_16x16x32_bf16 v[48:51], v[170:173], v[186:189], v[48:51]
	v_mfma_f32_16x16x32_bf16 v[44:47], v[138:141], v[194:197], v[44:47]
	v_mfma_f32_16x16x32_bf16 v[40:43], v[170:173], v[194:197], v[40:43]
	v_mfma_f32_16x16x32_bf16 v[36:39], v[138:141], v[202:205], v[36:39]
	v_mfma_f32_16x16x32_bf16 v[32:35], v[170:173], v[202:205], v[32:35]
	v_mfma_f32_16x16x32_bf16 v[28:31], v[130:133], v[174:177], v[28:31]
	v_mfma_f32_16x16x32_bf16 v[24:27], v[206:209], v[174:177], v[24:27]
	v_mfma_f32_16x16x32_bf16 v[20:23], v[130:133], v[182:185], v[20:23]
	v_mfma_f32_16x16x32_bf16 v[16:19], v[206:209], v[182:185], v[16:19]
	v_mfma_f32_16x16x32_bf16 v[12:15], v[130:133], v[190:193], v[12:15]
	v_mfma_f32_16x16x32_bf16 v[8:11], v[206:209], v[190:193], v[8:11]
	v_mfma_f32_16x16x32_bf16 v[4:7], v[130:133], v[198:201], v[4:7]
	v_mfma_f32_16x16x32_bf16 v[0:3], v[206:209], v[198:201], v[0:3]
	v_mfma_f32_16x16x32_bf16 v[28:31], v[166:169], v[178:181], v[28:31]
	v_mfma_f32_16x16x32_bf16 v[24:27], v[162:165], v[178:181], v[24:27]
	v_mfma_f32_16x16x32_bf16 v[20:23], v[166:169], v[186:189], v[20:23]
	v_mfma_f32_16x16x32_bf16 v[16:19], v[162:165], v[186:189], v[16:19]
	v_mfma_f32_16x16x32_bf16 v[12:15], v[166:169], v[194:197], v[12:15]
	v_mfma_f32_16x16x32_bf16 v[8:11], v[162:165], v[194:197], v[8:11]
	v_mfma_f32_16x16x32_bf16 v[4:7], v[166:169], v[202:205], v[4:7]
	v_mfma_f32_16x16x32_bf16 v[0:3], v[162:165], v[202:205], v[0:3]
	s_barrier
	ds_read_b128 v[130:133], v157
	ds_read_b128 v[134:137], v157 offset:1024
	ds_read_b128 v[138:141], v157 offset:2048
	ds_read_b128 v[156:159], v157 offset:3072
	ds_read_b128 v[160:163], v151 offset:32768
	ds_read_b128 v[164:167], v151 offset:33792
	ds_read_b128 v[168:171], v150 offset:32768
	ds_read_b128 v[172:175], v150 offset:33792
	ds_read_b128 v[176:179], v149 offset:32768
	ds_read_b128 v[180:183], v149 offset:33792
	ds_read_b128 v[184:187], v148 offset:32768
	ds_read_b128 v[188:191], v148 offset:33792
	s_waitcnt vmcnt(2)
	s_barrier
	s_waitcnt lgkmcnt(0)
	s_waitcnt lgkmcnt(0)
	v_mfma_f32_16x16x32_bf16 v[124:127], v[130:133], v[160:163], v[124:127]
	v_mfma_f32_16x16x32_bf16 v[120:123], v[138:141], v[160:163], v[120:123]
	v_mfma_f32_16x16x32_bf16 v[116:119], v[130:133], v[168:171], v[116:119]
	v_mfma_f32_16x16x32_bf16 v[112:115], v[138:141], v[168:171], v[112:115]
	v_mfma_f32_16x16x32_bf16 v[108:111], v[130:133], v[176:179], v[108:111]
	v_mfma_f32_16x16x32_bf16 v[104:107], v[138:141], v[176:179], v[104:107]
	v_mfma_f32_16x16x32_bf16 v[100:103], v[130:133], v[184:187], v[100:103]
	v_mfma_f32_16x16x32_bf16 v[96:99], v[138:141], v[184:187], v[96:99]
	v_mfma_f32_16x16x32_bf16 v[124:127], v[134:137], v[164:167], v[124:127]
	v_mfma_f32_16x16x32_bf16 v[120:123], v[156:159], v[164:167], v[120:123]
	v_mfma_f32_16x16x32_bf16 v[116:119], v[134:137], v[172:175], v[116:119]
	v_mfma_f32_16x16x32_bf16 v[112:115], v[156:159], v[172:175], v[112:115]
	v_mfma_f32_16x16x32_bf16 v[108:111], v[134:137], v[180:183], v[108:111]
	v_mfma_f32_16x16x32_bf16 v[104:107], v[156:159], v[180:183], v[104:107]
	v_mfma_f32_16x16x32_bf16 v[100:103], v[134:137], v[188:191], v[100:103]
	v_mfma_f32_16x16x32_bf16 v[96:99], v[156:159], v[188:191], v[96:99]
	s_barrier
	ds_read_b128 v[192:195], v152
	ds_read_b128 v[196:199], v152 offset:1024
	ds_read_b128 v[200:203], v152 offset:2048
	ds_read_b128 v[204:207], v152 offset:3072
	s_waitcnt vmcnt(0)
	s_barrier
	s_waitcnt lgkmcnt(0)
	s_waitcnt lgkmcnt(0)
	v_mfma_f32_16x16x32_bf16 v[92:95], v[192:195], v[160:163], v[92:95]
	v_mfma_f32_16x16x32_bf16 v[88:91], v[200:203], v[160:163], v[88:91]
	v_mfma_f32_16x16x32_bf16 v[84:87], v[192:195], v[168:171], v[84:87]
	v_mfma_f32_16x16x32_bf16 v[80:83], v[200:203], v[168:171], v[80:83]
	v_mfma_f32_16x16x32_bf16 v[76:79], v[192:195], v[176:179], v[76:79]
	v_mfma_f32_16x16x32_bf16 v[72:75], v[200:203], v[176:179], v[72:75]
	v_mfma_f32_16x16x32_bf16 v[68:71], v[192:195], v[184:187], v[68:71]
	v_mfma_f32_16x16x32_bf16 v[64:67], v[200:203], v[184:187], v[64:67]
	v_mfma_f32_16x16x32_bf16 v[92:95], v[196:199], v[164:167], v[92:95]
	v_mfma_f32_16x16x32_bf16 v[88:91], v[204:207], v[164:167], v[88:91]
	v_mfma_f32_16x16x32_bf16 v[84:87], v[196:199], v[172:175], v[84:87]
	v_mfma_f32_16x16x32_bf16 v[80:83], v[204:207], v[172:175], v[80:83]
	v_mfma_f32_16x16x32_bf16 v[76:79], v[196:199], v[180:183], v[76:79]
	v_mfma_f32_16x16x32_bf16 v[72:75], v[204:207], v[180:183], v[72:75]
	v_mfma_f32_16x16x32_bf16 v[68:71], v[196:199], v[188:191], v[68:71]
	v_mfma_f32_16x16x32_bf16 v[64:67], v[204:207], v[188:191], v[64:67]
	s_barrier
	ds_read_b128 v[160:163], v151 offset:49152
	ds_read_b128 v[164:167], v151 offset:50176
	ds_read_b128 v[168:171], v150 offset:49152
	ds_read_b128 v[150:153], v150 offset:50176
	ds_read_b128 v[172:175], v149 offset:49152
	ds_read_b128 v[176:179], v149 offset:50176
	ds_read_b128 v[180:183], v148 offset:49152
	ds_read_b128 v[184:187], v148 offset:50176
	s_barrier
	s_waitcnt lgkmcnt(0)
	s_waitcnt lgkmcnt(0)
	v_mfma_f32_16x16x32_bf16 v[60:63], v[130:133], v[160:163], v[60:63]
	v_mfma_f32_16x16x32_bf16 v[56:59], v[138:141], v[160:163], v[56:59]
	v_mfma_f32_16x16x32_bf16 v[52:55], v[130:133], v[168:171], v[52:55]
	v_mfma_f32_16x16x32_bf16 v[48:51], v[138:141], v[168:171], v[48:51]
	v_mfma_f32_16x16x32_bf16 v[44:47], v[130:133], v[172:175], v[44:47]
	v_mfma_f32_16x16x32_bf16 v[40:43], v[138:141], v[172:175], v[40:43]
	v_mfma_f32_16x16x32_bf16 v[36:39], v[130:133], v[180:183], v[36:39]
	v_mfma_f32_16x16x32_bf16 v[32:35], v[138:141], v[180:183], v[32:35]
	v_mfma_f32_16x16x32_bf16 v[60:63], v[134:137], v[164:167], v[60:63]
	v_mfma_f32_16x16x32_bf16 v[56:59], v[156:159], v[164:167], v[56:59]
	v_mfma_f32_16x16x32_bf16 v[52:55], v[134:137], v[150:153], v[52:55]
	v_mfma_f32_16x16x32_bf16 v[48:51], v[156:159], v[150:153], v[48:51]
	v_mfma_f32_16x16x32_bf16 v[44:47], v[134:137], v[176:179], v[44:47]
	v_mfma_f32_16x16x32_bf16 v[40:43], v[156:159], v[176:179], v[40:43]
	v_mfma_f32_16x16x32_bf16 v[36:39], v[134:137], v[184:187], v[36:39]
	v_mfma_f32_16x16x32_bf16 v[32:35], v[156:159], v[184:187], v[32:35]
	v_mfma_f32_16x16x32_bf16 v[28:31], v[192:195], v[160:163], v[28:31]
	v_mfma_f32_16x16x32_bf16 v[24:27], v[200:203], v[160:163], v[24:27]
	v_mfma_f32_16x16x32_bf16 v[20:23], v[192:195], v[168:171], v[20:23]
	v_mfma_f32_16x16x32_bf16 v[16:19], v[200:203], v[168:171], v[16:19]
	v_mfma_f32_16x16x32_bf16 v[12:15], v[192:195], v[172:175], v[12:15]
	v_mfma_f32_16x16x32_bf16 v[8:11], v[200:203], v[172:175], v[8:11]
	v_mfma_f32_16x16x32_bf16 v[4:7], v[192:195], v[180:183], v[4:7]
	v_mfma_f32_16x16x32_bf16 v[0:3], v[200:203], v[180:183], v[0:3]
	v_mfma_f32_16x16x32_bf16 v[28:31], v[196:199], v[164:167], v[28:31]
	v_mfma_f32_16x16x32_bf16 v[24:27], v[204:207], v[164:167], v[24:27]
	v_mfma_f32_16x16x32_bf16 v[20:23], v[196:199], v[150:153], v[20:23]
	v_mfma_f32_16x16x32_bf16 v[16:19], v[204:207], v[150:153], v[16:19]
	v_mfma_f32_16x16x32_bf16 v[12:15], v[196:199], v[176:179], v[12:15]
	v_mfma_f32_16x16x32_bf16 v[8:11], v[204:207], v[176:179], v[8:11]
	v_mfma_f32_16x16x32_bf16 v[4:7], v[196:199], v[184:187], v[4:7]
	v_mfma_f32_16x16x32_bf16 v[0:3], v[204:207], v[184:187], v[0:3]
	s_movk_i32 s1, 0x100
	v_cmp_gt_u32_e32 vcc, s1, v128
	s_barrier
	s_and_saveexec_b64 s[56:57], vcc
	s_cbranch_execz .LBB0_189
	s_barrier

.LBB0_574:
	ds_read_b128 v[176:179], v173
	ds_read_b128 v[180:183], v173 offset:1024
	ds_read_b128 v[184:187], v173 offset:2048
	ds_read_b128 v[188:191], v173 offset:3072
	v_add_u32_e32 v174, 0xc000, v160
	v_lshl_add_u64 v[240:241], s[4:5], 0, v[142:143]
	v_readfirstlane_b32 s43, v174
	v_add_u32_e32 v175, 0xe000, v160
	v_lshl_add_u64 v[224:225], v[240:241], 0, s[12:13]
	s_mov_b32 m0, s43
	v_lshl_add_u64 v[242:243], s[4:5], 0, v[140:141]
	v_readfirstlane_b32 s43, v175
	ds_read_b128 v[192:195], v153
	ds_read_b128 v[196:199], v153 offset:1024
	ds_read_b128 v[200:203], v152
	ds_read_b128 v[204:207], v152 offset:1024
	ds_read_b128 v[208:211], v151
	ds_read_b128 v[212:215], v151 offset:1024
	ds_read_b128 v[216:219], v150
	ds_read_b128 v[220:223], v150 offset:1024
	global_load_lds_dwordx4 v[224:225], off
	v_lshl_add_u64 v[224:225], v[242:243], 0, s[12:13]
	s_mov_b32 m0, s43
	s_nop 0
	global_load_lds_dwordx4 v[224:225], off
	s_waitcnt lgkmcnt(8)
	s_barrier
	s_waitcnt lgkmcnt(0)
	s_waitcnt lgkmcnt(0)
	v_mfma_f32_16x16x32_bf16 v[124:127], v[176:179], v[192:195], v[124:127]
	v_mfma_f32_16x16x32_bf16 v[120:123], v[184:187], v[192:195], v[120:123]
	v_mfma_f32_16x16x32_bf16 v[116:119], v[176:179], v[200:203], v[116:119]
	v_mfma_f32_16x16x32_bf16 v[112:115], v[184:187], v[200:203], v[112:115]
	v_mfma_f32_16x16x32_bf16 v[108:111], v[176:179], v[208:211], v[108:111]
	v_mfma_f32_16x16x32_bf16 v[104:107], v[184:187], v[208:211], v[104:107]
	v_mfma_f32_16x16x32_bf16 v[100:103], v[176:179], v[216:219], v[100:103]
	v_mfma_f32_16x16x32_bf16 v[96:99], v[184:187], v[216:219], v[96:99]
	v_mfma_f32_16x16x32_bf16 v[124:127], v[180:183], v[196:199], v[124:127]
	v_mfma_f32_16x16x32_bf16 v[120:123], v[188:191], v[196:199], v[120:123]
	v_mfma_f32_16x16x32_bf16 v[116:119], v[180:183], v[204:207], v[116:119]
	v_mfma_f32_16x16x32_bf16 v[112:115], v[188:191], v[204:207], v[112:115]
	v_mfma_f32_16x16x32_bf16 v[108:111], v[180:183], v[212:215], v[108:111]
	v_mfma_f32_16x16x32_bf16 v[104:107], v[188:191], v[212:215], v[104:107]
	v_mfma_f32_16x16x32_bf16 v[100:103], v[180:183], v[220:223], v[100:103]
	v_mfma_f32_16x16x32_bf16 v[96:99], v[188:191], v[220:223], v[96:99]
	s_barrier
	v_lshl_add_u64 v[244:245], s[4:5], 0, v[138:139]
	v_readfirstlane_b32 s43, v149
	v_lshl_add_u64 v[246:247], v[244:245], 0, s[14:15]
	s_mov_b32 m0, s43
	v_add_u32_e32 v250, 0x2000, v149
	ds_read_b128 v[224:227], v170
	ds_read_b128 v[228:231], v170 offset:1024
	ds_read_b128 v[232:235], v170 offset:2048
	ds_read_b128 v[236:239], v170 offset:3072
	global_load_lds_dwordx4 v[246:247], off
	v_lshl_add_u64 v[246:247], s[4:5], 0, v[136:137]
	v_readfirstlane_b32 s43, v250
	v_lshl_add_u64 v[248:249], v[246:247], 0, s[14:15]
	s_mov_b32 m0, s43
	s_nop 0
	global_load_lds_dwordx4 v[248:249], off
	s_barrier
	s_waitcnt lgkmcnt(0)
	s_waitcnt lgkmcnt(0)
	v_mfma_f32_16x16x32_bf16 v[92:95], v[224:227], v[192:195], v[92:95]
	v_mfma_f32_16x16x32_bf16 v[88:91], v[232:235], v[192:195], v[88:91]
	v_mfma_f32_16x16x32_bf16 v[84:87], v[224:227], v[200:203], v[84:87]
	v_mfma_f32_16x16x32_bf16 v[80:83], v[232:235], v[200:203], v[80:83]
	v_mfma_f32_16x16x32_bf16 v[76:79], v[224:227], v[208:211], v[76:79]
	v_mfma_f32_16x16x32_bf16 v[72:75], v[232:235], v[208:211], v[72:75]
	v_mfma_f32_16x16x32_bf16 v[68:71], v[224:227], v[216:219], v[68:71]
	v_mfma_f32_16x16x32_bf16 v[64:67], v[232:235], v[216:219], v[64:67]
	v_mfma_f32_16x16x32_bf16 v[92:95], v[228:231], v[196:199], v[92:95]
	v_mfma_f32_16x16x32_bf16 v[88:91], v[236:239], v[196:199], v[88:91]
	v_mfma_f32_16x16x32_bf16 v[84:87], v[228:231], v[204:207], v[84:87]
	v_mfma_f32_16x16x32_bf16 v[80:83], v[236:239], v[204:207], v[80:83]
	v_mfma_f32_16x16x32_bf16 v[76:79], v[228:231], v[212:215], v[76:79]
	v_mfma_f32_16x16x32_bf16 v[72:75], v[236:239], v[212:215], v[72:75]
	v_mfma_f32_16x16x32_bf16 v[68:71], v[228:231], v[220:223], v[68:71]
	v_mfma_f32_16x16x32_bf16 v[64:67], v[236:239], v[220:223], v[64:67]
	v_readfirstlane_b32 s43, v160
	v_lshl_add_u64 v[248:249], v[240:241], 0, s[16:17]
	s_mov_b32 m0, s43
	v_readfirstlane_b32 s43, v161
	s_barrier
	ds_read_b128 v[192:195], v153 offset:16384
	ds_read_b128 v[196:199], v153 offset:17408
	ds_read_b128 v[200:203], v152 offset:16384
	ds_read_b128 v[204:207], v152 offset:17408
	ds_read_b128 v[208:211], v151 offset:16384
	ds_read_b128 v[212:215], v151 offset:17408
	ds_read_b128 v[216:219], v150 offset:16384
	ds_read_b128 v[220:223], v150 offset:17408
	global_load_lds_dwordx4 v[248:249], off
	v_lshl_add_u64 v[248:249], v[242:243], 0, s[16:17]
	s_mov_b32 m0, s43
	s_nop 0
	global_load_lds_dwordx4 v[248:249], off
	s_barrier
	s_waitcnt lgkmcnt(0)
	s_waitcnt lgkmcnt(0)
	v_mfma_f32_16x16x32_bf16 v[60:63], v[176:179], v[192:195], v[60:63]
	v_mfma_f32_16x16x32_bf16 v[56:59], v[184:187], v[192:195], v[56:59]
	v_mfma_f32_16x16x32_bf16 v[52:55], v[176:179], v[200:203], v[52:55]
	v_mfma_f32_16x16x32_bf16 v[48:51], v[184:187], v[200:203], v[48:51]
	v_mfma_f32_16x16x32_bf16 v[44:47], v[176:179], v[208:211], v[44:47]
	v_mfma_f32_16x16x32_bf16 v[40:43], v[184:187], v[208:211], v[40:43]
	v_mfma_f32_16x16x32_bf16 v[36:39], v[176:179], v[216:219], v[36:39]
	v_mfma_f32_16x16x32_bf16 v[32:35], v[184:187], v[216:219], v[32:35]
	v_mfma_f32_16x16x32_bf16 v[60:63], v[180:183], v[196:199], v[60:63]
	v_mfma_f32_16x16x32_bf16 v[56:59], v[188:191], v[196:199], v[56:59]
	v_mfma_f32_16x16x32_bf16 v[52:55], v[180:183], v[204:207], v[52:55]
	v_mfma_f32_16x16x32_bf16 v[48:51], v[188:191], v[204:207], v[48:51]
	v_mfma_f32_16x16x32_bf16 v[44:47], v[180:183], v[212:215], v[44:47]
	v_mfma_f32_16x16x32_bf16 v[40:43], v[188:191], v[212:215], v[40:43]
	v_mfma_f32_16x16x32_bf16 v[36:39], v[180:183], v[220:223], v[36:39]
	v_mfma_f32_16x16x32_bf16 v[32:35], v[188:191], v[220:223], v[32:35]
	s_barrier
	v_readfirstlane_b32 s43, v163
	v_add_u32_e32 v178, 0x2000, v163
	v_lshl_add_u64 v[176:177], v[244:245], 0, s[18:19]
	s_mov_b32 m0, s43
	v_readfirstlane_b32 s43, v178
	global_load_lds_dwordx4 v[176:177], off
	v_lshl_add_u64 v[176:177], v[246:247], 0, s[18:19]
	s_mov_b32 m0, s43
	s_nop 0
	global_load_lds_dwordx4 v[176:177], off
	s_waitcnt vmcnt(6)
	s_barrier
	v_mfma_f32_16x16x32_bf16 v[28:31], v[224:227], v[192:195], v[28:31]
	v_mfma_f32_16x16x32_bf16 v[24:27], v[232:235], v[192:195], v[24:27]
	v_mfma_f32_16x16x32_bf16 v[20:23], v[224:227], v[200:203], v[20:23]
	v_mfma_f32_16x16x32_bf16 v[16:19], v[232:235], v[200:203], v[16:19]
	v_mfma_f32_16x16x32_bf16 v[12:15], v[224:227], v[208:211], v[12:15]
	v_mfma_f32_16x16x32_bf16 v[8:11], v[232:235], v[208:211], v[8:11]
	v_mfma_f32_16x16x32_bf16 v[4:7], v[224:227], v[216:219], v[4:7]
	v_mfma_f32_16x16x32_bf16 v[0:3], v[232:235], v[216:219], v[0:3]
	v_mfma_f32_16x16x32_bf16 v[28:31], v[228:231], v[196:199], v[28:31]
	v_mfma_f32_16x16x32_bf16 v[24:27], v[236:239], v[196:199], v[24:27]
	v_mfma_f32_16x16x32_bf16 v[20:23], v[228:231], v[204:207], v[20:23]
	v_mfma_f32_16x16x32_bf16 v[16:19], v[236:239], v[204:207], v[16:19]
	v_mfma_f32_16x16x32_bf16 v[12:15], v[228:231], v[212:215], v[12:15]
	v_mfma_f32_16x16x32_bf16 v[8:11], v[236:239], v[212:215], v[8:11]
	v_mfma_f32_16x16x32_bf16 v[4:7], v[228:231], v[220:223], v[4:7]
	v_mfma_f32_16x16x32_bf16 v[0:3], v[236:239], v[220:223], v[0:3]
	s_barrier
	ds_read_b128 v[176:179], v162
	ds_read_b128 v[180:183], v162 offset:1024
	ds_read_b128 v[184:187], v162 offset:2048
	ds_read_b128 v[188:191], v162 offset:3072
	v_readfirstlane_b32 s43, v164
	v_lshl_add_u64 v[224:225], v[240:241], 0, s[20:21]
	s_mov_b32 m0, s43
	v_readfirstlane_b32 s43, v165
	ds_read_b128 v[192:195], v153 offset:32768
	ds_read_b128 v[196:199], v153 offset:33792
	ds_read_b128 v[200:203], v152 offset:32768
	ds_read_b128 v[204:207], v152 offset:33792
	ds_read_b128 v[208:211], v151 offset:32768
	ds_read_b128 v[212:215], v151 offset:33792
	ds_read_b128 v[216:219], v150 offset:32768
	ds_read_b128 v[220:223], v150 offset:33792
	global_load_lds_dwordx4 v[224:225], off
	v_lshl_add_u64 v[224:225], v[242:243], 0, s[20:21]
	s_mov_b32 m0, s43
	s_nop 0
	global_load_lds_dwordx4 v[224:225], off
	s_waitcnt lgkmcnt(8)
	s_barrier
	s_waitcnt lgkmcnt(0)
	s_waitcnt lgkmcnt(0)
	v_mfma_f32_16x16x32_bf16 v[124:127], v[176:179], v[192:195], v[124:127]
	v_mfma_f32_16x16x32_bf16 v[120:123], v[184:187], v[192:195], v[120:123]
	v_mfma_f32_16x16x32_bf16 v[116:119], v[176:179], v[200:203], v[116:119]
	v_mfma_f32_16x16x32_bf16 v[112:115], v[184:187], v[200:203], v[112:115]
	v_mfma_f32_16x16x32_bf16 v[108:111], v[176:179], v[208:211], v[108:111]
	v_mfma_f32_16x16x32_bf16 v[104:107], v[184:187], v[208:211], v[104:107]
	v_mfma_f32_16x16x32_bf16 v[100:103], v[176:179], v[216:219], v[100:103]
	v_mfma_f32_16x16x32_bf16 v[96:99], v[184:187], v[216:219], v[96:99]
	v_mfma_f32_16x16x32_bf16 v[124:127], v[180:183], v[196:199], v[124:127]
	v_mfma_f32_16x16x32_bf16 v[120:123], v[188:191], v[196:199], v[120:123]
	v_mfma_f32_16x16x32_bf16 v[116:119], v[180:183], v[204:207], v[116:119]
	v_mfma_f32_16x16x32_bf16 v[112:115], v[188:191], v[204:207], v[112:115]
	v_mfma_f32_16x16x32_bf16 v[108:111], v[180:183], v[212:215], v[108:111]
	v_mfma_f32_16x16x32_bf16 v[104:107], v[188:191], v[212:215], v[104:107]
	v_mfma_f32_16x16x32_bf16 v[100:103], v[180:183], v[220:223], v[100:103]
	v_mfma_f32_16x16x32_bf16 v[96:99], v[188:191], v[220:223], v[96:99]
	s_barrier
	v_readfirstlane_b32 s43, v166
	v_lshl_add_u64 v[248:249], v[244:245], 0, s[22:23]
	s_mov_b32 m0, s43
	v_readfirstlane_b32 s43, v167
	ds_read_b128 v[224:227], v159
	ds_read_b128 v[228:231], v159 offset:1024
	ds_read_b128 v[232:235], v159 offset:2048
	ds_read_b128 v[236:239], v159 offset:3072
	global_load_lds_dwordx4 v[248:249], off
	v_lshl_add_u64 v[248:249], v[246:247], 0, s[22:23]
	s_mov_b32 m0, s43
	s_nop 0
	global_load_lds_dwordx4 v[248:249], off
	s_barrier
	s_waitcnt lgkmcnt(0)
	s_waitcnt lgkmcnt(0)
	v_mfma_f32_16x16x32_bf16 v[92:95], v[224:227], v[192:195], v[92:95]
	v_mfma_f32_16x16x32_bf16 v[88:91], v[232:235], v[192:195], v[88:91]
	v_mfma_f32_16x16x32_bf16 v[84:87], v[224:227], v[200:203], v[84:87]
	v_mfma_f32_16x16x32_bf16 v[80:83], v[232:235], v[200:203], v[80:83]
	v_mfma_f32_16x16x32_bf16 v[76:79], v[224:227], v[208:211], v[76:79]
	v_mfma_f32_16x16x32_bf16 v[72:75], v[232:235], v[208:211], v[72:75]
	v_mfma_f32_16x16x32_bf16 v[68:71], v[224:227], v[216:219], v[68:71]
	v_mfma_f32_16x16x32_bf16 v[64:67], v[232:235], v[216:219], v[64:67]
	v_mfma_f32_16x16x32_bf16 v[92:95], v[228:231], v[196:199], v[92:95]
	v_mfma_f32_16x16x32_bf16 v[88:91], v[236:239], v[196:199], v[88:91]
	v_mfma_f32_16x16x32_bf16 v[84:87], v[228:231], v[204:207], v[84:87]
	v_mfma_f32_16x16x32_bf16 v[80:83], v[236:239], v[204:207], v[80:83]
	v_mfma_f32_16x16x32_bf16 v[76:79], v[228:231], v[212:215], v[76:79]
	v_mfma_f32_16x16x32_bf16 v[72:75], v[236:239], v[212:215], v[72:75]
	v_mfma_f32_16x16x32_bf16 v[68:71], v[228:231], v[220:223], v[68:71]
	v_mfma_f32_16x16x32_bf16 v[64:67], v[236:239], v[220:223], v[64:67]
	v_readfirstlane_b32 s43, v168
	v_lshl_add_u64 v[240:241], v[240:241], 0, s[24:25]
	s_mov_b32 m0, s43
	v_readfirstlane_b32 s43, v169
	s_barrier
	ds_read_b128 v[192:195], v153 offset:49152
	ds_read_b128 v[196:199], v153 offset:50176
	ds_read_b128 v[200:203], v152 offset:49152
	ds_read_b128 v[204:207], v152 offset:50176
	ds_read_b128 v[208:211], v151 offset:49152
	ds_read_b128 v[212:215], v151 offset:50176
	ds_read_b128 v[216:219], v150 offset:49152
	ds_read_b128 v[220:223], v150 offset:50176
	global_load_lds_dwordx4 v[240:241], off
	v_lshl_add_u64 v[240:241], v[242:243], 0, s[24:25]
	s_mov_b32 m0, s43
	s_nop 0
	global_load_lds_dwordx4 v[240:241], off
	s_barrier
	s_waitcnt lgkmcnt(0)
	s_waitcnt lgkmcnt(0)
	v_mfma_f32_16x16x32_bf16 v[60:63], v[176:179], v[192:195], v[60:63]
	v_mfma_f32_16x16x32_bf16 v[56:59], v[184:187], v[192:195], v[56:59]
	v_mfma_f32_16x16x32_bf16 v[52:55], v[176:179], v[200:203], v[52:55]
	v_mfma_f32_16x16x32_bf16 v[48:51], v[184:187], v[200:203], v[48:51]
	v_mfma_f32_16x16x32_bf16 v[44:47], v[176:179], v[208:211], v[44:47]
	v_mfma_f32_16x16x32_bf16 v[40:43], v[184:187], v[208:211], v[40:43]
	v_mfma_f32_16x16x32_bf16 v[36:39], v[176:179], v[216:219], v[36:39]
	v_mfma_f32_16x16x32_bf16 v[32:35], v[184:187], v[216:219], v[32:35]
	v_mfma_f32_16x16x32_bf16 v[60:63], v[180:183], v[196:199], v[60:63]
	v_mfma_f32_16x16x32_bf16 v[56:59], v[188:191], v[196:199], v[56:59]
	v_mfma_f32_16x16x32_bf16 v[52:55], v[180:183], v[204:207], v[52:55]
	v_mfma_f32_16x16x32_bf16 v[48:51], v[188:191], v[204:207], v[48:51]
	v_mfma_f32_16x16x32_bf16 v[44:47], v[180:183], v[212:215], v[44:47]
	v_mfma_f32_16x16x32_bf16 v[40:43], v[188:191], v[212:215], v[40:43]
	v_mfma_f32_16x16x32_bf16 v[36:39], v[180:183], v[220:223], v[36:39]
	v_mfma_f32_16x16x32_bf16 v[32:35], v[188:191], v[220:223], v[32:35]
	s_barrier
	v_readfirstlane_b32 s43, v171
	v_lshl_add_u64 v[176:177], v[244:245], 0, s[26:27]
	s_mov_b32 m0, s43
	v_readfirstlane_b32 s43, v172
	global_load_lds_dwordx4 v[176:177], off
	v_lshl_add_u64 v[176:177], v[246:247], 0, s[26:27]
	s_mov_b32 m0, s43
	s_nop 0
	global_load_lds_dwordx4 v[176:177], off
	s_waitcnt vmcnt(6)
	s_barrier
	v_mfma_f32_16x16x32_bf16 v[28:31], v[224:227], v[192:195], v[28:31]
	v_mfma_f32_16x16x32_bf16 v[24:27], v[232:235], v[192:195], v[24:27]
	v_mfma_f32_16x16x32_bf16 v[20:23], v[224:227], v[200:203], v[20:23]
	v_mfma_f32_16x16x32_bf16 v[16:19], v[232:235], v[200:203], v[16:19]
	v_mfma_f32_16x16x32_bf16 v[12:15], v[224:227], v[208:211], v[12:15]
	v_mfma_f32_16x16x32_bf16 v[8:11], v[232:235], v[208:211], v[8:11]
	v_mfma_f32_16x16x32_bf16 v[4:7], v[224:227], v[216:219], v[4:7]
	v_mfma_f32_16x16x32_bf16 v[0:3], v[232:235], v[216:219], v[0:3]
	v_mfma_f32_16x16x32_bf16 v[28:31], v[228:231], v[196:199], v[28:31]
	v_mfma_f32_16x16x32_bf16 v[24:27], v[236:239], v[196:199], v[24:27]
	v_mfma_f32_16x16x32_bf16 v[20:23], v[228:231], v[204:207], v[20:23]
	v_mfma_f32_16x16x32_bf16 v[16:19], v[236:239], v[204:207], v[16:19]
	v_mfma_f32_16x16x32_bf16 v[12:15], v[228:231], v[212:215], v[12:15]
	v_mfma_f32_16x16x32_bf16 v[8:11], v[236:239], v[212:215], v[8:11]
	v_mfma_f32_16x16x32_bf16 v[4:7], v[228:231], v[220:223], v[4:7]
	v_mfma_f32_16x16x32_bf16 v[0:3], v[236:239], v[220:223], v[0:3]
	s_add_i32 s41, s41, 2
	v_lshl_add_u64 v[136:137], v[136:137], 0, s[28:29]
	v_lshl_add_u64 v[138:139], v[138:139], 0, s[28:29]
	v_lshl_add_u64 v[140:141], v[140:141], 0, s[28:29]
	s_cmp_lt_u32 s41, 12
	v_lshl_add_u64 v[142:143], v[142:143], 0, s[28:29]
	s_barrier
	s_cbranch_scc1 .LBB0_574
	v_readfirstlane_b32 s41, v174
	v_lshl_add_u64 v[132:133], v[132:133], 0, s[30:31]
	s_mov_b32 m0, s41
	v_readfirstlane_b32 s41, v175
	ds_read_b128 v[136:139], v173
	ds_read_b128 v[140:143], v173 offset:1024
	ds_read_b128 v[164:167], v173 offset:2048
	ds_read_b128 v[176:179], v173 offset:3072
	ds_read_b128 v[180:183], v153
	ds_read_b128 v[184:187], v153 offset:1024
	ds_read_b128 v[188:191], v152
	ds_read_b128 v[192:195], v152 offset:1024
	ds_read_b128 v[196:199], v151
	ds_read_b128 v[200:203], v151 offset:1024
	ds_read_b128 v[204:207], v150
	ds_read_b128 v[208:211], v150 offset:1024
	global_load_lds_dwordx4 v[132:133], off
	v_lshl_add_u64 v[132:133], v[134:135], 0, s[30:31]
	s_mov_b32 m0, s41
	s_nop 0
	global_load_lds_dwordx4 v[132:133], off
	s_barrier
	s_waitcnt lgkmcnt(0)
	s_waitcnt lgkmcnt(0)
	v_mfma_f32_16x16x32_bf16 v[124:127], v[136:139], v[180:183], v[124:127]
	v_mfma_f32_16x16x32_bf16 v[120:123], v[164:167], v[180:183], v[120:123]
	v_mfma_f32_16x16x32_bf16 v[116:119], v[136:139], v[188:191], v[116:119]
	v_mfma_f32_16x16x32_bf16 v[108:111], v[136:139], v[196:199], v[108:111]
	v_mfma_f32_16x16x32_bf16 v[100:103], v[136:139], v[204:207], v[100:103]
	v_mfma_f32_16x16x32_bf16 v[124:127], v[140:143], v[184:187], v[124:127]
	v_mfma_f32_16x16x32_bf16 v[120:123], v[176:179], v[184:187], v[120:123]
	v_mfma_f32_16x16x32_bf16 v[116:119], v[140:143], v[192:195], v[116:119]
	v_mfma_f32_16x16x32_bf16 v[112:115], v[164:167], v[188:191], v[112:115]
	v_mfma_f32_16x16x32_bf16 v[108:111], v[140:143], v[200:203], v[108:111]
	v_mfma_f32_16x16x32_bf16 v[104:107], v[164:167], v[196:199], v[104:107]
	v_mfma_f32_16x16x32_bf16 v[100:103], v[140:143], v[208:211], v[100:103]
	v_mfma_f32_16x16x32_bf16 v[96:99], v[164:167], v[204:207], v[96:99]
	v_mfma_f32_16x16x32_bf16 v[132:135], v[176:179], v[192:195], v[112:115]
	v_mfma_f32_16x16x32_bf16 v[172:175], v[176:179], v[200:203], v[104:107]
	v_mfma_f32_16x16x32_bf16 v[212:215], v[176:179], v[208:211], v[96:99]
	s_barrier
	s_nop 2
	ds_read_b128 v[96:99], v170
	ds_read_b128 v[104:107], v170 offset:1024
	ds_read_b128 v[112:115], v170 offset:2048
	ds_read_b128 v[168:171], v170 offset:3072
	s_barrier
	s_waitcnt lgkmcnt(0)
	s_waitcnt lgkmcnt(0)
	v_mfma_f32_16x16x32_bf16 v[92:95], v[96:99], v[180:183], v[92:95]
	v_mfma_f32_16x16x32_bf16 v[88:91], v[112:115], v[180:183], v[88:91]
	v_mfma_f32_16x16x32_bf16 v[84:87], v[96:99], v[188:191], v[84:87]
	v_mfma_f32_16x16x32_bf16 v[76:79], v[96:99], v[196:199], v[76:79]
	v_mfma_f32_16x16x32_bf16 v[68:71], v[96:99], v[204:207], v[68:71]
	v_mfma_f32_16x16x32_bf16 v[92:95], v[104:107], v[184:187], v[92:95]
	v_mfma_f32_16x16x32_bf16 v[88:91], v[168:171], v[184:187], v[88:91]
	v_mfma_f32_16x16x32_bf16 v[84:87], v[104:107], v[192:195], v[84:87]
	v_mfma_f32_16x16x32_bf16 v[80:83], v[112:115], v[188:191], v[80:83]
	v_mfma_f32_16x16x32_bf16 v[76:79], v[104:107], v[200:203], v[76:79]
	v_mfma_f32_16x16x32_bf16 v[72:75], v[112:115], v[196:199], v[72:75]
	v_mfma_f32_16x16x32_bf16 v[68:71], v[104:107], v[208:211], v[68:71]
	v_mfma_f32_16x16x32_bf16 v[64:67], v[112:115], v[204:207], v[64:67]
	v_mfma_f32_16x16x32_bf16 v[180:183], v[168:171], v[192:195], v[80:83]
	v_mfma_f32_16x16x32_bf16 v[184:187], v[168:171], v[200:203], v[72:75]
	v_mfma_f32_16x16x32_bf16 v[188:191], v[168:171], v[208:211], v[64:67]
	s_barrier
	s_nop 2
	ds_read_b128 v[64:67], v153 offset:16384
	ds_read_b128 v[72:75], v153 offset:17408
	ds_read_b128 v[80:83], v152 offset:16384
	ds_read_b128 v[192:195], v152 offset:17408
	ds_read_b128 v[196:199], v151 offset:16384
	ds_read_b128 v[200:203], v151 offset:17408
	ds_read_b128 v[204:207], v150 offset:16384
	ds_read_b128 v[208:211], v150 offset:17408
	s_waitcnt vmcnt(4)
	s_barrier
	s_waitcnt lgkmcnt(0)
	s_waitcnt lgkmcnt(0)
	v_mfma_f32_16x16x32_bf16 v[60:63], v[136:139], v[64:67], v[60:63]
	v_mfma_f32_16x16x32_bf16 v[56:59], v[164:167], v[64:67], v[56:59]
	v_mfma_f32_16x16x32_bf16 v[52:55], v[136:139], v[80:83], v[52:55]
	v_mfma_f32_16x16x32_bf16 v[44:47], v[136:139], v[196:199], v[44:47]
	v_mfma_f32_16x16x32_bf16 v[36:39], v[136:139], v[204:207], v[36:39]
	v_mfma_f32_16x16x32_bf16 v[60:63], v[140:143], v[72:75], v[60:63]
	v_mfma_f32_16x16x32_bf16 v[56:59], v[176:179], v[72:75], v[56:59]
	v_mfma_f32_16x16x32_bf16 v[52:55], v[140:143], v[192:195], v[52:55]
	v_mfma_f32_16x16x32_bf16 v[48:51], v[164:167], v[80:83], v[48:51]
	v_mfma_f32_16x16x32_bf16 v[44:47], v[140:143], v[200:203], v[44:47]
	v_mfma_f32_16x16x32_bf16 v[40:43], v[164:167], v[196:199], v[40:43]
	v_mfma_f32_16x16x32_bf16 v[36:39], v[140:143], v[208:211], v[36:39]
	v_mfma_f32_16x16x32_bf16 v[32:35], v[164:167], v[204:207], v[32:35]
	v_mfma_f32_16x16x32_bf16 v[216:219], v[176:179], v[192:195], v[48:51]
	v_mfma_f32_16x16x32_bf16 v[220:223], v[176:179], v[200:203], v[40:43]
	v_mfma_f32_16x16x32_bf16 v[136:139], v[176:179], v[208:211], v[32:35]
	v_mfma_f32_16x16x32_bf16 v[28:31], v[96:99], v[64:67], v[28:31]
	v_mfma_f32_16x16x32_bf16 v[24:27], v[112:115], v[64:67], v[24:27]
	v_mfma_f32_16x16x32_bf16 v[20:23], v[96:99], v[80:83], v[20:23]
	v_mfma_f32_16x16x32_bf16 v[12:15], v[96:99], v[196:199], v[12:15]
	v_mfma_f32_16x16x32_bf16 v[4:7], v[96:99], v[204:207], v[4:7]
	v_mfma_f32_16x16x32_bf16 v[28:31], v[104:107], v[72:75], v[28:31]
	v_mfma_f32_16x16x32_bf16 v[24:27], v[168:171], v[72:75], v[24:27]
	v_mfma_f32_16x16x32_bf16 v[20:23], v[104:107], v[192:195], v[20:23]
	v_mfma_f32_16x16x32_bf16 v[16:19], v[112:115], v[80:83], v[16:19]
	v_mfma_f32_16x16x32_bf16 v[12:15], v[104:107], v[200:203], v[12:15]
	v_mfma_f32_16x16x32_bf16 v[8:11], v[112:115], v[196:199], v[8:11]
	v_mfma_f32_16x16x32_bf16 v[4:7], v[104:107], v[208:211], v[4:7]
	v_mfma_f32_16x16x32_bf16 v[0:3], v[112:115], v[204:207], v[0:3]
	v_mfma_f32_16x16x32_bf16 v[140:143], v[168:171], v[192:195], v[16:19]
	v_mfma_f32_16x16x32_bf16 v[164:167], v[168:171], v[200:203], v[8:11]
	v_mfma_f32_16x16x32_bf16 v[168:171], v[168:171], v[208:211], v[0:3]
	s_barrier
	s_nop 2
	ds_read_b128 v[0:3], v162
	ds_read_b128 v[8:11], v162 offset:1024
	ds_read_b128 v[16:19], v162 offset:2048
	ds_read_b128 v[160:163], v162 offset:3072
	ds_read_b128 v[32:35], v153 offset:32768
	ds_read_b128 v[40:43], v153 offset:33792
	ds_read_b128 v[48:51], v152 offset:32768
	ds_read_b128 v[64:67], v152 offset:33792
	ds_read_b128 v[176:179], v151 offset:32768
	ds_read_b128 v[192:195], v151 offset:33792
	ds_read_b128 v[196:199], v150 offset:32768
	ds_read_b128 v[200:203], v150 offset:33792
	s_waitcnt vmcnt(2)
	s_barrier
	s_waitcnt lgkmcnt(0)
	s_waitcnt lgkmcnt(0)
	v_mfma_f32_16x16x32_bf16 v[72:75], v[0:3], v[32:35], v[124:127]
	v_mfma_f32_16x16x32_bf16 v[124:127], v[8:11], v[40:43], v[72:75]
	v_mfma_f32_16x16x32_bf16 v[72:75], v[16:19], v[32:35], v[120:123]
	v_mfma_f32_16x16x32_bf16 v[120:123], v[160:163], v[40:43], v[72:75]
	v_mfma_f32_16x16x32_bf16 v[72:75], v[0:3], v[48:51], v[116:119]
	v_mfma_f32_16x16x32_bf16 v[112:115], v[8:11], v[64:67], v[72:75]
	v_mfma_f32_16x16x32_bf16 v[72:75], v[16:19], v[48:51], v[132:135]
	v_mfma_f32_16x16x32_bf16 v[116:119], v[160:163], v[64:67], v[72:75]
	v_mfma_f32_16x16x32_bf16 v[72:75], v[0:3], v[176:179], v[108:111]
	v_mfma_f32_16x16x32_bf16 v[104:107], v[8:11], v[192:195], v[72:75]
	v_mfma_f32_16x16x32_bf16 v[72:75], v[16:19], v[176:179], v[172:175]
	v_mfma_f32_16x16x32_bf16 v[108:111], v[160:163], v[192:195], v[72:75]
	v_mfma_f32_16x16x32_bf16 v[72:75], v[0:3], v[196:199], v[100:103]
	v_mfma_f32_16x16x32_bf16 v[96:99], v[8:11], v[200:203], v[72:75]
	v_mfma_f32_16x16x32_bf16 v[72:75], v[16:19], v[196:199], v[212:215]
	v_mfma_f32_16x16x32_bf16 v[100:103], v[160:163], v[200:203], v[72:75]
	s_barrier
	ds_read_b128 v[132:135], v159
	ds_read_b128 v[172:175], v159 offset:1024
	ds_read_b128 v[204:207], v159 offset:2048
	ds_read_b128 v[208:211], v159 offset:3072
	s_waitcnt vmcnt(0)
	s_barrier
	s_waitcnt lgkmcnt(0)
	s_waitcnt lgkmcnt(0)
	v_mfma_f32_16x16x32_bf16 v[72:75], v[132:135], v[32:35], v[92:95]
	v_mfma_f32_16x16x32_bf16 v[32:35], v[204:207], v[32:35], v[88:91]
	v_mfma_f32_16x16x32_bf16 v[88:91], v[208:211], v[40:43], v[32:35]
	v_mfma_f32_16x16x32_bf16 v[32:35], v[132:135], v[48:51], v[84:87]
	v_mfma_f32_16x16x32_bf16 v[80:83], v[172:175], v[64:67], v[32:35]
	v_mfma_f32_16x16x32_bf16 v[32:35], v[204:207], v[48:51], v[180:183]
	v_mfma_f32_16x16x32_bf16 v[84:87], v[208:211], v[64:67], v[32:35]
	v_mfma_f32_16x16x32_bf16 v[32:35], v[132:135], v[176:179], v[76:79]
	v_mfma_f32_16x16x32_bf16 v[92:95], v[172:175], v[40:43], v[72:75]
	v_mfma_f32_16x16x32_bf16 v[72:75], v[172:175], v[192:195], v[32:35]
	v_mfma_f32_16x16x32_bf16 v[32:35], v[204:207], v[176:179], v[184:187]
	v_mfma_f32_16x16x32_bf16 v[76:79], v[208:211], v[192:195], v[32:35]
	v_mfma_f32_16x16x32_bf16 v[32:35], v[132:135], v[196:199], v[68:71]
	v_mfma_f32_16x16x32_bf16 v[64:67], v[172:175], v[200:203], v[32:35]
	v_mfma_f32_16x16x32_bf16 v[32:35], v[204:207], v[196:199], v[188:191]
	v_mfma_f32_16x16x32_bf16 v[68:71], v[208:211], v[200:203], v[32:35]
	s_barrier
	ds_read_b128 v[176:179], v153 offset:49152
	ds_read_b128 v[180:183], v153 offset:50176
	ds_read_b128 v[184:187], v152 offset:49152
	ds_read_b128 v[188:191], v152 offset:50176
	ds_read_b128 v[192:195], v151 offset:49152
	ds_read_b128 v[196:199], v151 offset:50176
	ds_read_b128 v[200:203], v150 offset:49152
	ds_read_b128 v[150:153], v150 offset:50176
	s_barrier
	s_waitcnt lgkmcnt(0)
	s_waitcnt lgkmcnt(0)
	v_mfma_f32_16x16x32_bf16 v[32:35], v[0:3], v[176:179], v[60:63]
	v_mfma_f32_16x16x32_bf16 v[60:63], v[8:11], v[180:183], v[32:35]
	v_mfma_f32_16x16x32_bf16 v[32:35], v[16:19], v[176:179], v[56:59]
	v_mfma_f32_16x16x32_bf16 v[56:59], v[160:163], v[180:183], v[32:35]
	v_mfma_f32_16x16x32_bf16 v[32:35], v[0:3], v[184:187], v[52:55]
	v_mfma_f32_16x16x32_bf16 v[48:51], v[8:11], v[188:191], v[32:35]
	v_mfma_f32_16x16x32_bf16 v[32:35], v[16:19], v[184:187], v[216:219]
	v_mfma_f32_16x16x32_bf16 v[52:55], v[160:163], v[188:191], v[32:35]
	v_mfma_f32_16x16x32_bf16 v[32:35], v[0:3], v[192:195], v[44:47]
	v_mfma_f32_16x16x32_bf16 v[40:43], v[8:11], v[196:199], v[32:35]
	v_mfma_f32_16x16x32_bf16 v[32:35], v[16:19], v[192:195], v[220:223]
	v_mfma_f32_16x16x32_bf16 v[0:3], v[0:3], v[200:203], v[36:39]
	v_mfma_f32_16x16x32_bf16 v[44:47], v[160:163], v[196:199], v[32:35]
	v_mfma_f32_16x16x32_bf16 v[32:35], v[8:11], v[150:153], v[0:3]
	v_mfma_f32_16x16x32_bf16 v[0:3], v[16:19], v[200:203], v[136:139]
	v_mfma_f32_16x16x32_bf16 v[36:39], v[160:163], v[150:153], v[0:3]
	v_mfma_f32_16x16x32_bf16 v[0:3], v[132:135], v[176:179], v[28:31]
	v_mfma_f32_16x16x32_bf16 v[28:31], v[172:175], v[180:183], v[0:3]
	v_mfma_f32_16x16x32_bf16 v[0:3], v[204:207], v[176:179], v[24:27]
	v_mfma_f32_16x16x32_bf16 v[24:27], v[208:211], v[180:183], v[0:3]
	v_mfma_f32_16x16x32_bf16 v[0:3], v[132:135], v[184:187], v[20:23]
	v_mfma_f32_16x16x32_bf16 v[16:19], v[172:175], v[188:191], v[0:3]
	v_mfma_f32_16x16x32_bf16 v[0:3], v[204:207], v[184:187], v[140:143]
	v_mfma_f32_16x16x32_bf16 v[20:23], v[208:211], v[188:191], v[0:3]
	v_mfma_f32_16x16x32_bf16 v[0:3], v[132:135], v[192:195], v[12:15]
	v_mfma_f32_16x16x32_bf16 v[8:11], v[172:175], v[196:199], v[0:3]
	v_mfma_f32_16x16x32_bf16 v[0:3], v[204:207], v[192:195], v[164:167]
	v_mfma_f32_16x16x32_bf16 v[12:15], v[208:211], v[196:199], v[0:3]
	v_mfma_f32_16x16x32_bf16 v[0:3], v[132:135], v[200:203], v[4:7]
	v_mfma_f32_16x16x32_bf16 v[4:7], v[204:207], v[200:203], v[168:171]
	v_mfma_f32_16x16x32_bf16 v[0:3], v[172:175], v[150:153], v[0:3]
	v_mfma_f32_16x16x32_bf16 v[4:7], v[208:211], v[150:153], v[4:7]
	v_cmp_gt_u32_e32 vcc, s57, v130
	s_barrier
	s_and_saveexec_b64 s[44:45], vcc
	s_cbranch_execz .LBB0_568
	s_barrier
	s_branch .LBB0_568

.LBB0_692:
	ds_read_b128 v[176:179], v172
	ds_read_b128 v[180:183], v172 offset:1024
	ds_read_b128 v[184:187], v172 offset:2048
	ds_read_b128 v[188:191], v172 offset:3072
	v_add_u32_e32 v173, 0xc000, v159
	v_lshl_add_u64 v[240:241], s[4:5], 0, v[136:137]
	v_readfirstlane_b32 s38, v173
	v_lshl_add_u64 v[174:175], v[240:241], 0, s[10:11]
	s_mov_b32 m0, s38
	ds_read_b128 v[192:195], v152
	ds_read_b128 v[196:199], v152 offset:1024
	ds_read_b128 v[200:203], v151
	ds_read_b128 v[204:207], v151 offset:1024
	ds_read_b128 v[208:211], v150
	ds_read_b128 v[212:215], v150 offset:1024
	ds_read_b128 v[216:219], v149
	ds_read_b128 v[220:223], v149 offset:1024
	global_load_lds_dwordx4 v[174:175], off
	v_add_u32_e32 v174, 0xe000, v159
	v_lshl_add_u64 v[242:243], s[4:5], 0, v[134:135]
	v_readfirstlane_b32 s38, v174
	v_lshl_add_u64 v[224:225], v[242:243], 0, s[10:11]
	s_mov_b32 m0, s38
	s_nop 0
	global_load_lds_dwordx4 v[224:225], off
	s_waitcnt lgkmcnt(8)
	s_barrier
	s_waitcnt lgkmcnt(0)
	s_waitcnt lgkmcnt(0)
	v_mfma_f32_16x16x32_bf16 v[124:127], v[176:179], v[192:195], v[124:127]
	v_mfma_f32_16x16x32_bf16 v[120:123], v[184:187], v[192:195], v[120:123]
	v_mfma_f32_16x16x32_bf16 v[116:119], v[176:179], v[200:203], v[116:119]
	v_mfma_f32_16x16x32_bf16 v[112:115], v[184:187], v[200:203], v[112:115]
	v_mfma_f32_16x16x32_bf16 v[108:111], v[176:179], v[208:211], v[108:111]
	v_mfma_f32_16x16x32_bf16 v[104:107], v[184:187], v[208:211], v[104:107]
	v_mfma_f32_16x16x32_bf16 v[100:103], v[176:179], v[216:219], v[100:103]
	v_mfma_f32_16x16x32_bf16 v[96:99], v[184:187], v[216:219], v[96:99]
	v_mfma_f32_16x16x32_bf16 v[124:127], v[180:183], v[196:199], v[124:127]
	v_mfma_f32_16x16x32_bf16 v[120:123], v[188:191], v[196:199], v[120:123]
	v_mfma_f32_16x16x32_bf16 v[116:119], v[180:183], v[204:207], v[116:119]
	v_mfma_f32_16x16x32_bf16 v[112:115], v[188:191], v[204:207], v[112:115]
	v_mfma_f32_16x16x32_bf16 v[108:111], v[180:183], v[212:215], v[108:111]
	v_mfma_f32_16x16x32_bf16 v[104:107], v[188:191], v[212:215], v[104:107]
	v_mfma_f32_16x16x32_bf16 v[100:103], v[180:183], v[220:223], v[100:103]
	v_mfma_f32_16x16x32_bf16 v[96:99], v[188:191], v[220:223], v[96:99]
	s_barrier
	v_lshl_add_u64 v[244:245], s[4:5], 0, v[140:141]
	v_readfirstlane_b32 s38, v148
	v_lshl_add_u64 v[246:247], v[244:245], 0, s[12:13]
	s_mov_b32 m0, s38
	v_add_u32_e32 v175, 0x2000, v148
	ds_read_b128 v[224:227], v169
	ds_read_b128 v[228:231], v169 offset:1024
	ds_read_b128 v[232:235], v169 offset:2048
	ds_read_b128 v[236:239], v169 offset:3072
	global_load_lds_dwordx4 v[246:247], off
	v_lshl_add_u64 v[246:247], s[4:5], 0, v[138:139]
	v_readfirstlane_b32 s38, v175
	v_lshl_add_u64 v[248:249], v[246:247], 0, s[12:13]
	s_mov_b32 m0, s38
	s_nop 0
	global_load_lds_dwordx4 v[248:249], off
	s_barrier
	s_waitcnt lgkmcnt(0)
	s_waitcnt lgkmcnt(0)
	v_mfma_f32_16x16x32_bf16 v[92:95], v[224:227], v[192:195], v[92:95]
	v_mfma_f32_16x16x32_bf16 v[88:91], v[232:235], v[192:195], v[88:91]
	v_mfma_f32_16x16x32_bf16 v[84:87], v[224:227], v[200:203], v[84:87]
	v_mfma_f32_16x16x32_bf16 v[80:83], v[232:235], v[200:203], v[80:83]
	v_mfma_f32_16x16x32_bf16 v[76:79], v[224:227], v[208:211], v[76:79]
	v_mfma_f32_16x16x32_bf16 v[72:75], v[232:235], v[208:211], v[72:75]
	v_mfma_f32_16x16x32_bf16 v[68:71], v[224:227], v[216:219], v[68:71]
	v_mfma_f32_16x16x32_bf16 v[64:67], v[232:235], v[216:219], v[64:67]
	v_mfma_f32_16x16x32_bf16 v[92:95], v[228:231], v[196:199], v[92:95]
	v_mfma_f32_16x16x32_bf16 v[88:91], v[236:239], v[196:199], v[88:91]
	v_mfma_f32_16x16x32_bf16 v[84:87], v[228:231], v[204:207], v[84:87]
	v_mfma_f32_16x16x32_bf16 v[80:83], v[236:239], v[204:207], v[80:83]
	v_mfma_f32_16x16x32_bf16 v[76:79], v[228:231], v[212:215], v[76:79]
	v_mfma_f32_16x16x32_bf16 v[72:75], v[236:239], v[212:215], v[72:75]
	v_mfma_f32_16x16x32_bf16 v[68:71], v[228:231], v[220:223], v[68:71]
	v_mfma_f32_16x16x32_bf16 v[64:67], v[236:239], v[220:223], v[64:67]
	v_readfirstlane_b32 s38, v159
	v_lshl_add_u64 v[248:249], v[240:241], 0, s[14:15]
	s_mov_b32 m0, s38
	v_readfirstlane_b32 s38, v160
	s_barrier
	ds_read_b128 v[192:195], v152 offset:16384
	ds_read_b128 v[196:199], v152 offset:17408
	ds_read_b128 v[200:203], v151 offset:16384
	ds_read_b128 v[204:207], v151 offset:17408
	ds_read_b128 v[208:211], v150 offset:16384
	ds_read_b128 v[212:215], v150 offset:17408
	ds_read_b128 v[216:219], v149 offset:16384
	ds_read_b128 v[220:223], v149 offset:17408
	global_load_lds_dwordx4 v[248:249], off
	v_lshl_add_u64 v[248:249], v[242:243], 0, s[14:15]
	s_mov_b32 m0, s38
	s_nop 0
	global_load_lds_dwordx4 v[248:249], off
	s_barrier
	s_waitcnt lgkmcnt(0)
	s_waitcnt lgkmcnt(0)
	v_mfma_f32_16x16x32_bf16 v[60:63], v[176:179], v[192:195], v[60:63]
	v_mfma_f32_16x16x32_bf16 v[56:59], v[184:187], v[192:195], v[56:59]
	v_mfma_f32_16x16x32_bf16 v[52:55], v[176:179], v[200:203], v[52:55]
	v_mfma_f32_16x16x32_bf16 v[48:51], v[184:187], v[200:203], v[48:51]
	v_mfma_f32_16x16x32_bf16 v[44:47], v[176:179], v[208:211], v[44:47]
	v_mfma_f32_16x16x32_bf16 v[40:43], v[184:187], v[208:211], v[40:43]
	v_mfma_f32_16x16x32_bf16 v[36:39], v[176:179], v[216:219], v[36:39]
	v_mfma_f32_16x16x32_bf16 v[32:35], v[184:187], v[216:219], v[32:35]
	v_mfma_f32_16x16x32_bf16 v[60:63], v[180:183], v[196:199], v[60:63]
	v_mfma_f32_16x16x32_bf16 v[56:59], v[188:191], v[196:199], v[56:59]
	v_mfma_f32_16x16x32_bf16 v[52:55], v[180:183], v[204:207], v[52:55]
	v_mfma_f32_16x16x32_bf16 v[48:51], v[188:191], v[204:207], v[48:51]
	v_mfma_f32_16x16x32_bf16 v[44:47], v[180:183], v[212:215], v[44:47]
	v_mfma_f32_16x16x32_bf16 v[40:43], v[188:191], v[212:215], v[40:43]
	v_mfma_f32_16x16x32_bf16 v[36:39], v[180:183], v[220:223], v[36:39]
	v_mfma_f32_16x16x32_bf16 v[32:35], v[188:191], v[220:223], v[32:35]
	s_barrier
	v_readfirstlane_b32 s38, v162
	v_add_u32_e32 v175, 0x2000, v162
	v_lshl_add_u64 v[176:177], v[244:245], 0, s[16:17]
	s_mov_b32 m0, s38
	v_readfirstlane_b32 s38, v175
	global_load_lds_dwordx4 v[176:177], off
	v_lshl_add_u64 v[176:177], v[246:247], 0, s[16:17]
	s_mov_b32 m0, s38
	s_nop 0
	global_load_lds_dwordx4 v[176:177], off
	s_waitcnt vmcnt(6)
	s_barrier
	v_mfma_f32_16x16x32_bf16 v[28:31], v[224:227], v[192:195], v[28:31]
	v_mfma_f32_16x16x32_bf16 v[24:27], v[232:235], v[192:195], v[24:27]
	v_mfma_f32_16x16x32_bf16 v[20:23], v[224:227], v[200:203], v[20:23]
	v_mfma_f32_16x16x32_bf16 v[16:19], v[232:235], v[200:203], v[16:19]
	v_mfma_f32_16x16x32_bf16 v[12:15], v[224:227], v[208:211], v[12:15]
	v_mfma_f32_16x16x32_bf16 v[8:11], v[232:235], v[208:211], v[8:11]
	v_mfma_f32_16x16x32_bf16 v[4:7], v[224:227], v[216:219], v[4:7]
	v_mfma_f32_16x16x32_bf16 v[0:3], v[232:235], v[216:219], v[0:3]
	v_mfma_f32_16x16x32_bf16 v[28:31], v[228:231], v[196:199], v[28:31]
	v_mfma_f32_16x16x32_bf16 v[24:27], v[236:239], v[196:199], v[24:27]
	v_mfma_f32_16x16x32_bf16 v[20:23], v[228:231], v[204:207], v[20:23]
	v_mfma_f32_16x16x32_bf16 v[16:19], v[236:239], v[204:207], v[16:19]
	v_mfma_f32_16x16x32_bf16 v[12:15], v[228:231], v[212:215], v[12:15]
	v_mfma_f32_16x16x32_bf16 v[8:11], v[236:239], v[212:215], v[8:11]
	v_mfma_f32_16x16x32_bf16 v[4:7], v[228:231], v[220:223], v[4:7]
	v_mfma_f32_16x16x32_bf16 v[0:3], v[236:239], v[220:223], v[0:3]
	s_barrier
	ds_read_b128 v[176:179], v161
	ds_read_b128 v[180:183], v161 offset:1024
	ds_read_b128 v[184:187], v161 offset:2048
	ds_read_b128 v[188:191], v161 offset:3072
	v_readfirstlane_b32 s38, v163
	v_lshl_add_u64 v[224:225], v[240:241], 0, s[18:19]
	s_mov_b32 m0, s38
	v_readfirstlane_b32 s38, v164
	ds_read_b128 v[192:195], v152 offset:32768
	ds_read_b128 v[196:199], v152 offset:33792
	ds_read_b128 v[200:203], v151 offset:32768
	ds_read_b128 v[204:207], v151 offset:33792
	ds_read_b128 v[208:211], v150 offset:32768
	ds_read_b128 v[212:215], v150 offset:33792
	ds_read_b128 v[216:219], v149 offset:32768
	ds_read_b128 v[220:223], v149 offset:33792
	global_load_lds_dwordx4 v[224:225], off
	v_lshl_add_u64 v[224:225], v[242:243], 0, s[18:19]
	s_mov_b32 m0, s38
	s_nop 0
	global_load_lds_dwordx4 v[224:225], off
	s_waitcnt lgkmcnt(8)
	s_barrier
	s_waitcnt lgkmcnt(0)
	s_waitcnt lgkmcnt(0)
	v_mfma_f32_16x16x32_bf16 v[124:127], v[176:179], v[192:195], v[124:127]
	v_mfma_f32_16x16x32_bf16 v[120:123], v[184:187], v[192:195], v[120:123]
	v_mfma_f32_16x16x32_bf16 v[116:119], v[176:179], v[200:203], v[116:119]
	v_mfma_f32_16x16x32_bf16 v[112:115], v[184:187], v[200:203], v[112:115]
	v_mfma_f32_16x16x32_bf16 v[108:111], v[176:179], v[208:211], v[108:111]
	v_mfma_f32_16x16x32_bf16 v[104:107], v[184:187], v[208:211], v[104:107]
	v_mfma_f32_16x16x32_bf16 v[100:103], v[176:179], v[216:219], v[100:103]
	v_mfma_f32_16x16x32_bf16 v[96:99], v[184:187], v[216:219], v[96:99]
	v_mfma_f32_16x16x32_bf16 v[124:127], v[180:183], v[196:199], v[124:127]
	v_mfma_f32_16x16x32_bf16 v[120:123], v[188:191], v[196:199], v[120:123]
	v_mfma_f32_16x16x32_bf16 v[116:119], v[180:183], v[204:207], v[116:119]
	v_mfma_f32_16x16x32_bf16 v[112:115], v[188:191], v[204:207], v[112:115]
	v_mfma_f32_16x16x32_bf16 v[108:111], v[180:183], v[212:215], v[108:111]
	v_mfma_f32_16x16x32_bf16 v[104:107], v[188:191], v[212:215], v[104:107]
	v_mfma_f32_16x16x32_bf16 v[100:103], v[180:183], v[220:223], v[100:103]
	v_mfma_f32_16x16x32_bf16 v[96:99], v[188:191], v[220:223], v[96:99]
	s_barrier
	v_readfirstlane_b32 s38, v165
	v_lshl_add_u64 v[248:249], v[244:245], 0, s[20:21]
	s_mov_b32 m0, s38
	v_readfirstlane_b32 s38, v166
	ds_read_b128 v[224:227], v153
	ds_read_b128 v[228:231], v153 offset:1024
	ds_read_b128 v[232:235], v153 offset:2048
	ds_read_b128 v[236:239], v153 offset:3072
	global_load_lds_dwordx4 v[248:249], off
	v_lshl_add_u64 v[248:249], v[246:247], 0, s[20:21]
	s_mov_b32 m0, s38
	s_nop 0
	global_load_lds_dwordx4 v[248:249], off
	s_barrier
	s_waitcnt lgkmcnt(0)
	s_waitcnt lgkmcnt(0)
	v_mfma_f32_16x16x32_bf16 v[92:95], v[224:227], v[192:195], v[92:95]
	v_mfma_f32_16x16x32_bf16 v[88:91], v[232:235], v[192:195], v[88:91]
	v_mfma_f32_16x16x32_bf16 v[84:87], v[224:227], v[200:203], v[84:87]
	v_mfma_f32_16x16x32_bf16 v[80:83], v[232:235], v[200:203], v[80:83]
	v_mfma_f32_16x16x32_bf16 v[76:79], v[224:227], v[208:211], v[76:79]
	v_mfma_f32_16x16x32_bf16 v[72:75], v[232:235], v[208:211], v[72:75]
	v_mfma_f32_16x16x32_bf16 v[68:71], v[224:227], v[216:219], v[68:71]
	v_mfma_f32_16x16x32_bf16 v[64:67], v[232:235], v[216:219], v[64:67]
	v_mfma_f32_16x16x32_bf16 v[92:95], v[228:231], v[196:199], v[92:95]
	v_mfma_f32_16x16x32_bf16 v[88:91], v[236:239], v[196:199], v[88:91]
	v_mfma_f32_16x16x32_bf16 v[84:87], v[228:231], v[204:207], v[84:87]
	v_mfma_f32_16x16x32_bf16 v[80:83], v[236:239], v[204:207], v[80:83]
	v_mfma_f32_16x16x32_bf16 v[76:79], v[228:231], v[212:215], v[76:79]
	v_mfma_f32_16x16x32_bf16 v[72:75], v[236:239], v[212:215], v[72:75]
	v_mfma_f32_16x16x32_bf16 v[68:71], v[228:231], v[220:223], v[68:71]
	v_mfma_f32_16x16x32_bf16 v[64:67], v[236:239], v[220:223], v[64:67]
	v_readfirstlane_b32 s38, v167
	v_lshl_add_u64 v[240:241], v[240:241], 0, s[22:23]
	s_mov_b32 m0, s38
	v_readfirstlane_b32 s38, v168
	s_barrier
	ds_read_b128 v[192:195], v152 offset:49152
	ds_read_b128 v[196:199], v152 offset:50176
	ds_read_b128 v[200:203], v151 offset:49152
	ds_read_b128 v[204:207], v151 offset:50176
	ds_read_b128 v[208:211], v150 offset:49152
	ds_read_b128 v[212:215], v150 offset:50176
	ds_read_b128 v[216:219], v149 offset:49152
	ds_read_b128 v[220:223], v149 offset:50176
	global_load_lds_dwordx4 v[240:241], off
	v_lshl_add_u64 v[240:241], v[242:243], 0, s[22:23]
	s_mov_b32 m0, s38
	s_nop 0
	global_load_lds_dwordx4 v[240:241], off
	s_barrier
	s_waitcnt lgkmcnt(0)
	s_waitcnt lgkmcnt(0)
	v_mfma_f32_16x16x32_bf16 v[60:63], v[176:179], v[192:195], v[60:63]
	v_mfma_f32_16x16x32_bf16 v[56:59], v[184:187], v[192:195], v[56:59]
	v_mfma_f32_16x16x32_bf16 v[52:55], v[176:179], v[200:203], v[52:55]
	v_mfma_f32_16x16x32_bf16 v[48:51], v[184:187], v[200:203], v[48:51]
	v_mfma_f32_16x16x32_bf16 v[44:47], v[176:179], v[208:211], v[44:47]
	v_mfma_f32_16x16x32_bf16 v[40:43], v[184:187], v[208:211], v[40:43]
	v_mfma_f32_16x16x32_bf16 v[36:39], v[176:179], v[216:219], v[36:39]
	v_mfma_f32_16x16x32_bf16 v[32:35], v[184:187], v[216:219], v[32:35]
	v_mfma_f32_16x16x32_bf16 v[60:63], v[180:183], v[196:199], v[60:63]
	v_mfma_f32_16x16x32_bf16 v[56:59], v[188:191], v[196:199], v[56:59]
	v_mfma_f32_16x16x32_bf16 v[52:55], v[180:183], v[204:207], v[52:55]
	v_mfma_f32_16x16x32_bf16 v[48:51], v[188:191], v[204:207], v[48:51]
	v_mfma_f32_16x16x32_bf16 v[44:47], v[180:183], v[212:215], v[44:47]
	v_mfma_f32_16x16x32_bf16 v[40:43], v[188:191], v[212:215], v[40:43]
	v_mfma_f32_16x16x32_bf16 v[36:39], v[180:183], v[220:223], v[36:39]
	v_mfma_f32_16x16x32_bf16 v[32:35], v[188:191], v[220:223], v[32:35]
	s_barrier
	v_readfirstlane_b32 s38, v170
	v_lshl_add_u64 v[176:177], v[244:245], 0, s[24:25]
	s_mov_b32 m0, s38
	v_readfirstlane_b32 s38, v171
	global_load_lds_dwordx4 v[176:177], off
	v_lshl_add_u64 v[176:177], v[246:247], 0, s[24:25]
	s_mov_b32 m0, s38
	s_nop 0
	global_load_lds_dwordx4 v[176:177], off
	s_waitcnt vmcnt(6)
	s_barrier
	v_mfma_f32_16x16x32_bf16 v[28:31], v[224:227], v[192:195], v[28:31]
	v_mfma_f32_16x16x32_bf16 v[24:27], v[232:235], v[192:195], v[24:27]
	v_mfma_f32_16x16x32_bf16 v[20:23], v[224:227], v[200:203], v[20:23]
	v_mfma_f32_16x16x32_bf16 v[16:19], v[232:235], v[200:203], v[16:19]
	v_mfma_f32_16x16x32_bf16 v[12:15], v[224:227], v[208:211], v[12:15]
	v_mfma_f32_16x16x32_bf16 v[8:11], v[232:235], v[208:211], v[8:11]
	v_mfma_f32_16x16x32_bf16 v[4:7], v[224:227], v[216:219], v[4:7]
	v_mfma_f32_16x16x32_bf16 v[0:3], v[232:235], v[216:219], v[0:3]
	v_mfma_f32_16x16x32_bf16 v[28:31], v[228:231], v[196:199], v[28:31]
	v_mfma_f32_16x16x32_bf16 v[24:27], v[236:239], v[196:199], v[24:27]
	v_mfma_f32_16x16x32_bf16 v[20:23], v[228:231], v[204:207], v[20:23]
	v_mfma_f32_16x16x32_bf16 v[16:19], v[236:239], v[204:207], v[16:19]
	v_mfma_f32_16x16x32_bf16 v[12:15], v[228:231], v[212:215], v[12:15]
	v_mfma_f32_16x16x32_bf16 v[8:11], v[236:239], v[212:215], v[8:11]
	v_mfma_f32_16x16x32_bf16 v[4:7], v[228:231], v[220:223], v[4:7]
	v_mfma_f32_16x16x32_bf16 v[0:3], v[236:239], v[220:223], v[0:3]
	s_add_i32 s31, s31, 2
	v_lshl_add_u64 v[134:135], v[134:135], 0, s[26:27]
	v_lshl_add_u64 v[136:137], v[136:137], 0, s[26:27]
	v_lshl_add_u64 v[138:139], v[138:139], 0, s[26:27]
	s_cmp_lt_u32 s31, 12
	v_lshl_add_u64 v[140:141], v[140:141], 0, s[26:27]
	s_barrier
	s_cbranch_scc1 .LBB0_692
	v_readfirstlane_b32 s31, v173
	v_lshl_add_u64 v[130:131], v[130:131], 0, s[28:29]
	s_mov_b32 m0, s31
	v_readfirstlane_b32 s31, v174
	ds_read_b128 v[134:137], v172
	ds_read_b128 v[138:141], v172 offset:1024
	ds_read_b128 v[162:165], v172 offset:2048
	ds_read_b128 v[176:179], v172 offset:3072
	ds_read_b128 v[180:183], v152
	ds_read_b128 v[184:187], v152 offset:1024
	ds_read_b128 v[188:191], v151
	ds_read_b128 v[192:195], v151 offset:1024
	ds_read_b128 v[196:199], v150
	ds_read_b128 v[200:203], v150 offset:1024
	ds_read_b128 v[204:207], v149
	ds_read_b128 v[208:211], v149 offset:1024
	global_load_lds_dwordx4 v[130:131], off
	v_lshl_add_u64 v[130:131], v[132:133], 0, s[28:29]
	s_mov_b32 m0, s31
	s_nop 0
	global_load_lds_dwordx4 v[130:131], off
	s_barrier
	s_waitcnt lgkmcnt(0)
	s_waitcnt lgkmcnt(0)
	v_mfma_f32_16x16x32_bf16 v[124:127], v[134:137], v[180:183], v[124:127]
	v_mfma_f32_16x16x32_bf16 v[120:123], v[162:165], v[180:183], v[120:123]
	v_mfma_f32_16x16x32_bf16 v[116:119], v[134:137], v[188:191], v[116:119]
	v_mfma_f32_16x16x32_bf16 v[112:115], v[162:165], v[188:191], v[112:115]
	v_mfma_f32_16x16x32_bf16 v[108:111], v[134:137], v[196:199], v[108:111]
	v_mfma_f32_16x16x32_bf16 v[104:107], v[162:165], v[196:199], v[104:107]
	v_mfma_f32_16x16x32_bf16 v[100:103], v[134:137], v[204:207], v[100:103]
	v_mfma_f32_16x16x32_bf16 v[96:99], v[162:165], v[204:207], v[96:99]
	v_mfma_f32_16x16x32_bf16 v[124:127], v[138:141], v[184:187], v[124:127]
	v_mfma_f32_16x16x32_bf16 v[120:123], v[176:179], v[184:187], v[120:123]
	v_mfma_f32_16x16x32_bf16 v[116:119], v[138:141], v[192:195], v[116:119]
	v_mfma_f32_16x16x32_bf16 v[112:115], v[176:179], v[192:195], v[112:115]
	v_mfma_f32_16x16x32_bf16 v[108:111], v[138:141], v[200:203], v[108:111]
	v_mfma_f32_16x16x32_bf16 v[104:107], v[176:179], v[200:203], v[104:107]
	v_mfma_f32_16x16x32_bf16 v[100:103], v[138:141], v[208:211], v[100:103]
	v_mfma_f32_16x16x32_bf16 v[96:99], v[176:179], v[208:211], v[96:99]
	s_barrier
	ds_read_b128 v[130:133], v169
	ds_read_b128 v[170:173], v169 offset:1024
	ds_read_b128 v[212:215], v169 offset:2048
	ds_read_b128 v[166:169], v169 offset:3072
	s_barrier
	s_waitcnt lgkmcnt(0)
	s_waitcnt lgkmcnt(0)
	v_mfma_f32_16x16x32_bf16 v[92:95], v[130:133], v[180:183], v[92:95]
	v_mfma_f32_16x16x32_bf16 v[88:91], v[212:215], v[180:183], v[88:91]
	v_mfma_f32_16x16x32_bf16 v[84:87], v[130:133], v[188:191], v[84:87]
	v_mfma_f32_16x16x32_bf16 v[80:83], v[212:215], v[188:191], v[80:83]
	v_mfma_f32_16x16x32_bf16 v[76:79], v[130:133], v[196:199], v[76:79]
	v_mfma_f32_16x16x32_bf16 v[72:75], v[212:215], v[196:199], v[72:75]
	v_mfma_f32_16x16x32_bf16 v[68:71], v[130:133], v[204:207], v[68:71]
	v_mfma_f32_16x16x32_bf16 v[64:67], v[212:215], v[204:207], v[64:67]
	v_mfma_f32_16x16x32_bf16 v[92:95], v[170:173], v[184:187], v[92:95]
	v_mfma_f32_16x16x32_bf16 v[88:91], v[166:169], v[184:187], v[88:91]
	v_mfma_f32_16x16x32_bf16 v[84:87], v[170:173], v[192:195], v[84:87]
	v_mfma_f32_16x16x32_bf16 v[80:83], v[166:169], v[192:195], v[80:83]
	v_mfma_f32_16x16x32_bf16 v[76:79], v[170:173], v[200:203], v[76:79]
	v_mfma_f32_16x16x32_bf16 v[72:75], v[166:169], v[200:203], v[72:75]
	v_mfma_f32_16x16x32_bf16 v[68:71], v[170:173], v[208:211], v[68:71]
	v_mfma_f32_16x16x32_bf16 v[64:67], v[166:169], v[208:211], v[64:67]
	s_barrier
	ds_read_b128 v[180:183], v152 offset:16384
	ds_read_b128 v[184:187], v152 offset:17408
	ds_read_b128 v[188:191], v151 offset:16384
	ds_read_b128 v[192:195], v151 offset:17408
	ds_read_b128 v[196:199], v150 offset:16384
	ds_read_b128 v[200:203], v150 offset:17408
	ds_read_b128 v[204:207], v149 offset:16384
	ds_read_b128 v[208:211], v149 offset:17408
	s_waitcnt vmcnt(4)
	s_barrier
	s_waitcnt lgkmcnt(0)
	s_waitcnt lgkmcnt(0)
	v_mfma_f32_16x16x32_bf16 v[60:63], v[134:137], v[180:183], v[60:63]
	v_mfma_f32_16x16x32_bf16 v[56:59], v[162:165], v[180:183], v[56:59]
	v_mfma_f32_16x16x32_bf16 v[52:55], v[134:137], v[188:191], v[52:55]
	v_mfma_f32_16x16x32_bf16 v[48:51], v[162:165], v[188:191], v[48:51]
	v_mfma_f32_16x16x32_bf16 v[44:47], v[134:137], v[196:199], v[44:47]
	v_mfma_f32_16x16x32_bf16 v[40:43], v[162:165], v[196:199], v[40:43]
	v_mfma_f32_16x16x32_bf16 v[36:39], v[134:137], v[204:207], v[36:39]
	v_mfma_f32_16x16x32_bf16 v[32:35], v[162:165], v[204:207], v[32:35]
	v_mfma_f32_16x16x32_bf16 v[60:63], v[138:141], v[184:187], v[60:63]
	v_mfma_f32_16x16x32_bf16 v[56:59], v[176:179], v[184:187], v[56:59]
	v_mfma_f32_16x16x32_bf16 v[52:55], v[138:141], v[192:195], v[52:55]
	v_mfma_f32_16x16x32_bf16 v[48:51], v[176:179], v[192:195], v[48:51]
	v_mfma_f32_16x16x32_bf16 v[44:47], v[138:141], v[200:203], v[44:47]
	v_mfma_f32_16x16x32_bf16 v[40:43], v[176:179], v[200:203], v[40:43]
	v_mfma_f32_16x16x32_bf16 v[36:39], v[138:141], v[208:211], v[36:39]
	v_mfma_f32_16x16x32_bf16 v[32:35], v[176:179], v[208:211], v[32:35]
	v_mfma_f32_16x16x32_bf16 v[28:31], v[130:133], v[180:183], v[28:31]
	v_mfma_f32_16x16x32_bf16 v[24:27], v[212:215], v[180:183], v[24:27]
	v_mfma_f32_16x16x32_bf16 v[20:23], v[130:133], v[188:191], v[20:23]
	v_mfma_f32_16x16x32_bf16 v[16:19], v[212:215], v[188:191], v[16:19]
	v_mfma_f32_16x16x32_bf16 v[12:15], v[130:133], v[196:199], v[12:15]
	v_mfma_f32_16x16x32_bf16 v[8:11], v[212:215], v[196:199], v[8:11]
	v_mfma_f32_16x16x32_bf16 v[4:7], v[130:133], v[204:207], v[4:7]
	v_mfma_f32_16x16x32_bf16 v[0:3], v[212:215], v[204:207], v[0:3]
	v_mfma_f32_16x16x32_bf16 v[28:31], v[170:173], v[184:187], v[28:31]
	v_mfma_f32_16x16x32_bf16 v[24:27], v[166:169], v[184:187], v[24:27]
	v_mfma_f32_16x16x32_bf16 v[20:23], v[170:173], v[192:195], v[20:23]
	v_mfma_f32_16x16x32_bf16 v[16:19], v[166:169], v[192:195], v[16:19]
	v_mfma_f32_16x16x32_bf16 v[12:15], v[170:173], v[200:203], v[12:15]
	v_mfma_f32_16x16x32_bf16 v[8:11], v[166:169], v[200:203], v[8:11]
	v_mfma_f32_16x16x32_bf16 v[4:7], v[170:173], v[208:211], v[4:7]
	v_mfma_f32_16x16x32_bf16 v[0:3], v[166:169], v[208:211], v[0:3]
	s_barrier
	ds_read_b128 v[130:133], v161
	ds_read_b128 v[134:137], v161 offset:1024
	ds_read_b128 v[138:141], v161 offset:2048
	ds_read_b128 v[160:163], v161 offset:3072
	ds_read_b128 v[164:167], v152 offset:32768
	ds_read_b128 v[168:171], v152 offset:33792
	ds_read_b128 v[172:175], v151 offset:32768
	ds_read_b128 v[176:179], v151 offset:33792
	ds_read_b128 v[180:183], v150 offset:32768
	ds_read_b128 v[184:187], v150 offset:33792
	ds_read_b128 v[188:191], v149 offset:32768
	ds_read_b128 v[192:195], v149 offset:33792
	s_waitcnt vmcnt(2)
	s_barrier
	s_waitcnt lgkmcnt(0)
	s_waitcnt lgkmcnt(0)
	v_mfma_f32_16x16x32_bf16 v[124:127], v[130:133], v[164:167], v[124:127]
	v_mfma_f32_16x16x32_bf16 v[120:123], v[138:141], v[164:167], v[120:123]
	v_mfma_f32_16x16x32_bf16 v[116:119], v[130:133], v[172:175], v[116:119]
	v_mfma_f32_16x16x32_bf16 v[112:115], v[138:141], v[172:175], v[112:115]
	v_mfma_f32_16x16x32_bf16 v[108:111], v[130:133], v[180:183], v[108:111]
	v_mfma_f32_16x16x32_bf16 v[104:107], v[138:141], v[180:183], v[104:107]
	v_mfma_f32_16x16x32_bf16 v[100:103], v[130:133], v[188:191], v[100:103]
	v_mfma_f32_16x16x32_bf16 v[96:99], v[138:141], v[188:191], v[96:99]
	v_mfma_f32_16x16x32_bf16 v[124:127], v[134:137], v[168:171], v[124:127]
	v_mfma_f32_16x16x32_bf16 v[120:123], v[160:163], v[168:171], v[120:123]
	v_mfma_f32_16x16x32_bf16 v[116:119], v[134:137], v[176:179], v[116:119]
	v_mfma_f32_16x16x32_bf16 v[112:115], v[160:163], v[176:179], v[112:115]
	v_mfma_f32_16x16x32_bf16 v[108:111], v[134:137], v[184:187], v[108:111]
	v_mfma_f32_16x16x32_bf16 v[104:107], v[160:163], v[184:187], v[104:107]
	v_mfma_f32_16x16x32_bf16 v[100:103], v[134:137], v[192:195], v[100:103]
	v_mfma_f32_16x16x32_bf16 v[96:99], v[160:163], v[192:195], v[96:99]
	s_barrier
	ds_read_b128 v[196:199], v153
	ds_read_b128 v[200:203], v153 offset:1024
	ds_read_b128 v[204:207], v153 offset:2048
	ds_read_b128 v[208:211], v153 offset:3072
	s_waitcnt vmcnt(0)
	s_barrier
	s_waitcnt lgkmcnt(0)
	s_waitcnt lgkmcnt(0)
	v_mfma_f32_16x16x32_bf16 v[92:95], v[196:199], v[164:167], v[92:95]
	v_mfma_f32_16x16x32_bf16 v[88:91], v[204:207], v[164:167], v[88:91]
	v_mfma_f32_16x16x32_bf16 v[84:87], v[196:199], v[172:175], v[84:87]
	v_mfma_f32_16x16x32_bf16 v[80:83], v[204:207], v[172:175], v[80:83]
	v_mfma_f32_16x16x32_bf16 v[76:79], v[196:199], v[180:183], v[76:79]
	v_mfma_f32_16x16x32_bf16 v[72:75], v[204:207], v[180:183], v[72:75]
	v_mfma_f32_16x16x32_bf16 v[68:71], v[196:199], v[188:191], v[68:71]
	v_mfma_f32_16x16x32_bf16 v[64:67], v[204:207], v[188:191], v[64:67]
	v_mfma_f32_16x16x32_bf16 v[92:95], v[200:203], v[168:171], v[92:95]
	v_mfma_f32_16x16x32_bf16 v[88:91], v[208:211], v[168:171], v[88:91]
	v_mfma_f32_16x16x32_bf16 v[84:87], v[200:203], v[176:179], v[84:87]
	v_mfma_f32_16x16x32_bf16 v[80:83], v[208:211], v[176:179], v[80:83]
	v_mfma_f32_16x16x32_bf16 v[76:79], v[200:203], v[184:187], v[76:79]
	v_mfma_f32_16x16x32_bf16 v[72:75], v[208:211], v[184:187], v[72:75]
	v_mfma_f32_16x16x32_bf16 v[68:71], v[200:203], v[192:195], v[68:71]
	v_mfma_f32_16x16x32_bf16 v[64:67], v[208:211], v[192:195], v[64:67]
	s_barrier
	ds_read_b128 v[164:167], v152 offset:49152
	ds_read_b128 v[168:171], v152 offset:50176
	ds_read_b128 v[172:175], v151 offset:49152
	ds_read_b128 v[176:179], v151 offset:50176
	ds_read_b128 v[180:183], v150 offset:49152
	ds_read_b128 v[150:153], v150 offset:50176
	ds_read_b128 v[184:187], v149 offset:49152
	ds_read_b128 v[188:191], v149 offset:50176
	s_barrier
	s_waitcnt lgkmcnt(0)
	s_waitcnt lgkmcnt(0)
	v_mfma_f32_16x16x32_bf16 v[60:63], v[130:133], v[164:167], v[60:63]
	v_mfma_f32_16x16x32_bf16 v[56:59], v[138:141], v[164:167], v[56:59]
	v_mfma_f32_16x16x32_bf16 v[52:55], v[130:133], v[172:175], v[52:55]
	v_mfma_f32_16x16x32_bf16 v[48:51], v[138:141], v[172:175], v[48:51]
	v_mfma_f32_16x16x32_bf16 v[44:47], v[130:133], v[180:183], v[44:47]
	v_mfma_f32_16x16x32_bf16 v[40:43], v[138:141], v[180:183], v[40:43]
	v_mfma_f32_16x16x32_bf16 v[36:39], v[130:133], v[184:187], v[36:39]
	v_mfma_f32_16x16x32_bf16 v[32:35], v[138:141], v[184:187], v[32:35]
	v_mfma_f32_16x16x32_bf16 v[60:63], v[134:137], v[168:171], v[60:63]
	v_mfma_f32_16x16x32_bf16 v[56:59], v[160:163], v[168:171], v[56:59]
	v_mfma_f32_16x16x32_bf16 v[52:55], v[134:137], v[176:179], v[52:55]
	v_mfma_f32_16x16x32_bf16 v[48:51], v[160:163], v[176:179], v[48:51]
	v_mfma_f32_16x16x32_bf16 v[44:47], v[134:137], v[150:153], v[44:47]
	v_mfma_f32_16x16x32_bf16 v[40:43], v[160:163], v[150:153], v[40:43]
	v_mfma_f32_16x16x32_bf16 v[36:39], v[134:137], v[188:191], v[36:39]
	v_mfma_f32_16x16x32_bf16 v[32:35], v[160:163], v[188:191], v[32:35]
	v_mfma_f32_16x16x32_bf16 v[28:31], v[196:199], v[164:167], v[28:31]
	v_mfma_f32_16x16x32_bf16 v[24:27], v[204:207], v[164:167], v[24:27]
	v_mfma_f32_16x16x32_bf16 v[20:23], v[196:199], v[172:175], v[20:23]
	v_mfma_f32_16x16x32_bf16 v[16:19], v[204:207], v[172:175], v[16:19]
	v_mfma_f32_16x16x32_bf16 v[12:15], v[196:199], v[180:183], v[12:15]
	v_mfma_f32_16x16x32_bf16 v[8:11], v[204:207], v[180:183], v[8:11]
	v_mfma_f32_16x16x32_bf16 v[4:7], v[196:199], v[184:187], v[4:7]
	v_mfma_f32_16x16x32_bf16 v[0:3], v[204:207], v[184:187], v[0:3]
	v_mfma_f32_16x16x32_bf16 v[28:31], v[200:203], v[168:171], v[28:31]
	v_mfma_f32_16x16x32_bf16 v[24:27], v[208:211], v[168:171], v[24:27]
	v_mfma_f32_16x16x32_bf16 v[20:23], v[200:203], v[176:179], v[20:23]
	v_mfma_f32_16x16x32_bf16 v[16:19], v[208:211], v[176:179], v[16:19]
	v_mfma_f32_16x16x32_bf16 v[12:15], v[200:203], v[150:153], v[12:15]
	v_mfma_f32_16x16x32_bf16 v[8:11], v[208:211], v[150:153], v[8:11]
	v_mfma_f32_16x16x32_bf16 v[4:7], v[200:203], v[188:191], v[4:7]
	v_mfma_f32_16x16x32_bf16 v[0:3], v[208:211], v[188:191], v[0:3]
	v_cmp_gt_u32_e32 vcc, s52, v143
	s_barrier
	s_and_saveexec_b64 s[38:39], vcc
	s_cbranch_execz .LBB0_686
	s_barrier
	s_branch .LBB0_686

.LBB0_755:
	ds_read_b128 v[180:183], v177
	ds_read_b128 v[184:187], v177 offset:1024
	ds_read_b128 v[188:191], v177 offset:2048
	ds_read_b128 v[192:195], v177 offset:3072
	v_add_u32_e32 v178, 0xc000, v164
	v_lshl_add_u64 v[244:245], s[4:5], 0, v[146:147]
	v_readfirstlane_b32 s41, v178
	v_add_u32_e32 v179, 0xe000, v164
	v_lshl_add_u64 v[228:229], v[244:245], 0, s[12:13]
	s_mov_b32 m0, s41
	v_lshl_add_u64 v[246:247], s[4:5], 0, v[144:145]
	v_readfirstlane_b32 s41, v179
	ds_read_b128 v[196:199], v161
	ds_read_b128 v[200:203], v161 offset:1024
	ds_read_b128 v[204:207], v160
	ds_read_b128 v[208:211], v160 offset:1024
	ds_read_b128 v[212:215], v159
	ds_read_b128 v[216:219], v159 offset:1024
	ds_read_b128 v[220:223], v153
	ds_read_b128 v[224:227], v153 offset:1024
	global_load_lds_dwordx4 v[228:229], off
	v_lshl_add_u64 v[228:229], v[246:247], 0, s[12:13]
	s_mov_b32 m0, s41
	s_nop 0
	global_load_lds_dwordx4 v[228:229], off
	s_waitcnt lgkmcnt(8)
	s_barrier
	s_waitcnt lgkmcnt(0)
	s_waitcnt lgkmcnt(0)
	v_mfma_f32_16x16x32_bf16 v[124:127], v[180:183], v[196:199], v[124:127]
	v_mfma_f32_16x16x32_bf16 v[120:123], v[188:191], v[196:199], v[120:123]
	v_mfma_f32_16x16x32_bf16 v[116:119], v[180:183], v[204:207], v[116:119]
	v_mfma_f32_16x16x32_bf16 v[112:115], v[188:191], v[204:207], v[112:115]
	v_mfma_f32_16x16x32_bf16 v[108:111], v[180:183], v[212:215], v[108:111]
	v_mfma_f32_16x16x32_bf16 v[104:107], v[188:191], v[212:215], v[104:107]
	v_mfma_f32_16x16x32_bf16 v[100:103], v[180:183], v[220:223], v[100:103]
	v_mfma_f32_16x16x32_bf16 v[96:99], v[188:191], v[220:223], v[96:99]
	v_mfma_f32_16x16x32_bf16 v[124:127], v[184:187], v[200:203], v[124:127]
	v_mfma_f32_16x16x32_bf16 v[120:123], v[192:195], v[200:203], v[120:123]
	v_mfma_f32_16x16x32_bf16 v[116:119], v[184:187], v[208:211], v[116:119]
	v_mfma_f32_16x16x32_bf16 v[112:115], v[192:195], v[208:211], v[112:115]
	v_mfma_f32_16x16x32_bf16 v[108:111], v[184:187], v[216:219], v[108:111]
	v_mfma_f32_16x16x32_bf16 v[104:107], v[192:195], v[216:219], v[104:107]
	v_mfma_f32_16x16x32_bf16 v[100:103], v[184:187], v[224:227], v[100:103]
	v_mfma_f32_16x16x32_bf16 v[96:99], v[192:195], v[224:227], v[96:99]
	s_barrier
	v_lshl_add_u64 v[248:249], s[4:5], 0, v[142:143]
	v_readfirstlane_b32 s41, v162
	v_lshl_add_u64 v[250:251], v[248:249], 0, s[14:15]
	s_mov_b32 m0, s41
	v_add_u32_e32 v254, 0x2000, v162
	ds_read_b128 v[228:231], v173
	ds_read_b128 v[232:235], v173 offset:1024
	ds_read_b128 v[236:239], v173 offset:2048
	ds_read_b128 v[240:243], v173 offset:3072
	global_load_lds_dwordx4 v[250:251], off
	v_lshl_add_u64 v[250:251], s[4:5], 0, v[140:141]
	v_readfirstlane_b32 s41, v254
	v_lshl_add_u64 v[252:253], v[250:251], 0, s[14:15]
	s_mov_b32 m0, s41
	s_nop 0
	global_load_lds_dwordx4 v[252:253], off
	s_barrier
	s_waitcnt lgkmcnt(0)
	s_waitcnt lgkmcnt(0)
	v_mfma_f32_16x16x32_bf16 v[92:95], v[228:231], v[196:199], v[92:95]
	v_mfma_f32_16x16x32_bf16 v[88:91], v[236:239], v[196:199], v[88:91]
	v_mfma_f32_16x16x32_bf16 v[84:87], v[228:231], v[204:207], v[84:87]
	v_mfma_f32_16x16x32_bf16 v[80:83], v[236:239], v[204:207], v[80:83]
	v_mfma_f32_16x16x32_bf16 v[76:79], v[228:231], v[212:215], v[76:79]
	v_mfma_f32_16x16x32_bf16 v[72:75], v[236:239], v[212:215], v[72:75]
	v_mfma_f32_16x16x32_bf16 v[68:71], v[228:231], v[220:223], v[68:71]
	v_mfma_f32_16x16x32_bf16 v[64:67], v[236:239], v[220:223], v[64:67]
	v_mfma_f32_16x16x32_bf16 v[92:95], v[232:235], v[200:203], v[92:95]
	v_mfma_f32_16x16x32_bf16 v[88:91], v[240:243], v[200:203], v[88:91]
	v_mfma_f32_16x16x32_bf16 v[84:87], v[232:235], v[208:211], v[84:87]
	v_mfma_f32_16x16x32_bf16 v[80:83], v[240:243], v[208:211], v[80:83]
	v_mfma_f32_16x16x32_bf16 v[76:79], v[232:235], v[216:219], v[76:79]
	v_mfma_f32_16x16x32_bf16 v[72:75], v[240:243], v[216:219], v[72:75]
	v_mfma_f32_16x16x32_bf16 v[68:71], v[232:235], v[224:227], v[68:71]
	v_mfma_f32_16x16x32_bf16 v[64:67], v[240:243], v[224:227], v[64:67]
	v_readfirstlane_b32 s41, v164
	v_lshl_add_u64 v[252:253], v[244:245], 0, s[16:17]
	s_mov_b32 m0, s41
	v_readfirstlane_b32 s41, v165
	s_barrier
	ds_read_b128 v[196:199], v161 offset:16384
	ds_read_b128 v[200:203], v161 offset:17408
	ds_read_b128 v[204:207], v160 offset:16384
	ds_read_b128 v[208:211], v160 offset:17408
	ds_read_b128 v[212:215], v159 offset:16384
	ds_read_b128 v[216:219], v159 offset:17408
	ds_read_b128 v[220:223], v153 offset:16384
	ds_read_b128 v[224:227], v153 offset:17408
	global_load_lds_dwordx4 v[252:253], off
	v_lshl_add_u64 v[252:253], v[246:247], 0, s[16:17]
	s_mov_b32 m0, s41
	s_nop 0
	global_load_lds_dwordx4 v[252:253], off
	s_barrier
	s_waitcnt lgkmcnt(0)
	s_waitcnt lgkmcnt(0)
	v_mfma_f32_16x16x32_bf16 v[60:63], v[180:183], v[196:199], v[60:63]
	v_mfma_f32_16x16x32_bf16 v[56:59], v[188:191], v[196:199], v[56:59]
	v_mfma_f32_16x16x32_bf16 v[52:55], v[180:183], v[204:207], v[52:55]
	v_mfma_f32_16x16x32_bf16 v[48:51], v[188:191], v[204:207], v[48:51]
	v_mfma_f32_16x16x32_bf16 v[44:47], v[180:183], v[212:215], v[44:47]
	v_mfma_f32_16x16x32_bf16 v[40:43], v[188:191], v[212:215], v[40:43]
	v_mfma_f32_16x16x32_bf16 v[36:39], v[180:183], v[220:223], v[36:39]
	v_mfma_f32_16x16x32_bf16 v[32:35], v[188:191], v[220:223], v[32:35]
	v_mfma_f32_16x16x32_bf16 v[60:63], v[184:187], v[200:203], v[60:63]
	v_mfma_f32_16x16x32_bf16 v[56:59], v[192:195], v[200:203], v[56:59]
	v_mfma_f32_16x16x32_bf16 v[52:55], v[184:187], v[208:211], v[52:55]
	v_mfma_f32_16x16x32_bf16 v[48:51], v[192:195], v[208:211], v[48:51]
	v_mfma_f32_16x16x32_bf16 v[44:47], v[184:187], v[216:219], v[44:47]
	v_mfma_f32_16x16x32_bf16 v[40:43], v[192:195], v[216:219], v[40:43]
	v_mfma_f32_16x16x32_bf16 v[36:39], v[184:187], v[224:227], v[36:39]
	v_mfma_f32_16x16x32_bf16 v[32:35], v[192:195], v[224:227], v[32:35]
	s_barrier
	v_readfirstlane_b32 s41, v167
	v_add_u32_e32 v182, 0x2000, v167
	v_lshl_add_u64 v[180:181], v[248:249], 0, s[18:19]
	s_mov_b32 m0, s41
	v_readfirstlane_b32 s41, v182
	global_load_lds_dwordx4 v[180:181], off
	v_lshl_add_u64 v[180:181], v[250:251], 0, s[18:19]
	s_mov_b32 m0, s41
	s_nop 0
	global_load_lds_dwordx4 v[180:181], off
	s_waitcnt vmcnt(6)
	s_barrier
	v_mfma_f32_16x16x32_bf16 v[28:31], v[228:231], v[196:199], v[28:31]
	v_mfma_f32_16x16x32_bf16 v[24:27], v[236:239], v[196:199], v[24:27]
	v_mfma_f32_16x16x32_bf16 v[20:23], v[228:231], v[204:207], v[20:23]
	v_mfma_f32_16x16x32_bf16 v[16:19], v[236:239], v[204:207], v[16:19]
	v_mfma_f32_16x16x32_bf16 v[12:15], v[228:231], v[212:215], v[12:15]
	v_mfma_f32_16x16x32_bf16 v[8:11], v[236:239], v[212:215], v[8:11]
	v_mfma_f32_16x16x32_bf16 v[4:7], v[228:231], v[220:223], v[4:7]
	v_mfma_f32_16x16x32_bf16 v[0:3], v[236:239], v[220:223], v[0:3]
	v_mfma_f32_16x16x32_bf16 v[28:31], v[232:235], v[200:203], v[28:31]
	v_mfma_f32_16x16x32_bf16 v[24:27], v[240:243], v[200:203], v[24:27]
	v_mfma_f32_16x16x32_bf16 v[20:23], v[232:235], v[208:211], v[20:23]
	v_mfma_f32_16x16x32_bf16 v[16:19], v[240:243], v[208:211], v[16:19]
	v_mfma_f32_16x16x32_bf16 v[12:15], v[232:235], v[216:219], v[12:15]
	v_mfma_f32_16x16x32_bf16 v[8:11], v[240:243], v[216:219], v[8:11]
	v_mfma_f32_16x16x32_bf16 v[4:7], v[232:235], v[224:227], v[4:7]
	v_mfma_f32_16x16x32_bf16 v[0:3], v[240:243], v[224:227], v[0:3]
	s_barrier
	ds_read_b128 v[180:183], v166
	ds_read_b128 v[184:187], v166 offset:1024
	ds_read_b128 v[188:191], v166 offset:2048
	ds_read_b128 v[192:195], v166 offset:3072
	v_readfirstlane_b32 s41, v168
	v_lshl_add_u64 v[228:229], v[244:245], 0, s[20:21]
	s_mov_b32 m0, s41
	v_readfirstlane_b32 s41, v169
	ds_read_b128 v[196:199], v161 offset:32768
	ds_read_b128 v[200:203], v161 offset:33792
	ds_read_b128 v[204:207], v160 offset:32768
	ds_read_b128 v[208:211], v160 offset:33792
	ds_read_b128 v[212:215], v159 offset:32768
	ds_read_b128 v[216:219], v159 offset:33792
	ds_read_b128 v[220:223], v153 offset:32768
	ds_read_b128 v[224:227], v153 offset:33792
	global_load_lds_dwordx4 v[228:229], off
	v_lshl_add_u64 v[228:229], v[246:247], 0, s[20:21]
	s_mov_b32 m0, s41
	s_nop 0
	global_load_lds_dwordx4 v[228:229], off
	s_waitcnt lgkmcnt(8)
	s_barrier
	s_waitcnt lgkmcnt(0)
	s_waitcnt lgkmcnt(0)
	v_mfma_f32_16x16x32_bf16 v[124:127], v[180:183], v[196:199], v[124:127]
	v_mfma_f32_16x16x32_bf16 v[120:123], v[188:191], v[196:199], v[120:123]
	v_mfma_f32_16x16x32_bf16 v[116:119], v[180:183], v[204:207], v[116:119]
	v_mfma_f32_16x16x32_bf16 v[112:115], v[188:191], v[204:207], v[112:115]
	v_mfma_f32_16x16x32_bf16 v[108:111], v[180:183], v[212:215], v[108:111]
	v_mfma_f32_16x16x32_bf16 v[104:107], v[188:191], v[212:215], v[104:107]
	v_mfma_f32_16x16x32_bf16 v[100:103], v[180:183], v[220:223], v[100:103]
	v_mfma_f32_16x16x32_bf16 v[96:99], v[188:191], v[220:223], v[96:99]
	v_mfma_f32_16x16x32_bf16 v[124:127], v[184:187], v[200:203], v[124:127]
	v_mfma_f32_16x16x32_bf16 v[120:123], v[192:195], v[200:203], v[120:123]
	v_mfma_f32_16x16x32_bf16 v[116:119], v[184:187], v[208:211], v[116:119]
	v_mfma_f32_16x16x32_bf16 v[112:115], v[192:195], v[208:211], v[112:115]
	v_mfma_f32_16x16x32_bf16 v[108:111], v[184:187], v[216:219], v[108:111]
	v_mfma_f32_16x16x32_bf16 v[104:107], v[192:195], v[216:219], v[104:107]
	v_mfma_f32_16x16x32_bf16 v[100:103], v[184:187], v[224:227], v[100:103]
	v_mfma_f32_16x16x32_bf16 v[96:99], v[192:195], v[224:227], v[96:99]
	s_barrier
	v_readfirstlane_b32 s41, v170
	v_lshl_add_u64 v[252:253], v[248:249], 0, s[22:23]
	s_mov_b32 m0, s41
	v_readfirstlane_b32 s41, v171
	ds_read_b128 v[228:231], v163
	ds_read_b128 v[232:235], v163 offset:1024
	ds_read_b128 v[236:239], v163 offset:2048
	ds_read_b128 v[240:243], v163 offset:3072
	global_load_lds_dwordx4 v[252:253], off
	v_lshl_add_u64 v[252:253], v[250:251], 0, s[22:23]
	s_mov_b32 m0, s41
	s_nop 0
	global_load_lds_dwordx4 v[252:253], off
	s_barrier
	s_waitcnt lgkmcnt(0)
	s_waitcnt lgkmcnt(0)
	v_mfma_f32_16x16x32_bf16 v[92:95], v[228:231], v[196:199], v[92:95]
	v_mfma_f32_16x16x32_bf16 v[88:91], v[236:239], v[196:199], v[88:91]
	v_mfma_f32_16x16x32_bf16 v[84:87], v[228:231], v[204:207], v[84:87]
	v_mfma_f32_16x16x32_bf16 v[80:83], v[236:239], v[204:207], v[80:83]
	v_mfma_f32_16x16x32_bf16 v[76:79], v[228:231], v[212:215], v[76:79]
	v_mfma_f32_16x16x32_bf16 v[72:75], v[236:239], v[212:215], v[72:75]
	v_mfma_f32_16x16x32_bf16 v[68:71], v[228:231], v[220:223], v[68:71]
	v_mfma_f32_16x16x32_bf16 v[64:67], v[236:239], v[220:223], v[64:67]
	v_mfma_f32_16x16x32_bf16 v[92:95], v[232:235], v[200:203], v[92:95]
	v_mfma_f32_16x16x32_bf16 v[88:91], v[240:243], v[200:203], v[88:91]
	v_mfma_f32_16x16x32_bf16 v[84:87], v[232:235], v[208:211], v[84:87]
	v_mfma_f32_16x16x32_bf16 v[80:83], v[240:243], v[208:211], v[80:83]
	v_mfma_f32_16x16x32_bf16 v[76:79], v[232:235], v[216:219], v[76:79]
	v_mfma_f32_16x16x32_bf16 v[72:75], v[240:243], v[216:219], v[72:75]
	v_mfma_f32_16x16x32_bf16 v[68:71], v[232:235], v[224:227], v[68:71]
	v_mfma_f32_16x16x32_bf16 v[64:67], v[240:243], v[224:227], v[64:67]
	v_readfirstlane_b32 s41, v172
	v_lshl_add_u64 v[244:245], v[244:245], 0, s[24:25]
	s_mov_b32 m0, s41
	v_readfirstlane_b32 s41, v174
	s_barrier
	ds_read_b128 v[196:199], v161 offset:49152
	ds_read_b128 v[200:203], v161 offset:50176
	ds_read_b128 v[204:207], v160 offset:49152
	ds_read_b128 v[208:211], v160 offset:50176
	ds_read_b128 v[212:215], v159 offset:49152
	ds_read_b128 v[216:219], v159 offset:50176
	ds_read_b128 v[220:223], v153 offset:49152
	ds_read_b128 v[224:227], v153 offset:50176
	global_load_lds_dwordx4 v[244:245], off
	v_lshl_add_u64 v[244:245], v[246:247], 0, s[24:25]
	s_mov_b32 m0, s41
	s_nop 0
	global_load_lds_dwordx4 v[244:245], off
	s_barrier
	s_waitcnt lgkmcnt(0)
	s_waitcnt lgkmcnt(0)
	v_mfma_f32_16x16x32_bf16 v[60:63], v[180:183], v[196:199], v[60:63]
	v_mfma_f32_16x16x32_bf16 v[56:59], v[188:191], v[196:199], v[56:59]
	v_mfma_f32_16x16x32_bf16 v[52:55], v[180:183], v[204:207], v[52:55]
	v_mfma_f32_16x16x32_bf16 v[48:51], v[188:191], v[204:207], v[48:51]
	v_mfma_f32_16x16x32_bf16 v[44:47], v[180:183], v[212:215], v[44:47]
	v_mfma_f32_16x16x32_bf16 v[40:43], v[188:191], v[212:215], v[40:43]
	v_mfma_f32_16x16x32_bf16 v[36:39], v[180:183], v[220:223], v[36:39]
	v_mfma_f32_16x16x32_bf16 v[32:35], v[188:191], v[220:223], v[32:35]
	v_mfma_f32_16x16x32_bf16 v[60:63], v[184:187], v[200:203], v[60:63]
	v_mfma_f32_16x16x32_bf16 v[56:59], v[192:195], v[200:203], v[56:59]
	v_mfma_f32_16x16x32_bf16 v[52:55], v[184:187], v[208:211], v[52:55]
	v_mfma_f32_16x16x32_bf16 v[48:51], v[192:195], v[208:211], v[48:51]
	v_mfma_f32_16x16x32_bf16 v[44:47], v[184:187], v[216:219], v[44:47]
	v_mfma_f32_16x16x32_bf16 v[40:43], v[192:195], v[216:219], v[40:43]
	v_mfma_f32_16x16x32_bf16 v[36:39], v[184:187], v[224:227], v[36:39]
	v_mfma_f32_16x16x32_bf16 v[32:35], v[192:195], v[224:227], v[32:35]
	s_barrier
	v_readfirstlane_b32 s41, v175
	v_lshl_add_u64 v[180:181], v[248:249], 0, s[26:27]
	s_mov_b32 m0, s41
	v_readfirstlane_b32 s41, v176
	global_load_lds_dwordx4 v[180:181], off
	v_lshl_add_u64 v[180:181], v[250:251], 0, s[26:27]
	s_mov_b32 m0, s41
	s_nop 0
	global_load_lds_dwordx4 v[180:181], off
	s_waitcnt vmcnt(6)
	s_barrier
	v_mfma_f32_16x16x32_bf16 v[28:31], v[228:231], v[196:199], v[28:31]
	v_mfma_f32_16x16x32_bf16 v[24:27], v[236:239], v[196:199], v[24:27]
	v_mfma_f32_16x16x32_bf16 v[20:23], v[228:231], v[204:207], v[20:23]
	v_mfma_f32_16x16x32_bf16 v[16:19], v[236:239], v[204:207], v[16:19]
	v_mfma_f32_16x16x32_bf16 v[12:15], v[228:231], v[212:215], v[12:15]
	v_mfma_f32_16x16x32_bf16 v[8:11], v[236:239], v[212:215], v[8:11]
	v_mfma_f32_16x16x32_bf16 v[4:7], v[228:231], v[220:223], v[4:7]
	v_mfma_f32_16x16x32_bf16 v[0:3], v[236:239], v[220:223], v[0:3]
	v_mfma_f32_16x16x32_bf16 v[28:31], v[232:235], v[200:203], v[28:31]
	v_mfma_f32_16x16x32_bf16 v[24:27], v[240:243], v[200:203], v[24:27]
	v_mfma_f32_16x16x32_bf16 v[20:23], v[232:235], v[208:211], v[20:23]
	v_mfma_f32_16x16x32_bf16 v[16:19], v[240:243], v[208:211], v[16:19]
	v_mfma_f32_16x16x32_bf16 v[12:15], v[232:235], v[216:219], v[12:15]
	v_mfma_f32_16x16x32_bf16 v[8:11], v[240:243], v[216:219], v[8:11]
	v_mfma_f32_16x16x32_bf16 v[4:7], v[232:235], v[224:227], v[4:7]
	v_mfma_f32_16x16x32_bf16 v[0:3], v[240:243], v[224:227], v[0:3]
	s_add_i32 s40, s40, 2
	v_lshl_add_u64 v[140:141], v[140:141], 0, s[28:29]
	v_lshl_add_u64 v[142:143], v[142:143], 0, s[28:29]
	v_lshl_add_u64 v[144:145], v[144:145], 0, s[28:29]
	s_cmp_lt_u32 s40, 40
	v_lshl_add_u64 v[146:147], v[146:147], 0, s[28:29]
	s_barrier
	s_cbranch_scc1 .LBB0_755
	s_add_u32 s38, s38, 0x1580
	s_addc_u32 s39, s39, 0
	v_lshl_add_u64 v[134:135], v[134:135], 1, s[38:39]
	v_readfirstlane_b32 s40, v178
	v_lshl_add_u64 v[132:133], v[132:133], 1, v[134:135]
	s_mov_b32 m0, s40
	ds_read_b128 v[140:143], v177
	ds_read_b128 v[144:147], v177 offset:1024
	ds_read_b128 v[168:171], v177 offset:2048
	ds_read_b128 v[174:177], v177 offset:3072
	ds_read_b128 v[180:183], v161
	ds_read_b128 v[184:187], v161 offset:1024
	ds_read_b128 v[188:191], v160
	ds_read_b128 v[192:195], v160 offset:1024
	ds_read_b128 v[196:199], v159
	ds_read_b128 v[200:203], v159 offset:1024
	ds_read_b128 v[204:207], v153
	ds_read_b128 v[208:211], v153 offset:1024
	global_load_lds_dwordx4 v[132:133], off
	v_lshl_add_u64 v[132:133], v[138:139], 1, s[38:39]
	v_readfirstlane_b32 s38, v179
	v_lshl_add_u64 v[132:133], v[136:137], 1, v[132:133]
	s_mov_b32 m0, s38
	s_nop 0
	global_load_lds_dwordx4 v[132:133], off
	s_barrier
	s_waitcnt lgkmcnt(0)
	s_waitcnt lgkmcnt(0)
	v_mfma_f32_16x16x32_bf16 v[124:127], v[140:143], v[180:183], v[124:127]
	v_mfma_f32_16x16x32_bf16 v[120:123], v[168:171], v[180:183], v[120:123]
	v_mfma_f32_16x16x32_bf16 v[116:119], v[140:143], v[188:191], v[116:119]
	v_mfma_f32_16x16x32_bf16 v[108:111], v[140:143], v[196:199], v[108:111]
	v_mfma_f32_16x16x32_bf16 v[100:103], v[140:143], v[204:207], v[100:103]
	v_mfma_f32_16x16x32_bf16 v[124:127], v[144:147], v[184:187], v[124:127]
	v_mfma_f32_16x16x32_bf16 v[120:123], v[174:177], v[184:187], v[120:123]
	v_mfma_f32_16x16x32_bf16 v[116:119], v[144:147], v[192:195], v[116:119]
	v_mfma_f32_16x16x32_bf16 v[112:115], v[168:171], v[188:191], v[112:115]
	v_mfma_f32_16x16x32_bf16 v[108:111], v[144:147], v[200:203], v[108:111]
	v_mfma_f32_16x16x32_bf16 v[104:107], v[168:171], v[196:199], v[104:107]
	v_mfma_f32_16x16x32_bf16 v[100:103], v[144:147], v[208:211], v[100:103]
	v_mfma_f32_16x16x32_bf16 v[96:99], v[168:171], v[204:207], v[96:99]
	v_mfma_f32_16x16x32_bf16 v[132:135], v[174:177], v[192:195], v[112:115]
	v_mfma_f32_16x16x32_bf16 v[136:139], v[174:177], v[200:203], v[104:107]
	v_mfma_f32_16x16x32_bf16 v[212:215], v[174:177], v[208:211], v[96:99]
	s_barrier
	s_nop 2
	ds_read_b128 v[96:99], v173
	ds_read_b128 v[104:107], v173 offset:1024
	ds_read_b128 v[112:115], v173 offset:2048
	ds_read_b128 v[216:219], v173 offset:3072
	s_barrier
	s_waitcnt lgkmcnt(0)
	s_waitcnt lgkmcnt(0)
	v_mfma_f32_16x16x32_bf16 v[92:95], v[96:99], v[180:183], v[92:95]
	v_mfma_f32_16x16x32_bf16 v[88:91], v[112:115], v[180:183], v[88:91]
	v_mfma_f32_16x16x32_bf16 v[84:87], v[96:99], v[188:191], v[84:87]
	v_mfma_f32_16x16x32_bf16 v[76:79], v[96:99], v[196:199], v[76:79]
	v_mfma_f32_16x16x32_bf16 v[68:71], v[96:99], v[204:207], v[68:71]
	v_mfma_f32_16x16x32_bf16 v[92:95], v[104:107], v[184:187], v[92:95]
	v_mfma_f32_16x16x32_bf16 v[88:91], v[216:219], v[184:187], v[88:91]
	v_mfma_f32_16x16x32_bf16 v[84:87], v[104:107], v[192:195], v[84:87]
	v_mfma_f32_16x16x32_bf16 v[80:83], v[112:115], v[188:191], v[80:83]
	v_mfma_f32_16x16x32_bf16 v[76:79], v[104:107], v[200:203], v[76:79]
	v_mfma_f32_16x16x32_bf16 v[72:75], v[112:115], v[196:199], v[72:75]
	v_mfma_f32_16x16x32_bf16 v[68:71], v[104:107], v[208:211], v[68:71]
	v_mfma_f32_16x16x32_bf16 v[64:67], v[112:115], v[204:207], v[64:67]
	v_mfma_f32_16x16x32_bf16 v[178:181], v[216:219], v[192:195], v[80:83]
	v_mfma_f32_16x16x32_bf16 v[182:185], v[216:219], v[200:203], v[72:75]
	v_mfma_f32_16x16x32_bf16 v[186:189], v[216:219], v[208:211], v[64:67]
	s_barrier
	s_nop 2
	ds_read_b128 v[64:67], v161 offset:16384
	ds_read_b128 v[72:75], v161 offset:17408
	ds_read_b128 v[80:83], v160 offset:16384
	ds_read_b128 v[190:193], v160 offset:17408
	ds_read_b128 v[194:197], v159 offset:16384
	ds_read_b128 v[198:201], v159 offset:17408
	ds_read_b128 v[202:205], v153 offset:16384
	ds_read_b128 v[206:209], v153 offset:17408
	s_waitcnt vmcnt(4)
	s_barrier
	s_waitcnt lgkmcnt(0)
	s_waitcnt lgkmcnt(0)
	v_mfma_f32_16x16x32_bf16 v[60:63], v[140:143], v[64:67], v[60:63]
	v_mfma_f32_16x16x32_bf16 v[56:59], v[168:171], v[64:67], v[56:59]
	v_mfma_f32_16x16x32_bf16 v[52:55], v[140:143], v[80:83], v[52:55]
	v_mfma_f32_16x16x32_bf16 v[44:47], v[140:143], v[194:197], v[44:47]
	v_mfma_f32_16x16x32_bf16 v[36:39], v[140:143], v[202:205], v[36:39]
	v_mfma_f32_16x16x32_bf16 v[60:63], v[144:147], v[72:75], v[60:63]
	v_mfma_f32_16x16x32_bf16 v[56:59], v[174:177], v[72:75], v[56:59]
	v_mfma_f32_16x16x32_bf16 v[52:55], v[144:147], v[190:193], v[52:55]
	v_mfma_f32_16x16x32_bf16 v[48:51], v[168:171], v[80:83], v[48:51]
	v_mfma_f32_16x16x32_bf16 v[44:47], v[144:147], v[198:201], v[44:47]
	v_mfma_f32_16x16x32_bf16 v[40:43], v[168:171], v[194:197], v[40:43]
	v_mfma_f32_16x16x32_bf16 v[36:39], v[144:147], v[206:209], v[36:39]
	v_mfma_f32_16x16x32_bf16 v[32:35], v[168:171], v[202:205], v[32:35]
	v_mfma_f32_16x16x32_bf16 v[220:223], v[174:177], v[190:193], v[48:51]
	v_mfma_f32_16x16x32_bf16 v[224:227], v[174:177], v[198:201], v[40:43]
	v_mfma_f32_16x16x32_bf16 v[140:143], v[174:177], v[206:209], v[32:35]
	v_mfma_f32_16x16x32_bf16 v[28:31], v[96:99], v[64:67], v[28:31]
	v_mfma_f32_16x16x32_bf16 v[24:27], v[112:115], v[64:67], v[24:27]
	v_mfma_f32_16x16x32_bf16 v[20:23], v[96:99], v[80:83], v[20:23]
	v_mfma_f32_16x16x32_bf16 v[12:15], v[96:99], v[194:197], v[12:15]
	v_mfma_f32_16x16x32_bf16 v[4:7], v[96:99], v[202:205], v[4:7]
	v_mfma_f32_16x16x32_bf16 v[28:31], v[104:107], v[72:75], v[28:31]
	v_mfma_f32_16x16x32_bf16 v[24:27], v[216:219], v[72:75], v[24:27]
	v_mfma_f32_16x16x32_bf16 v[20:23], v[104:107], v[190:193], v[20:23]
	v_mfma_f32_16x16x32_bf16 v[16:19], v[112:115], v[80:83], v[16:19]
	v_mfma_f32_16x16x32_bf16 v[12:15], v[104:107], v[198:201], v[12:15]
	v_mfma_f32_16x16x32_bf16 v[8:11], v[112:115], v[194:197], v[8:11]
	v_mfma_f32_16x16x32_bf16 v[4:7], v[104:107], v[206:209], v[4:7]
	v_mfma_f32_16x16x32_bf16 v[0:3], v[112:115], v[202:205], v[0:3]
	v_mfma_f32_16x16x32_bf16 v[144:147], v[216:219], v[190:193], v[16:19]
	v_mfma_f32_16x16x32_bf16 v[168:171], v[216:219], v[198:201], v[8:11]
	v_mfma_f32_16x16x32_bf16 v[172:175], v[216:219], v[206:209], v[0:3]
	s_barrier
	s_nop 2
	ds_read_b128 v[0:3], v166
	ds_read_b128 v[8:11], v166 offset:1024
	ds_read_b128 v[16:19], v166 offset:2048
	ds_read_b128 v[164:167], v166 offset:3072
	ds_read_b128 v[32:35], v161 offset:32768
	ds_read_b128 v[40:43], v161 offset:33792
	ds_read_b128 v[48:51], v160 offset:32768
	ds_read_b128 v[64:67], v160 offset:33792
	ds_read_b128 v[190:193], v159 offset:32768
	ds_read_b128 v[194:197], v159 offset:33792
	ds_read_b128 v[198:201], v153 offset:32768
	ds_read_b128 v[202:205], v153 offset:33792
	s_waitcnt vmcnt(2)
	s_barrier
	s_waitcnt lgkmcnt(0)
	s_waitcnt lgkmcnt(0)
	v_mfma_f32_16x16x32_bf16 v[72:75], v[0:3], v[32:35], v[124:127]
	v_mfma_f32_16x16x32_bf16 v[124:127], v[8:11], v[40:43], v[72:75]
	v_mfma_f32_16x16x32_bf16 v[72:75], v[16:19], v[32:35], v[120:123]
	v_mfma_f32_16x16x32_bf16 v[120:123], v[164:167], v[40:43], v[72:75]
	v_mfma_f32_16x16x32_bf16 v[72:75], v[0:3], v[48:51], v[116:119]
	v_mfma_f32_16x16x32_bf16 v[112:115], v[8:11], v[64:67], v[72:75]
	v_mfma_f32_16x16x32_bf16 v[72:75], v[16:19], v[48:51], v[132:135]
	v_mfma_f32_16x16x32_bf16 v[116:119], v[164:167], v[64:67], v[72:75]
	v_mfma_f32_16x16x32_bf16 v[72:75], v[0:3], v[190:193], v[108:111]
	v_mfma_f32_16x16x32_bf16 v[104:107], v[8:11], v[194:197], v[72:75]
	v_mfma_f32_16x16x32_bf16 v[72:75], v[16:19], v[190:193], v[136:139]
	v_mfma_f32_16x16x32_bf16 v[108:111], v[164:167], v[194:197], v[72:75]
	v_mfma_f32_16x16x32_bf16 v[72:75], v[0:3], v[198:201], v[100:103]
	v_mfma_f32_16x16x32_bf16 v[96:99], v[8:11], v[202:205], v[72:75]
	v_mfma_f32_16x16x32_bf16 v[72:75], v[16:19], v[198:201], v[212:215]
	v_mfma_f32_16x16x32_bf16 v[100:103], v[164:167], v[202:205], v[72:75]
	s_barrier
	ds_read_b128 v[132:135], v163
	ds_read_b128 v[136:139], v163 offset:1024
	ds_read_b128 v[206:209], v163 offset:2048
	ds_read_b128 v[210:213], v163 offset:3072
	s_waitcnt vmcnt(0)
	s_barrier
	s_waitcnt lgkmcnt(0)
	s_waitcnt lgkmcnt(0)
	v_mfma_f32_16x16x32_bf16 v[72:75], v[132:135], v[32:35], v[92:95]
	v_mfma_f32_16x16x32_bf16 v[32:35], v[206:209], v[32:35], v[88:91]
	v_mfma_f32_16x16x32_bf16 v[88:91], v[210:213], v[40:43], v[32:35]
	v_mfma_f32_16x16x32_bf16 v[32:35], v[132:135], v[48:51], v[84:87]
	v_mfma_f32_16x16x32_bf16 v[80:83], v[136:139], v[64:67], v[32:35]
	v_mfma_f32_16x16x32_bf16 v[32:35], v[206:209], v[48:51], v[178:181]
	v_mfma_f32_16x16x32_bf16 v[84:87], v[210:213], v[64:67], v[32:35]
	v_mfma_f32_16x16x32_bf16 v[32:35], v[132:135], v[190:193], v[76:79]
	v_mfma_f32_16x16x32_bf16 v[92:95], v[136:139], v[40:43], v[72:75]
	v_mfma_f32_16x16x32_bf16 v[72:75], v[136:139], v[194:197], v[32:35]
	v_mfma_f32_16x16x32_bf16 v[32:35], v[206:209], v[190:193], v[182:185]
	v_mfma_f32_16x16x32_bf16 v[76:79], v[210:213], v[194:197], v[32:35]
	v_mfma_f32_16x16x32_bf16 v[32:35], v[132:135], v[198:201], v[68:71]
	v_mfma_f32_16x16x32_bf16 v[64:67], v[136:139], v[202:205], v[32:35]
	v_mfma_f32_16x16x32_bf16 v[32:35], v[206:209], v[198:201], v[186:189]
	v_mfma_f32_16x16x32_bf16 v[68:71], v[210:213], v[202:205], v[32:35]
	s_barrier
	ds_read_b128 v[176:179], v161 offset:49152
	ds_read_b128 v[180:183], v161 offset:50176
	ds_read_b128 v[184:187], v160 offset:49152
	ds_read_b128 v[160:163], v160 offset:50176
	ds_read_b128 v[188:191], v159 offset:49152
	ds_read_b128 v[192:195], v159 offset:50176
	ds_read_b128 v[196:199], v153 offset:49152
	ds_read_b128 v[200:203], v153 offset:50176
	s_barrier
	s_waitcnt lgkmcnt(0)
	s_waitcnt lgkmcnt(0)
	v_mfma_f32_16x16x32_bf16 v[32:35], v[0:3], v[176:179], v[60:63]
	v_mfma_f32_16x16x32_bf16 v[60:63], v[8:11], v[180:183], v[32:35]
	v_mfma_f32_16x16x32_bf16 v[32:35], v[16:19], v[176:179], v[56:59]
	v_mfma_f32_16x16x32_bf16 v[56:59], v[164:167], v[180:183], v[32:35]
	v_mfma_f32_16x16x32_bf16 v[32:35], v[0:3], v[184:187], v[52:55]
	v_mfma_f32_16x16x32_bf16 v[48:51], v[8:11], v[160:163], v[32:35]
	v_mfma_f32_16x16x32_bf16 v[32:35], v[16:19], v[184:187], v[220:223]
	v_mfma_f32_16x16x32_bf16 v[52:55], v[164:167], v[160:163], v[32:35]
	v_mfma_f32_16x16x32_bf16 v[32:35], v[0:3], v[188:191], v[44:47]
	v_mfma_f32_16x16x32_bf16 v[40:43], v[8:11], v[192:195], v[32:35]
	v_mfma_f32_16x16x32_bf16 v[32:35], v[16:19], v[188:191], v[224:227]
	v_mfma_f32_16x16x32_bf16 v[0:3], v[0:3], v[196:199], v[36:39]
	v_mfma_f32_16x16x32_bf16 v[44:47], v[164:167], v[192:195], v[32:35]
	v_mfma_f32_16x16x32_bf16 v[32:35], v[8:11], v[200:203], v[0:3]
	v_mfma_f32_16x16x32_bf16 v[0:3], v[16:19], v[196:199], v[140:143]
	v_mfma_f32_16x16x32_bf16 v[36:39], v[164:167], v[200:203], v[0:3]
	v_mfma_f32_16x16x32_bf16 v[0:3], v[132:135], v[176:179], v[28:31]
	v_mfma_f32_16x16x32_bf16 v[28:31], v[136:139], v[180:183], v[0:3]
	v_mfma_f32_16x16x32_bf16 v[0:3], v[206:209], v[176:179], v[24:27]
	v_mfma_f32_16x16x32_bf16 v[24:27], v[210:213], v[180:183], v[0:3]
	v_mfma_f32_16x16x32_bf16 v[0:3], v[132:135], v[184:187], v[20:23]
	v_mfma_f32_16x16x32_bf16 v[16:19], v[136:139], v[160:163], v[0:3]
	v_mfma_f32_16x16x32_bf16 v[0:3], v[206:209], v[184:187], v[144:147]
	v_mfma_f32_16x16x32_bf16 v[20:23], v[210:213], v[160:163], v[0:3]
	v_mfma_f32_16x16x32_bf16 v[0:3], v[132:135], v[188:191], v[12:15]
	v_mfma_f32_16x16x32_bf16 v[8:11], v[136:139], v[192:195], v[0:3]
	v_mfma_f32_16x16x32_bf16 v[0:3], v[206:209], v[188:191], v[168:171]
	v_mfma_f32_16x16x32_bf16 v[12:15], v[210:213], v[192:195], v[0:3]
	v_mfma_f32_16x16x32_bf16 v[0:3], v[132:135], v[196:199], v[4:7]
	v_mfma_f32_16x16x32_bf16 v[4:7], v[206:209], v[196:199], v[172:175]
	v_mfma_f32_16x16x32_bf16 v[0:3], v[136:139], v[200:203], v[0:3]
	v_mfma_f32_16x16x32_bf16 v[4:7], v[210:213], v[200:203], v[4:7]
	v_cmp_gt_u32_e32 vcc, s55, v130
	s_barrier
	s_and_saveexec_b64 s[38:39], vcc
	s_cbranch_execz .LBB0_749
	s_barrier
	s_branch .LBB0_749

.LBB0_886:
	ds_read_b128 v[176:179], v173
	ds_read_b128 v[180:183], v173 offset:1024
	ds_read_b128 v[184:187], v173 offset:2048
	ds_read_b128 v[188:191], v173 offset:3072
	v_add_u32_e32 v174, 0xc000, v153
	v_lshl_add_u64 v[240:241], s[38:39], 0, v[138:139]
	v_readfirstlane_b32 s6, v174
	v_add_u32_e32 v175, 0xe000, v153
	v_lshl_add_u64 v[224:225], v[240:241], 0, s[78:79]
	s_mov_b32 m0, s6
	v_lshl_add_u64 v[242:243], s[38:39], 0, v[136:137]
	v_readfirstlane_b32 s6, v175
	ds_read_b128 v[192:195], v151
	ds_read_b128 v[196:199], v151 offset:1024
	ds_read_b128 v[200:203], v150
	ds_read_b128 v[204:207], v150 offset:1024
	ds_read_b128 v[208:211], v149
	ds_read_b128 v[212:215], v149 offset:1024
	ds_read_b128 v[216:219], v148
	ds_read_b128 v[220:223], v148 offset:1024
	global_load_lds_dwordx4 v[224:225], off
	v_lshl_add_u64 v[224:225], v[242:243], 0, s[78:79]
	s_mov_b32 m0, s6
	s_nop 0
	global_load_lds_dwordx4 v[224:225], off
	s_waitcnt lgkmcnt(8)
	s_barrier
	s_waitcnt lgkmcnt(0)
	s_waitcnt lgkmcnt(0)
	v_mfma_f32_16x16x32_bf16 v[124:127], v[176:179], v[192:195], v[124:127]
	v_mfma_f32_16x16x32_bf16 v[120:123], v[184:187], v[192:195], v[120:123]
	v_mfma_f32_16x16x32_bf16 v[116:119], v[176:179], v[200:203], v[116:119]
	v_mfma_f32_16x16x32_bf16 v[112:115], v[184:187], v[200:203], v[112:115]
	v_mfma_f32_16x16x32_bf16 v[108:111], v[176:179], v[208:211], v[108:111]
	v_mfma_f32_16x16x32_bf16 v[104:107], v[184:187], v[208:211], v[104:107]
	v_mfma_f32_16x16x32_bf16 v[100:103], v[176:179], v[216:219], v[100:103]
	v_mfma_f32_16x16x32_bf16 v[96:99], v[184:187], v[216:219], v[96:99]
	v_mfma_f32_16x16x32_bf16 v[124:127], v[180:183], v[196:199], v[124:127]
	v_mfma_f32_16x16x32_bf16 v[120:123], v[188:191], v[196:199], v[120:123]
	v_mfma_f32_16x16x32_bf16 v[116:119], v[180:183], v[204:207], v[116:119]
	v_mfma_f32_16x16x32_bf16 v[112:115], v[188:191], v[204:207], v[112:115]
	v_mfma_f32_16x16x32_bf16 v[108:111], v[180:183], v[212:215], v[108:111]
	v_mfma_f32_16x16x32_bf16 v[104:107], v[188:191], v[212:215], v[104:107]
	v_mfma_f32_16x16x32_bf16 v[100:103], v[180:183], v[220:223], v[100:103]
	v_mfma_f32_16x16x32_bf16 v[96:99], v[188:191], v[220:223], v[96:99]
	s_barrier
	v_lshl_add_u64 v[244:245], s[38:39], 0, v[142:143]
	v_readfirstlane_b32 s6, v147
	v_lshl_add_u64 v[246:247], v[244:245], 0, s[80:81]
	s_mov_b32 m0, s6
	v_add_u32_e32 v250, 0x2000, v147
	ds_read_b128 v[224:227], v170
	ds_read_b128 v[228:231], v170 offset:1024
	ds_read_b128 v[232:235], v170 offset:2048
	ds_read_b128 v[236:239], v170 offset:3072
	global_load_lds_dwordx4 v[246:247], off
	v_lshl_add_u64 v[246:247], s[38:39], 0, v[140:141]
	v_readfirstlane_b32 s6, v250
	v_lshl_add_u64 v[248:249], v[246:247], 0, s[80:81]
	s_mov_b32 m0, s6
	s_nop 0
	global_load_lds_dwordx4 v[248:249], off
	s_barrier
	s_waitcnt lgkmcnt(0)
	s_waitcnt lgkmcnt(0)
	v_mfma_f32_16x16x32_bf16 v[92:95], v[224:227], v[192:195], v[92:95]
	v_mfma_f32_16x16x32_bf16 v[88:91], v[232:235], v[192:195], v[88:91]
	v_mfma_f32_16x16x32_bf16 v[84:87], v[224:227], v[200:203], v[84:87]
	v_mfma_f32_16x16x32_bf16 v[80:83], v[232:235], v[200:203], v[80:83]
	v_mfma_f32_16x16x32_bf16 v[76:79], v[224:227], v[208:211], v[76:79]
	v_mfma_f32_16x16x32_bf16 v[72:75], v[232:235], v[208:211], v[72:75]
	v_mfma_f32_16x16x32_bf16 v[68:71], v[224:227], v[216:219], v[68:71]
	v_mfma_f32_16x16x32_bf16 v[64:67], v[232:235], v[216:219], v[64:67]
	v_mfma_f32_16x16x32_bf16 v[92:95], v[228:231], v[196:199], v[92:95]
	v_mfma_f32_16x16x32_bf16 v[88:91], v[236:239], v[196:199], v[88:91]
	v_mfma_f32_16x16x32_bf16 v[84:87], v[228:231], v[204:207], v[84:87]
	v_mfma_f32_16x16x32_bf16 v[80:83], v[236:239], v[204:207], v[80:83]
	v_mfma_f32_16x16x32_bf16 v[76:79], v[228:231], v[212:215], v[76:79]
	v_mfma_f32_16x16x32_bf16 v[72:75], v[236:239], v[212:215], v[72:75]
	v_mfma_f32_16x16x32_bf16 v[68:71], v[228:231], v[220:223], v[68:71]
	v_mfma_f32_16x16x32_bf16 v[64:67], v[236:239], v[220:223], v[64:67]
	v_readfirstlane_b32 s6, v153
	v_lshl_add_u64 v[248:249], v[240:241], 0, s[82:83]
	s_mov_b32 m0, s6
	v_readfirstlane_b32 s6, v160
	s_barrier
	ds_read_b128 v[192:195], v151 offset:16384
	ds_read_b128 v[196:199], v151 offset:17408
	ds_read_b128 v[200:203], v150 offset:16384
	ds_read_b128 v[204:207], v150 offset:17408
	ds_read_b128 v[208:211], v149 offset:16384
	ds_read_b128 v[212:215], v149 offset:17408
	ds_read_b128 v[216:219], v148 offset:16384
	ds_read_b128 v[220:223], v148 offset:17408
	global_load_lds_dwordx4 v[248:249], off
	v_lshl_add_u64 v[248:249], v[242:243], 0, s[82:83]
	s_mov_b32 m0, s6
	s_nop 0
	global_load_lds_dwordx4 v[248:249], off
	s_barrier
	s_waitcnt lgkmcnt(0)
	s_waitcnt lgkmcnt(0)
	v_mfma_f32_16x16x32_bf16 v[60:63], v[176:179], v[192:195], v[60:63]
	v_mfma_f32_16x16x32_bf16 v[56:59], v[184:187], v[192:195], v[56:59]
	v_mfma_f32_16x16x32_bf16 v[52:55], v[176:179], v[200:203], v[52:55]
	v_mfma_f32_16x16x32_bf16 v[48:51], v[184:187], v[200:203], v[48:51]
	v_mfma_f32_16x16x32_bf16 v[44:47], v[176:179], v[208:211], v[44:47]
	v_mfma_f32_16x16x32_bf16 v[40:43], v[184:187], v[208:211], v[40:43]
	v_mfma_f32_16x16x32_bf16 v[36:39], v[176:179], v[216:219], v[36:39]
	v_mfma_f32_16x16x32_bf16 v[32:35], v[184:187], v[216:219], v[32:35]
	v_mfma_f32_16x16x32_bf16 v[60:63], v[180:183], v[196:199], v[60:63]
	v_mfma_f32_16x16x32_bf16 v[56:59], v[188:191], v[196:199], v[56:59]
	v_mfma_f32_16x16x32_bf16 v[52:55], v[180:183], v[204:207], v[52:55]
	v_mfma_f32_16x16x32_bf16 v[48:51], v[188:191], v[204:207], v[48:51]
	v_mfma_f32_16x16x32_bf16 v[44:47], v[180:183], v[212:215], v[44:47]
	v_mfma_f32_16x16x32_bf16 v[40:43], v[188:191], v[212:215], v[40:43]
	v_mfma_f32_16x16x32_bf16 v[36:39], v[180:183], v[220:223], v[36:39]
	v_mfma_f32_16x16x32_bf16 v[32:35], v[188:191], v[220:223], v[32:35]
	s_barrier
	v_readfirstlane_b32 s6, v162
	v_add_u32_e32 v178, 0x2000, v162
	v_lshl_add_u64 v[176:177], v[244:245], 0, s[90:91]
	s_mov_b32 m0, s6
	v_readfirstlane_b32 s6, v178
	global_load_lds_dwordx4 v[176:177], off
	v_lshl_add_u64 v[176:177], v[246:247], 0, s[90:91]
	s_mov_b32 m0, s6
	s_nop 0
	global_load_lds_dwordx4 v[176:177], off
	s_waitcnt vmcnt(6)
	s_barrier
	v_mfma_f32_16x16x32_bf16 v[28:31], v[224:227], v[192:195], v[28:31]
	v_mfma_f32_16x16x32_bf16 v[24:27], v[232:235], v[192:195], v[24:27]
	v_mfma_f32_16x16x32_bf16 v[20:23], v[224:227], v[200:203], v[20:23]
	v_mfma_f32_16x16x32_bf16 v[16:19], v[232:235], v[200:203], v[16:19]
	v_mfma_f32_16x16x32_bf16 v[12:15], v[224:227], v[208:211], v[12:15]
	v_mfma_f32_16x16x32_bf16 v[8:11], v[232:235], v[208:211], v[8:11]
	v_mfma_f32_16x16x32_bf16 v[4:7], v[224:227], v[216:219], v[4:7]
	v_mfma_f32_16x16x32_bf16 v[0:3], v[232:235], v[216:219], v[0:3]
	v_mfma_f32_16x16x32_bf16 v[28:31], v[228:231], v[196:199], v[28:31]
	v_mfma_f32_16x16x32_bf16 v[24:27], v[236:239], v[196:199], v[24:27]
	v_mfma_f32_16x16x32_bf16 v[20:23], v[228:231], v[204:207], v[20:23]
	v_mfma_f32_16x16x32_bf16 v[16:19], v[236:239], v[204:207], v[16:19]
	v_mfma_f32_16x16x32_bf16 v[12:15], v[228:231], v[212:215], v[12:15]
	v_mfma_f32_16x16x32_bf16 v[8:11], v[236:239], v[212:215], v[8:11]
	v_mfma_f32_16x16x32_bf16 v[4:7], v[228:231], v[220:223], v[4:7]
	v_mfma_f32_16x16x32_bf16 v[0:3], v[236:239], v[220:223], v[0:3]
	s_barrier
	ds_read_b128 v[176:179], v161
	ds_read_b128 v[180:183], v161 offset:1024
	ds_read_b128 v[184:187], v161 offset:2048
	ds_read_b128 v[188:191], v161 offset:3072
	v_readfirstlane_b32 s6, v164
	v_lshl_add_u64 v[224:225], v[240:241], 0, s[92:93]
	s_mov_b32 m0, s6
	v_readfirstlane_b32 s6, v165
	ds_read_b128 v[192:195], v151 offset:32768
	ds_read_b128 v[196:199], v151 offset:33792
	ds_read_b128 v[200:203], v150 offset:32768
	ds_read_b128 v[204:207], v150 offset:33792
	ds_read_b128 v[208:211], v149 offset:32768
	ds_read_b128 v[212:215], v149 offset:33792
	ds_read_b128 v[216:219], v148 offset:32768
	ds_read_b128 v[220:223], v148 offset:33792
	global_load_lds_dwordx4 v[224:225], off
	v_lshl_add_u64 v[224:225], v[242:243], 0, s[92:93]
	s_mov_b32 m0, s6
	s_nop 0
	global_load_lds_dwordx4 v[224:225], off
	s_waitcnt lgkmcnt(8)
	s_barrier
	s_waitcnt lgkmcnt(0)
	s_waitcnt lgkmcnt(0)
	v_mfma_f32_16x16x32_bf16 v[124:127], v[176:179], v[192:195], v[124:127]
	v_mfma_f32_16x16x32_bf16 v[120:123], v[184:187], v[192:195], v[120:123]
	v_mfma_f32_16x16x32_bf16 v[116:119], v[176:179], v[200:203], v[116:119]
	v_mfma_f32_16x16x32_bf16 v[112:115], v[184:187], v[200:203], v[112:115]
	v_mfma_f32_16x16x32_bf16 v[108:111], v[176:179], v[208:211], v[108:111]
	v_mfma_f32_16x16x32_bf16 v[104:107], v[184:187], v[208:211], v[104:107]
	v_mfma_f32_16x16x32_bf16 v[100:103], v[176:179], v[216:219], v[100:103]
	v_mfma_f32_16x16x32_bf16 v[96:99], v[184:187], v[216:219], v[96:99]
	v_mfma_f32_16x16x32_bf16 v[124:127], v[180:183], v[196:199], v[124:127]
	v_mfma_f32_16x16x32_bf16 v[120:123], v[188:191], v[196:199], v[120:123]
	v_mfma_f32_16x16x32_bf16 v[116:119], v[180:183], v[204:207], v[116:119]
	v_mfma_f32_16x16x32_bf16 v[112:115], v[188:191], v[204:207], v[112:115]
	v_mfma_f32_16x16x32_bf16 v[108:111], v[180:183], v[212:215], v[108:111]
	v_mfma_f32_16x16x32_bf16 v[104:107], v[188:191], v[212:215], v[104:107]
	v_mfma_f32_16x16x32_bf16 v[100:103], v[180:183], v[220:223], v[100:103]
	v_mfma_f32_16x16x32_bf16 v[96:99], v[188:191], v[220:223], v[96:99]
	s_barrier
	v_readfirstlane_b32 s6, v166
	v_lshl_add_u64 v[248:249], v[244:245], 0, s[94:95]
	s_mov_b32 m0, s6
	v_readfirstlane_b32 s6, v167
	ds_read_b128 v[224:227], v152
	ds_read_b128 v[228:231], v152 offset:1024
	ds_read_b128 v[232:235], v152 offset:2048
	ds_read_b128 v[236:239], v152 offset:3072
	global_load_lds_dwordx4 v[248:249], off
	v_lshl_add_u64 v[248:249], v[246:247], 0, s[94:95]
	s_mov_b32 m0, s6
	s_nop 0
	global_load_lds_dwordx4 v[248:249], off
	s_barrier
	s_waitcnt lgkmcnt(0)
	s_waitcnt lgkmcnt(0)
	v_mfma_f32_16x16x32_bf16 v[92:95], v[224:227], v[192:195], v[92:95]
	v_mfma_f32_16x16x32_bf16 v[88:91], v[232:235], v[192:195], v[88:91]
	v_mfma_f32_16x16x32_bf16 v[84:87], v[224:227], v[200:203], v[84:87]
	v_mfma_f32_16x16x32_bf16 v[80:83], v[232:235], v[200:203], v[80:83]
	v_mfma_f32_16x16x32_bf16 v[76:79], v[224:227], v[208:211], v[76:79]
	v_mfma_f32_16x16x32_bf16 v[72:75], v[232:235], v[208:211], v[72:75]
	v_mfma_f32_16x16x32_bf16 v[68:71], v[224:227], v[216:219], v[68:71]
	v_mfma_f32_16x16x32_bf16 v[64:67], v[232:235], v[216:219], v[64:67]
	v_mfma_f32_16x16x32_bf16 v[92:95], v[228:231], v[196:199], v[92:95]
	v_mfma_f32_16x16x32_bf16 v[88:91], v[236:239], v[196:199], v[88:91]
	v_mfma_f32_16x16x32_bf16 v[84:87], v[228:231], v[204:207], v[84:87]
	v_mfma_f32_16x16x32_bf16 v[80:83], v[236:239], v[204:207], v[80:83]
	v_mfma_f32_16x16x32_bf16 v[76:79], v[228:231], v[212:215], v[76:79]
	v_mfma_f32_16x16x32_bf16 v[72:75], v[236:239], v[212:215], v[72:75]
	v_mfma_f32_16x16x32_bf16 v[68:71], v[228:231], v[220:223], v[68:71]
	v_mfma_f32_16x16x32_bf16 v[64:67], v[236:239], v[220:223], v[64:67]
	v_readfirstlane_b32 s6, v168
	v_lshl_add_u64 v[240:241], v[240:241], 0, s[96:97]
	s_mov_b32 m0, s6
	v_readfirstlane_b32 s6, v169
	s_barrier
	ds_read_b128 v[192:195], v151 offset:49152
	ds_read_b128 v[196:199], v151 offset:50176
	ds_read_b128 v[200:203], v150 offset:49152
	ds_read_b128 v[204:207], v150 offset:50176
	ds_read_b128 v[208:211], v149 offset:49152
	ds_read_b128 v[212:215], v149 offset:50176
	ds_read_b128 v[216:219], v148 offset:49152
	ds_read_b128 v[220:223], v148 offset:50176
	global_load_lds_dwordx4 v[240:241], off
	v_lshl_add_u64 v[240:241], v[242:243], 0, s[96:97]
	s_mov_b32 m0, s6
	s_nop 0
	global_load_lds_dwordx4 v[240:241], off
	s_barrier
	s_waitcnt lgkmcnt(0)
	s_waitcnt lgkmcnt(0)
	v_mfma_f32_16x16x32_bf16 v[60:63], v[176:179], v[192:195], v[60:63]
	v_mfma_f32_16x16x32_bf16 v[56:59], v[184:187], v[192:195], v[56:59]
	v_mfma_f32_16x16x32_bf16 v[52:55], v[176:179], v[200:203], v[52:55]
	v_mfma_f32_16x16x32_bf16 v[48:51], v[184:187], v[200:203], v[48:51]
	v_mfma_f32_16x16x32_bf16 v[44:47], v[176:179], v[208:211], v[44:47]
	v_mfma_f32_16x16x32_bf16 v[40:43], v[184:187], v[208:211], v[40:43]
	v_mfma_f32_16x16x32_bf16 v[36:39], v[176:179], v[216:219], v[36:39]
	v_mfma_f32_16x16x32_bf16 v[32:35], v[184:187], v[216:219], v[32:35]
	v_mfma_f32_16x16x32_bf16 v[60:63], v[180:183], v[196:199], v[60:63]
	v_mfma_f32_16x16x32_bf16 v[56:59], v[188:191], v[196:199], v[56:59]
	v_mfma_f32_16x16x32_bf16 v[52:55], v[180:183], v[204:207], v[52:55]
	v_mfma_f32_16x16x32_bf16 v[48:51], v[188:191], v[204:207], v[48:51]
	v_mfma_f32_16x16x32_bf16 v[44:47], v[180:183], v[212:215], v[44:47]
	v_mfma_f32_16x16x32_bf16 v[40:43], v[188:191], v[212:215], v[40:43]
	v_mfma_f32_16x16x32_bf16 v[36:39], v[180:183], v[220:223], v[36:39]
	v_mfma_f32_16x16x32_bf16 v[32:35], v[188:191], v[220:223], v[32:35]
	s_barrier
	v_readfirstlane_b32 s6, v171
	v_lshl_add_u64 v[176:177], v[244:245], 0, s[40:41]
	s_mov_b32 m0, s6
	v_readfirstlane_b32 s6, v172
	global_load_lds_dwordx4 v[176:177], off
	v_lshl_add_u64 v[176:177], v[246:247], 0, s[40:41]
	s_mov_b32 m0, s6
	s_nop 0
	global_load_lds_dwordx4 v[176:177], off
	s_waitcnt vmcnt(6)
	s_barrier
	v_mfma_f32_16x16x32_bf16 v[28:31], v[224:227], v[192:195], v[28:31]
	v_mfma_f32_16x16x32_bf16 v[24:27], v[232:235], v[192:195], v[24:27]
	v_mfma_f32_16x16x32_bf16 v[20:23], v[224:227], v[200:203], v[20:23]
	v_mfma_f32_16x16x32_bf16 v[16:19], v[232:235], v[200:203], v[16:19]
	v_mfma_f32_16x16x32_bf16 v[12:15], v[224:227], v[208:211], v[12:15]
	v_mfma_f32_16x16x32_bf16 v[8:11], v[232:235], v[208:211], v[8:11]
	v_mfma_f32_16x16x32_bf16 v[4:7], v[224:227], v[216:219], v[4:7]
	v_mfma_f32_16x16x32_bf16 v[0:3], v[232:235], v[216:219], v[0:3]
	v_mfma_f32_16x16x32_bf16 v[28:31], v[228:231], v[196:199], v[28:31]
	v_mfma_f32_16x16x32_bf16 v[24:27], v[236:239], v[196:199], v[24:27]
	v_mfma_f32_16x16x32_bf16 v[20:23], v[228:231], v[204:207], v[20:23]
	v_mfma_f32_16x16x32_bf16 v[16:19], v[236:239], v[204:207], v[16:19]
	v_mfma_f32_16x16x32_bf16 v[12:15], v[228:231], v[212:215], v[12:15]
	v_mfma_f32_16x16x32_bf16 v[8:11], v[236:239], v[212:215], v[8:11]
	v_mfma_f32_16x16x32_bf16 v[4:7], v[228:231], v[220:223], v[4:7]
	v_mfma_f32_16x16x32_bf16 v[0:3], v[236:239], v[220:223], v[0:3]
	s_add_i32 s5, s5, 2
	v_lshl_add_u64 v[136:137], v[136:137], 0, s[42:43]
	v_lshl_add_u64 v[138:139], v[138:139], 0, s[42:43]
	v_lshl_add_u64 v[140:141], v[140:141], 0, s[42:43]
	s_cmp_lt_u32 s5, 12
	v_lshl_add_u64 v[142:143], v[142:143], 0, s[42:43]
	s_barrier
	s_cbranch_scc1 .LBB0_886
	s_mov_b64 s[6:7], 0x780
	v_readfirstlane_b32 s5, v174
	v_lshl_add_u64 v[132:133], v[132:133], 0, s[6:7]
	s_mov_b32 m0, s5
	v_readfirstlane_b32 s5, v175
	ds_read_b128 v[136:139], v173
	ds_read_b128 v[140:143], v173 offset:1024
	ds_read_b128 v[164:167], v173 offset:2048
	ds_read_b128 v[176:179], v173 offset:3072
	ds_read_b128 v[180:183], v151
	ds_read_b128 v[184:187], v151 offset:1024
	ds_read_b128 v[188:191], v150
	ds_read_b128 v[192:195], v150 offset:1024
	ds_read_b128 v[196:199], v149
	ds_read_b128 v[200:203], v149 offset:1024
	ds_read_b128 v[204:207], v148
	ds_read_b128 v[208:211], v148 offset:1024
	global_load_lds_dwordx4 v[132:133], off
	v_lshl_add_u64 v[132:133], v[134:135], 0, s[6:7]
	s_mov_b32 m0, s5
	s_nop 0
	global_load_lds_dwordx4 v[132:133], off
	s_barrier
	s_waitcnt lgkmcnt(0)
	s_waitcnt lgkmcnt(0)
	v_mfma_f32_16x16x32_bf16 v[124:127], v[136:139], v[180:183], v[124:127]
	v_mfma_f32_16x16x32_bf16 v[120:123], v[164:167], v[180:183], v[120:123]
	v_mfma_f32_16x16x32_bf16 v[116:119], v[136:139], v[188:191], v[116:119]
	v_mfma_f32_16x16x32_bf16 v[112:115], v[164:167], v[188:191], v[112:115]
	v_mfma_f32_16x16x32_bf16 v[108:111], v[136:139], v[196:199], v[108:111]
	v_mfma_f32_16x16x32_bf16 v[104:107], v[164:167], v[196:199], v[104:107]
	v_mfma_f32_16x16x32_bf16 v[100:103], v[136:139], v[204:207], v[100:103]
	v_mfma_f32_16x16x32_bf16 v[96:99], v[164:167], v[204:207], v[96:99]
	v_mfma_f32_16x16x32_bf16 v[124:127], v[140:143], v[184:187], v[124:127]
	v_mfma_f32_16x16x32_bf16 v[120:123], v[176:179], v[184:187], v[120:123]
	v_mfma_f32_16x16x32_bf16 v[116:119], v[140:143], v[192:195], v[116:119]
	v_mfma_f32_16x16x32_bf16 v[112:115], v[176:179], v[192:195], v[112:115]
	v_mfma_f32_16x16x32_bf16 v[108:111], v[140:143], v[200:203], v[108:111]
	v_mfma_f32_16x16x32_bf16 v[104:107], v[176:179], v[200:203], v[104:107]
	v_mfma_f32_16x16x32_bf16 v[100:103], v[140:143], v[208:211], v[100:103]
	v_mfma_f32_16x16x32_bf16 v[96:99], v[176:179], v[208:211], v[96:99]
	s_barrier
	ds_read_b128 v[132:135], v170
	ds_read_b128 v[172:175], v170 offset:1024
	ds_read_b128 v[212:215], v170 offset:2048
	ds_read_b128 v[168:171], v170 offset:3072
	s_barrier
	s_waitcnt lgkmcnt(0)
	s_waitcnt lgkmcnt(0)
	v_mfma_f32_16x16x32_bf16 v[92:95], v[132:135], v[180:183], v[92:95]
	v_mfma_f32_16x16x32_bf16 v[88:91], v[212:215], v[180:183], v[88:91]
	v_mfma_f32_16x16x32_bf16 v[84:87], v[132:135], v[188:191], v[84:87]
	v_mfma_f32_16x16x32_bf16 v[80:83], v[212:215], v[188:191], v[80:83]
	v_mfma_f32_16x16x32_bf16 v[76:79], v[132:135], v[196:199], v[76:79]
	v_mfma_f32_16x16x32_bf16 v[72:75], v[212:215], v[196:199], v[72:75]
	v_mfma_f32_16x16x32_bf16 v[68:71], v[132:135], v[204:207], v[68:71]
	v_mfma_f32_16x16x32_bf16 v[64:67], v[212:215], v[204:207], v[64:67]
	v_mfma_f32_16x16x32_bf16 v[92:95], v[172:175], v[184:187], v[92:95]
	v_mfma_f32_16x16x32_bf16 v[88:91], v[168:171], v[184:187], v[88:91]
	v_mfma_f32_16x16x32_bf16 v[84:87], v[172:175], v[192:195], v[84:87]
	v_mfma_f32_16x16x32_bf16 v[80:83], v[168:171], v[192:195], v[80:83]
	v_mfma_f32_16x16x32_bf16 v[76:79], v[172:175], v[200:203], v[76:79]
	v_mfma_f32_16x16x32_bf16 v[72:75], v[168:171], v[200:203], v[72:75]
	v_mfma_f32_16x16x32_bf16 v[68:71], v[172:175], v[208:211], v[68:71]
	v_mfma_f32_16x16x32_bf16 v[64:67], v[168:171], v[208:211], v[64:67]
	s_barrier
	ds_read_b128 v[180:183], v151 offset:16384
	ds_read_b128 v[184:187], v151 offset:17408
	ds_read_b128 v[188:191], v150 offset:16384
	ds_read_b128 v[192:195], v150 offset:17408
	ds_read_b128 v[196:199], v149 offset:16384
	ds_read_b128 v[200:203], v149 offset:17408
	ds_read_b128 v[204:207], v148 offset:16384
	ds_read_b128 v[208:211], v148 offset:17408
	s_waitcnt vmcnt(4)
	s_barrier
	s_waitcnt lgkmcnt(0)
	s_waitcnt lgkmcnt(0)
	v_mfma_f32_16x16x32_bf16 v[60:63], v[136:139], v[180:183], v[60:63]
	v_mfma_f32_16x16x32_bf16 v[56:59], v[164:167], v[180:183], v[56:59]
	v_mfma_f32_16x16x32_bf16 v[52:55], v[136:139], v[188:191], v[52:55]
	v_mfma_f32_16x16x32_bf16 v[48:51], v[164:167], v[188:191], v[48:51]
	v_mfma_f32_16x16x32_bf16 v[44:47], v[136:139], v[196:199], v[44:47]
	v_mfma_f32_16x16x32_bf16 v[40:43], v[164:167], v[196:199], v[40:43]
	v_mfma_f32_16x16x32_bf16 v[36:39], v[136:139], v[204:207], v[36:39]
	v_mfma_f32_16x16x32_bf16 v[32:35], v[164:167], v[204:207], v[32:35]
	v_mfma_f32_16x16x32_bf16 v[60:63], v[140:143], v[184:187], v[60:63]
	v_mfma_f32_16x16x32_bf16 v[56:59], v[176:179], v[184:187], v[56:59]
	v_mfma_f32_16x16x32_bf16 v[52:55], v[140:143], v[192:195], v[52:55]
	v_mfma_f32_16x16x32_bf16 v[48:51], v[176:179], v[192:195], v[48:51]
	v_mfma_f32_16x16x32_bf16 v[44:47], v[140:143], v[200:203], v[44:47]
	v_mfma_f32_16x16x32_bf16 v[40:43], v[176:179], v[200:203], v[40:43]
	v_mfma_f32_16x16x32_bf16 v[36:39], v[140:143], v[208:211], v[36:39]
	v_mfma_f32_16x16x32_bf16 v[32:35], v[176:179], v[208:211], v[32:35]
	v_mfma_f32_16x16x32_bf16 v[28:31], v[132:135], v[180:183], v[28:31]
	v_mfma_f32_16x16x32_bf16 v[24:27], v[212:215], v[180:183], v[24:27]
	v_mfma_f32_16x16x32_bf16 v[20:23], v[132:135], v[188:191], v[20:23]
	v_mfma_f32_16x16x32_bf16 v[16:19], v[212:215], v[188:191], v[16:19]
	v_mfma_f32_16x16x32_bf16 v[12:15], v[132:135], v[196:199], v[12:15]
	v_mfma_f32_16x16x32_bf16 v[8:11], v[212:215], v[196:199], v[8:11]
	v_mfma_f32_16x16x32_bf16 v[4:7], v[132:135], v[204:207], v[4:7]
	v_mfma_f32_16x16x32_bf16 v[0:3], v[212:215], v[204:207], v[0:3]
	v_mfma_f32_16x16x32_bf16 v[28:31], v[172:175], v[184:187], v[28:31]
	v_mfma_f32_16x16x32_bf16 v[24:27], v[168:171], v[184:187], v[24:27]
	v_mfma_f32_16x16x32_bf16 v[20:23], v[172:175], v[192:195], v[20:23]
	v_mfma_f32_16x16x32_bf16 v[16:19], v[168:171], v[192:195], v[16:19]
	v_mfma_f32_16x16x32_bf16 v[12:15], v[172:175], v[200:203], v[12:15]
	v_mfma_f32_16x16x32_bf16 v[8:11], v[168:171], v[200:203], v[8:11]
	v_mfma_f32_16x16x32_bf16 v[4:7], v[172:175], v[208:211], v[4:7]
	v_mfma_f32_16x16x32_bf16 v[0:3], v[168:171], v[208:211], v[0:3]
	s_barrier
	ds_read_b128 v[132:135], v161
	ds_read_b128 v[136:139], v161 offset:1024
	ds_read_b128 v[140:143], v161 offset:2048
	ds_read_b128 v[164:167], v161 offset:3072
	ds_read_b128 v[168:171], v151 offset:32768
	ds_read_b128 v[172:175], v151 offset:33792
	ds_read_b128 v[176:179], v150 offset:32768
	ds_read_b128 v[180:183], v150 offset:33792
	ds_read_b128 v[184:187], v149 offset:32768
	ds_read_b128 v[188:191], v149 offset:33792
	ds_read_b128 v[192:195], v148 offset:32768
	ds_read_b128 v[196:199], v148 offset:33792
	s_waitcnt vmcnt(2)
	s_barrier
	s_waitcnt lgkmcnt(0)
	s_waitcnt lgkmcnt(0)
	v_mfma_f32_16x16x32_bf16 v[124:127], v[132:135], v[168:171], v[124:127]
	v_mfma_f32_16x16x32_bf16 v[120:123], v[140:143], v[168:171], v[120:123]
	v_mfma_f32_16x16x32_bf16 v[116:119], v[132:135], v[176:179], v[116:119]
	v_mfma_f32_16x16x32_bf16 v[112:115], v[140:143], v[176:179], v[112:115]
	v_mfma_f32_16x16x32_bf16 v[108:111], v[132:135], v[184:187], v[108:111]
	v_mfma_f32_16x16x32_bf16 v[104:107], v[140:143], v[184:187], v[104:107]
	v_mfma_f32_16x16x32_bf16 v[100:103], v[132:135], v[192:195], v[100:103]
	v_mfma_f32_16x16x32_bf16 v[96:99], v[140:143], v[192:195], v[96:99]
	v_mfma_f32_16x16x32_bf16 v[124:127], v[136:139], v[172:175], v[124:127]
	v_mfma_f32_16x16x32_bf16 v[120:123], v[164:167], v[172:175], v[120:123]
	v_mfma_f32_16x16x32_bf16 v[116:119], v[136:139], v[180:183], v[116:119]
	v_mfma_f32_16x16x32_bf16 v[112:115], v[164:167], v[180:183], v[112:115]
	v_mfma_f32_16x16x32_bf16 v[108:111], v[136:139], v[188:191], v[108:111]
	v_mfma_f32_16x16x32_bf16 v[104:107], v[164:167], v[188:191], v[104:107]
	v_mfma_f32_16x16x32_bf16 v[100:103], v[136:139], v[196:199], v[100:103]
	v_mfma_f32_16x16x32_bf16 v[96:99], v[164:167], v[196:199], v[96:99]
	s_barrier
	ds_read_b128 v[200:203], v152
	ds_read_b128 v[204:207], v152 offset:1024
	ds_read_b128 v[208:211], v152 offset:2048
	ds_read_b128 v[212:215], v152 offset:3072
	s_waitcnt vmcnt(0)
	s_barrier
	s_waitcnt lgkmcnt(0)
	s_waitcnt lgkmcnt(0)
	v_mfma_f32_16x16x32_bf16 v[92:95], v[200:203], v[168:171], v[92:95]
	v_mfma_f32_16x16x32_bf16 v[88:91], v[208:211], v[168:171], v[88:91]
	v_mfma_f32_16x16x32_bf16 v[84:87], v[200:203], v[176:179], v[84:87]
	v_mfma_f32_16x16x32_bf16 v[80:83], v[208:211], v[176:179], v[80:83]
	v_mfma_f32_16x16x32_bf16 v[76:79], v[200:203], v[184:187], v[76:79]
	v_mfma_f32_16x16x32_bf16 v[72:75], v[208:211], v[184:187], v[72:75]
	v_mfma_f32_16x16x32_bf16 v[68:71], v[200:203], v[192:195], v[68:71]
	v_mfma_f32_16x16x32_bf16 v[64:67], v[208:211], v[192:195], v[64:67]
	v_mfma_f32_16x16x32_bf16 v[92:95], v[204:207], v[172:175], v[92:95]
	v_mfma_f32_16x16x32_bf16 v[88:91], v[212:215], v[172:175], v[88:91]
	v_mfma_f32_16x16x32_bf16 v[84:87], v[204:207], v[180:183], v[84:87]
	v_mfma_f32_16x16x32_bf16 v[80:83], v[212:215], v[180:183], v[80:83]
	v_mfma_f32_16x16x32_bf16 v[76:79], v[204:207], v[188:191], v[76:79]
	v_mfma_f32_16x16x32_bf16 v[72:75], v[212:215], v[188:191], v[72:75]
	v_mfma_f32_16x16x32_bf16 v[68:71], v[204:207], v[196:199], v[68:71]
	v_mfma_f32_16x16x32_bf16 v[64:67], v[212:215], v[196:199], v[64:67]
	s_barrier
	ds_read_b128 v[168:171], v151 offset:49152
	ds_read_b128 v[172:175], v151 offset:50176
	ds_read_b128 v[176:179], v150 offset:49152
	ds_read_b128 v[150:153], v150 offset:50176
	ds_read_b128 v[180:183], v149 offset:49152
	ds_read_b128 v[184:187], v149 offset:50176
	ds_read_b128 v[188:191], v148 offset:49152
	ds_read_b128 v[192:195], v148 offset:50176
	s_barrier
	s_waitcnt lgkmcnt(0)
	s_waitcnt lgkmcnt(0)
	v_mfma_f32_16x16x32_bf16 v[60:63], v[132:135], v[168:171], v[60:63]
	v_mfma_f32_16x16x32_bf16 v[56:59], v[140:143], v[168:171], v[56:59]
	v_mfma_f32_16x16x32_bf16 v[52:55], v[132:135], v[176:179], v[52:55]
	v_mfma_f32_16x16x32_bf16 v[48:51], v[140:143], v[176:179], v[48:51]
	v_mfma_f32_16x16x32_bf16 v[44:47], v[132:135], v[180:183], v[44:47]
	v_mfma_f32_16x16x32_bf16 v[40:43], v[140:143], v[180:183], v[40:43]
	v_mfma_f32_16x16x32_bf16 v[36:39], v[132:135], v[188:191], v[36:39]
	v_mfma_f32_16x16x32_bf16 v[32:35], v[140:143], v[188:191], v[32:35]
	v_mfma_f32_16x16x32_bf16 v[60:63], v[136:139], v[172:175], v[60:63]
	v_mfma_f32_16x16x32_bf16 v[56:59], v[164:167], v[172:175], v[56:59]
	v_mfma_f32_16x16x32_bf16 v[52:55], v[136:139], v[150:153], v[52:55]
	v_mfma_f32_16x16x32_bf16 v[48:51], v[164:167], v[150:153], v[48:51]
	v_mfma_f32_16x16x32_bf16 v[44:47], v[136:139], v[184:187], v[44:47]
	v_mfma_f32_16x16x32_bf16 v[40:43], v[164:167], v[184:187], v[40:43]
	v_mfma_f32_16x16x32_bf16 v[36:39], v[136:139], v[192:195], v[36:39]
	v_mfma_f32_16x16x32_bf16 v[32:35], v[164:167], v[192:195], v[32:35]
	v_mfma_f32_16x16x32_bf16 v[28:31], v[200:203], v[168:171], v[28:31]
	v_mfma_f32_16x16x32_bf16 v[24:27], v[208:211], v[168:171], v[24:27]
	v_mfma_f32_16x16x32_bf16 v[20:23], v[200:203], v[176:179], v[20:23]
	v_mfma_f32_16x16x32_bf16 v[16:19], v[208:211], v[176:179], v[16:19]
	v_mfma_f32_16x16x32_bf16 v[12:15], v[200:203], v[180:183], v[12:15]
	v_mfma_f32_16x16x32_bf16 v[8:11], v[208:211], v[180:183], v[8:11]
	v_mfma_f32_16x16x32_bf16 v[4:7], v[200:203], v[188:191], v[4:7]
	v_mfma_f32_16x16x32_bf16 v[0:3], v[208:211], v[188:191], v[0:3]
	v_mfma_f32_16x16x32_bf16 v[28:31], v[204:207], v[172:175], v[28:31]
	v_mfma_f32_16x16x32_bf16 v[24:27], v[212:215], v[172:175], v[24:27]
	v_mfma_f32_16x16x32_bf16 v[20:23], v[204:207], v[150:153], v[20:23]
	v_mfma_f32_16x16x32_bf16 v[16:19], v[212:215], v[150:153], v[16:19]
	v_mfma_f32_16x16x32_bf16 v[12:15], v[204:207], v[184:187], v[12:15]
	v_mfma_f32_16x16x32_bf16 v[8:11], v[212:215], v[184:187], v[8:11]
	v_mfma_f32_16x16x32_bf16 v[4:7], v[204:207], v[192:195], v[4:7]
	v_mfma_f32_16x16x32_bf16 v[0:3], v[212:215], v[192:195], v[0:3]
	s_movk_i32 s5, 0x100
	v_cmp_gt_u32_e32 vcc, s5, v144
	s_barrier
	s_and_saveexec_b64 s[6:7], vcc
	s_cbranch_execz .LBB0_889
	s_barrier

.LBB0_1688:
	ds_read_b128 v[178:181], v175
	ds_read_b128 v[182:185], v175 offset:1024
	ds_read_b128 v[186:189], v175 offset:2048
	ds_read_b128 v[190:193], v175 offset:3072
	v_add_u32_e32 v176, 0xc000, v162
	v_lshl_add_u64 v[242:243], s[4:5], 0, v[142:143]
	v_readfirstlane_b32 s43, v176
	v_add_u32_e32 v177, 0xe000, v162
	v_lshl_add_u64 v[226:227], v[242:243], 0, s[12:13]
	s_mov_b32 m0, s43
	v_lshl_add_u64 v[244:245], s[4:5], 0, v[140:141]
	v_readfirstlane_b32 s43, v177
	ds_read_b128 v[194:197], v160
	ds_read_b128 v[198:201], v160 offset:1024
	ds_read_b128 v[202:205], v159
	ds_read_b128 v[206:209], v159 offset:1024
	ds_read_b128 v[210:213], v158
	ds_read_b128 v[214:217], v158 offset:1024
	ds_read_b128 v[218:221], v157
	ds_read_b128 v[222:225], v157 offset:1024
	global_load_lds_dwordx4 v[226:227], off
	v_lshl_add_u64 v[226:227], v[244:245], 0, s[12:13]
	s_mov_b32 m0, s43
	s_nop 0
	global_load_lds_dwordx4 v[226:227], off
	s_waitcnt lgkmcnt(8)
	s_barrier
	s_waitcnt lgkmcnt(0)
	s_waitcnt lgkmcnt(0)
	v_mfma_f32_16x16x32_bf16 v[124:127], v[178:181], v[194:197], v[124:127]
	v_mfma_f32_16x16x32_bf16 v[120:123], v[186:189], v[194:197], v[120:123]
	v_mfma_f32_16x16x32_bf16 v[116:119], v[178:181], v[202:205], v[116:119]
	v_mfma_f32_16x16x32_bf16 v[112:115], v[186:189], v[202:205], v[112:115]
	v_mfma_f32_16x16x32_bf16 v[108:111], v[178:181], v[210:213], v[108:111]
	v_mfma_f32_16x16x32_bf16 v[104:107], v[186:189], v[210:213], v[104:107]
	v_mfma_f32_16x16x32_bf16 v[100:103], v[178:181], v[218:221], v[100:103]
	v_mfma_f32_16x16x32_bf16 v[96:99], v[186:189], v[218:221], v[96:99]
	v_mfma_f32_16x16x32_bf16 v[124:127], v[182:185], v[198:201], v[124:127]
	v_mfma_f32_16x16x32_bf16 v[120:123], v[190:193], v[198:201], v[120:123]
	v_mfma_f32_16x16x32_bf16 v[116:119], v[182:185], v[206:209], v[116:119]
	v_mfma_f32_16x16x32_bf16 v[112:115], v[190:193], v[206:209], v[112:115]
	v_mfma_f32_16x16x32_bf16 v[108:111], v[182:185], v[214:217], v[108:111]
	v_mfma_f32_16x16x32_bf16 v[104:107], v[190:193], v[214:217], v[104:107]
	v_mfma_f32_16x16x32_bf16 v[100:103], v[182:185], v[222:225], v[100:103]
	v_mfma_f32_16x16x32_bf16 v[96:99], v[190:193], v[222:225], v[96:99]
	s_barrier
	v_lshl_add_u64 v[246:247], s[4:5], 0, v[138:139]
	v_readfirstlane_b32 s43, v156
	v_lshl_add_u64 v[248:249], v[246:247], 0, s[14:15]
	s_mov_b32 m0, s43
	v_add_u32_e32 v252, 0x2000, v156
	ds_read_b128 v[226:229], v172
	ds_read_b128 v[230:233], v172 offset:1024
	ds_read_b128 v[234:237], v172 offset:2048
	ds_read_b128 v[238:241], v172 offset:3072
	global_load_lds_dwordx4 v[248:249], off
	v_lshl_add_u64 v[248:249], s[4:5], 0, v[136:137]
	v_readfirstlane_b32 s43, v252
	v_lshl_add_u64 v[250:251], v[248:249], 0, s[14:15]
	s_mov_b32 m0, s43
	s_nop 0
	global_load_lds_dwordx4 v[250:251], off
	s_barrier
	s_waitcnt lgkmcnt(0)
	s_waitcnt lgkmcnt(0)
	v_mfma_f32_16x16x32_bf16 v[92:95], v[226:229], v[194:197], v[92:95]
	v_mfma_f32_16x16x32_bf16 v[88:91], v[234:237], v[194:197], v[88:91]
	v_mfma_f32_16x16x32_bf16 v[84:87], v[226:229], v[202:205], v[84:87]
	v_mfma_f32_16x16x32_bf16 v[80:83], v[234:237], v[202:205], v[80:83]
	v_mfma_f32_16x16x32_bf16 v[76:79], v[226:229], v[210:213], v[76:79]
	v_mfma_f32_16x16x32_bf16 v[72:75], v[234:237], v[210:213], v[72:75]
	v_mfma_f32_16x16x32_bf16 v[68:71], v[226:229], v[218:221], v[68:71]
	v_mfma_f32_16x16x32_bf16 v[64:67], v[234:237], v[218:221], v[64:67]
	v_mfma_f32_16x16x32_bf16 v[92:95], v[230:233], v[198:201], v[92:95]
	v_mfma_f32_16x16x32_bf16 v[88:91], v[238:241], v[198:201], v[88:91]
	v_mfma_f32_16x16x32_bf16 v[84:87], v[230:233], v[206:209], v[84:87]
	v_mfma_f32_16x16x32_bf16 v[80:83], v[238:241], v[206:209], v[80:83]
	v_mfma_f32_16x16x32_bf16 v[76:79], v[230:233], v[214:217], v[76:79]
	v_mfma_f32_16x16x32_bf16 v[72:75], v[238:241], v[214:217], v[72:75]
	v_mfma_f32_16x16x32_bf16 v[68:71], v[230:233], v[222:225], v[68:71]
	v_mfma_f32_16x16x32_bf16 v[64:67], v[238:241], v[222:225], v[64:67]
	v_readfirstlane_b32 s43, v162
	v_lshl_add_u64 v[250:251], v[242:243], 0, s[16:17]
	s_mov_b32 m0, s43
	v_readfirstlane_b32 s43, v163
	s_barrier
	ds_read_b128 v[194:197], v160 offset:16384
	ds_read_b128 v[198:201], v160 offset:17408
	ds_read_b128 v[202:205], v159 offset:16384
	ds_read_b128 v[206:209], v159 offset:17408
	ds_read_b128 v[210:213], v158 offset:16384
	ds_read_b128 v[214:217], v158 offset:17408
	ds_read_b128 v[218:221], v157 offset:16384
	ds_read_b128 v[222:225], v157 offset:17408
	global_load_lds_dwordx4 v[250:251], off
	v_lshl_add_u64 v[250:251], v[244:245], 0, s[16:17]
	s_mov_b32 m0, s43
	s_nop 0
	global_load_lds_dwordx4 v[250:251], off
	s_barrier
	s_waitcnt lgkmcnt(0)
	s_waitcnt lgkmcnt(0)
	v_mfma_f32_16x16x32_bf16 v[60:63], v[178:181], v[194:197], v[60:63]
	v_mfma_f32_16x16x32_bf16 v[56:59], v[186:189], v[194:197], v[56:59]
	v_mfma_f32_16x16x32_bf16 v[52:55], v[178:181], v[202:205], v[52:55]
	v_mfma_f32_16x16x32_bf16 v[48:51], v[186:189], v[202:205], v[48:51]
	v_mfma_f32_16x16x32_bf16 v[44:47], v[178:181], v[210:213], v[44:47]
	v_mfma_f32_16x16x32_bf16 v[40:43], v[186:189], v[210:213], v[40:43]
	v_mfma_f32_16x16x32_bf16 v[36:39], v[178:181], v[218:221], v[36:39]
	v_mfma_f32_16x16x32_bf16 v[32:35], v[186:189], v[218:221], v[32:35]
	v_mfma_f32_16x16x32_bf16 v[60:63], v[182:185], v[198:201], v[60:63]
	v_mfma_f32_16x16x32_bf16 v[56:59], v[190:193], v[198:201], v[56:59]
	v_mfma_f32_16x16x32_bf16 v[52:55], v[182:185], v[206:209], v[52:55]
	v_mfma_f32_16x16x32_bf16 v[48:51], v[190:193], v[206:209], v[48:51]
	v_mfma_f32_16x16x32_bf16 v[44:47], v[182:185], v[214:217], v[44:47]
	v_mfma_f32_16x16x32_bf16 v[40:43], v[190:193], v[214:217], v[40:43]
	v_mfma_f32_16x16x32_bf16 v[36:39], v[182:185], v[222:225], v[36:39]
	v_mfma_f32_16x16x32_bf16 v[32:35], v[190:193], v[222:225], v[32:35]
	s_barrier
	v_readfirstlane_b32 s43, v165
	v_add_u32_e32 v180, 0x2000, v165
	v_lshl_add_u64 v[178:179], v[246:247], 0, s[18:19]
	s_mov_b32 m0, s43
	v_readfirstlane_b32 s43, v180
	global_load_lds_dwordx4 v[178:179], off
	v_lshl_add_u64 v[178:179], v[248:249], 0, s[18:19]
	s_mov_b32 m0, s43
	s_nop 0
	global_load_lds_dwordx4 v[178:179], off
	s_waitcnt vmcnt(6)
	s_barrier
	v_mfma_f32_16x16x32_bf16 v[28:31], v[226:229], v[194:197], v[28:31]
	v_mfma_f32_16x16x32_bf16 v[24:27], v[234:237], v[194:197], v[24:27]
	v_mfma_f32_16x16x32_bf16 v[20:23], v[226:229], v[202:205], v[20:23]
	v_mfma_f32_16x16x32_bf16 v[16:19], v[234:237], v[202:205], v[16:19]
	v_mfma_f32_16x16x32_bf16 v[12:15], v[226:229], v[210:213], v[12:15]
	v_mfma_f32_16x16x32_bf16 v[8:11], v[234:237], v[210:213], v[8:11]
	v_mfma_f32_16x16x32_bf16 v[4:7], v[226:229], v[218:221], v[4:7]
	v_mfma_f32_16x16x32_bf16 v[0:3], v[234:237], v[218:221], v[0:3]
	v_mfma_f32_16x16x32_bf16 v[28:31], v[230:233], v[198:201], v[28:31]
	v_mfma_f32_16x16x32_bf16 v[24:27], v[238:241], v[198:201], v[24:27]
	v_mfma_f32_16x16x32_bf16 v[20:23], v[230:233], v[206:209], v[20:23]
	v_mfma_f32_16x16x32_bf16 v[16:19], v[238:241], v[206:209], v[16:19]
	v_mfma_f32_16x16x32_bf16 v[12:15], v[230:233], v[214:217], v[12:15]
	v_mfma_f32_16x16x32_bf16 v[8:11], v[238:241], v[214:217], v[8:11]
	v_mfma_f32_16x16x32_bf16 v[4:7], v[230:233], v[222:225], v[4:7]
	v_mfma_f32_16x16x32_bf16 v[0:3], v[238:241], v[222:225], v[0:3]
	s_barrier
	ds_read_b128 v[178:181], v164
	ds_read_b128 v[182:185], v164 offset:1024
	ds_read_b128 v[186:189], v164 offset:2048
	ds_read_b128 v[190:193], v164 offset:3072
	v_readfirstlane_b32 s43, v166
	v_lshl_add_u64 v[226:227], v[242:243], 0, s[20:21]
	s_mov_b32 m0, s43
	v_readfirstlane_b32 s43, v167
	ds_read_b128 v[194:197], v160 offset:32768
	ds_read_b128 v[198:201], v160 offset:33792
	ds_read_b128 v[202:205], v159 offset:32768
	ds_read_b128 v[206:209], v159 offset:33792
	ds_read_b128 v[210:213], v158 offset:32768
	ds_read_b128 v[214:217], v158 offset:33792
	ds_read_b128 v[218:221], v157 offset:32768
	ds_read_b128 v[222:225], v157 offset:33792
	global_load_lds_dwordx4 v[226:227], off
	v_lshl_add_u64 v[226:227], v[244:245], 0, s[20:21]
	s_mov_b32 m0, s43
	s_nop 0
	global_load_lds_dwordx4 v[226:227], off
	s_waitcnt lgkmcnt(8)
	s_barrier
	s_waitcnt lgkmcnt(0)
	s_waitcnt lgkmcnt(0)
	v_mfma_f32_16x16x32_bf16 v[124:127], v[178:181], v[194:197], v[124:127]
	v_mfma_f32_16x16x32_bf16 v[120:123], v[186:189], v[194:197], v[120:123]
	v_mfma_f32_16x16x32_bf16 v[116:119], v[178:181], v[202:205], v[116:119]
	v_mfma_f32_16x16x32_bf16 v[112:115], v[186:189], v[202:205], v[112:115]
	v_mfma_f32_16x16x32_bf16 v[108:111], v[178:181], v[210:213], v[108:111]
	v_mfma_f32_16x16x32_bf16 v[104:107], v[186:189], v[210:213], v[104:107]
	v_mfma_f32_16x16x32_bf16 v[100:103], v[178:181], v[218:221], v[100:103]
	v_mfma_f32_16x16x32_bf16 v[96:99], v[186:189], v[218:221], v[96:99]
	v_mfma_f32_16x16x32_bf16 v[124:127], v[182:185], v[198:201], v[124:127]
	v_mfma_f32_16x16x32_bf16 v[120:123], v[190:193], v[198:201], v[120:123]
	v_mfma_f32_16x16x32_bf16 v[116:119], v[182:185], v[206:209], v[116:119]
	v_mfma_f32_16x16x32_bf16 v[112:115], v[190:193], v[206:209], v[112:115]
	v_mfma_f32_16x16x32_bf16 v[108:111], v[182:185], v[214:217], v[108:111]
	v_mfma_f32_16x16x32_bf16 v[104:107], v[190:193], v[214:217], v[104:107]
	v_mfma_f32_16x16x32_bf16 v[100:103], v[182:185], v[222:225], v[100:103]
	v_mfma_f32_16x16x32_bf16 v[96:99], v[190:193], v[222:225], v[96:99]
	s_barrier
	v_readfirstlane_b32 s43, v168
	v_lshl_add_u64 v[250:251], v[246:247], 0, s[22:23]
	s_mov_b32 m0, s43
	v_readfirstlane_b32 s43, v169
	ds_read_b128 v[226:229], v161
	ds_read_b128 v[230:233], v161 offset:1024
	ds_read_b128 v[234:237], v161 offset:2048
	ds_read_b128 v[238:241], v161 offset:3072
	global_load_lds_dwordx4 v[250:251], off
	v_lshl_add_u64 v[250:251], v[248:249], 0, s[22:23]
	s_mov_b32 m0, s43
	s_nop 0
	global_load_lds_dwordx4 v[250:251], off
	s_barrier
	s_waitcnt lgkmcnt(0)
	s_waitcnt lgkmcnt(0)
	v_mfma_f32_16x16x32_bf16 v[92:95], v[226:229], v[194:197], v[92:95]
	v_mfma_f32_16x16x32_bf16 v[88:91], v[234:237], v[194:197], v[88:91]
	v_mfma_f32_16x16x32_bf16 v[84:87], v[226:229], v[202:205], v[84:87]
	v_mfma_f32_16x16x32_bf16 v[80:83], v[234:237], v[202:205], v[80:83]
	v_mfma_f32_16x16x32_bf16 v[76:79], v[226:229], v[210:213], v[76:79]
	v_mfma_f32_16x16x32_bf16 v[72:75], v[234:237], v[210:213], v[72:75]
	v_mfma_f32_16x16x32_bf16 v[68:71], v[226:229], v[218:221], v[68:71]
	v_mfma_f32_16x16x32_bf16 v[64:67], v[234:237], v[218:221], v[64:67]
	v_mfma_f32_16x16x32_bf16 v[92:95], v[230:233], v[198:201], v[92:95]
	v_mfma_f32_16x16x32_bf16 v[88:91], v[238:241], v[198:201], v[88:91]
	v_mfma_f32_16x16x32_bf16 v[84:87], v[230:233], v[206:209], v[84:87]
	v_mfma_f32_16x16x32_bf16 v[80:83], v[238:241], v[206:209], v[80:83]
	v_mfma_f32_16x16x32_bf16 v[76:79], v[230:233], v[214:217], v[76:79]
	v_mfma_f32_16x16x32_bf16 v[72:75], v[238:241], v[214:217], v[72:75]
	v_mfma_f32_16x16x32_bf16 v[68:71], v[230:233], v[222:225], v[68:71]
	v_mfma_f32_16x16x32_bf16 v[64:67], v[238:241], v[222:225], v[64:67]
	v_readfirstlane_b32 s43, v170
	v_lshl_add_u64 v[242:243], v[242:243], 0, s[24:25]
	s_mov_b32 m0, s43
	v_readfirstlane_b32 s43, v171
	s_barrier
	ds_read_b128 v[194:197], v160 offset:49152
	ds_read_b128 v[198:201], v160 offset:50176
	ds_read_b128 v[202:205], v159 offset:49152
	ds_read_b128 v[206:209], v159 offset:50176
	ds_read_b128 v[210:213], v158 offset:49152
	ds_read_b128 v[214:217], v158 offset:50176
	ds_read_b128 v[218:221], v157 offset:49152
	ds_read_b128 v[222:225], v157 offset:50176
	global_load_lds_dwordx4 v[242:243], off
	v_lshl_add_u64 v[242:243], v[244:245], 0, s[24:25]
	s_mov_b32 m0, s43
	s_nop 0
	global_load_lds_dwordx4 v[242:243], off
	s_barrier
	s_waitcnt lgkmcnt(0)
	s_waitcnt lgkmcnt(0)
	v_mfma_f32_16x16x32_bf16 v[60:63], v[178:181], v[194:197], v[60:63]
	v_mfma_f32_16x16x32_bf16 v[56:59], v[186:189], v[194:197], v[56:59]
	v_mfma_f32_16x16x32_bf16 v[52:55], v[178:181], v[202:205], v[52:55]
	v_mfma_f32_16x16x32_bf16 v[48:51], v[186:189], v[202:205], v[48:51]
	v_mfma_f32_16x16x32_bf16 v[44:47], v[178:181], v[210:213], v[44:47]
	v_mfma_f32_16x16x32_bf16 v[40:43], v[186:189], v[210:213], v[40:43]
	v_mfma_f32_16x16x32_bf16 v[36:39], v[178:181], v[218:221], v[36:39]
	v_mfma_f32_16x16x32_bf16 v[32:35], v[186:189], v[218:221], v[32:35]
	v_mfma_f32_16x16x32_bf16 v[60:63], v[182:185], v[198:201], v[60:63]
	v_mfma_f32_16x16x32_bf16 v[56:59], v[190:193], v[198:201], v[56:59]
	v_mfma_f32_16x16x32_bf16 v[52:55], v[182:185], v[206:209], v[52:55]
	v_mfma_f32_16x16x32_bf16 v[48:51], v[190:193], v[206:209], v[48:51]
	v_mfma_f32_16x16x32_bf16 v[44:47], v[182:185], v[214:217], v[44:47]
	v_mfma_f32_16x16x32_bf16 v[40:43], v[190:193], v[214:217], v[40:43]
	v_mfma_f32_16x16x32_bf16 v[36:39], v[182:185], v[222:225], v[36:39]
	v_mfma_f32_16x16x32_bf16 v[32:35], v[190:193], v[222:225], v[32:35]
	s_barrier
	v_readfirstlane_b32 s43, v173
	v_lshl_add_u64 v[178:179], v[246:247], 0, s[26:27]
	s_mov_b32 m0, s43
	v_readfirstlane_b32 s43, v174
	global_load_lds_dwordx4 v[178:179], off
	v_lshl_add_u64 v[178:179], v[248:249], 0, s[26:27]
	s_mov_b32 m0, s43
	s_nop 0
	global_load_lds_dwordx4 v[178:179], off
	s_waitcnt vmcnt(6)
	s_barrier
	v_mfma_f32_16x16x32_bf16 v[28:31], v[226:229], v[194:197], v[28:31]
	v_mfma_f32_16x16x32_bf16 v[24:27], v[234:237], v[194:197], v[24:27]
	v_mfma_f32_16x16x32_bf16 v[20:23], v[226:229], v[202:205], v[20:23]
	v_mfma_f32_16x16x32_bf16 v[16:19], v[234:237], v[202:205], v[16:19]
	v_mfma_f32_16x16x32_bf16 v[12:15], v[226:229], v[210:213], v[12:15]
	v_mfma_f32_16x16x32_bf16 v[8:11], v[234:237], v[210:213], v[8:11]
	v_mfma_f32_16x16x32_bf16 v[4:7], v[226:229], v[218:221], v[4:7]
	v_mfma_f32_16x16x32_bf16 v[0:3], v[234:237], v[218:221], v[0:3]
	v_mfma_f32_16x16x32_bf16 v[28:31], v[230:233], v[198:201], v[28:31]
	v_mfma_f32_16x16x32_bf16 v[24:27], v[238:241], v[198:201], v[24:27]
	v_mfma_f32_16x16x32_bf16 v[20:23], v[230:233], v[206:209], v[20:23]
	v_mfma_f32_16x16x32_bf16 v[16:19], v[238:241], v[206:209], v[16:19]
	v_mfma_f32_16x16x32_bf16 v[12:15], v[230:233], v[214:217], v[12:15]
	v_mfma_f32_16x16x32_bf16 v[8:11], v[238:241], v[214:217], v[8:11]
	v_mfma_f32_16x16x32_bf16 v[4:7], v[230:233], v[222:225], v[4:7]
	v_mfma_f32_16x16x32_bf16 v[0:3], v[238:241], v[222:225], v[0:3]
	s_add_i32 s41, s41, 2
	v_lshl_add_u64 v[136:137], v[136:137], 0, s[28:29]
	v_lshl_add_u64 v[138:139], v[138:139], 0, s[28:29]
	v_lshl_add_u64 v[140:141], v[140:141], 0, s[28:29]
	s_cmp_lt_u32 s41, 12
	v_lshl_add_u64 v[142:143], v[142:143], 0, s[28:29]
	s_barrier
	s_cbranch_scc1 .LBB0_1688
	v_readfirstlane_b32 s41, v176
	v_lshl_add_u64 v[132:133], v[132:133], 0, s[30:31]
	s_mov_b32 m0, s41
	v_readfirstlane_b32 s41, v177
	ds_read_b128 v[136:139], v175
	ds_read_b128 v[140:143], v175 offset:1024
	ds_read_b128 v[166:169], v175 offset:2048
	ds_read_b128 v[178:181], v175 offset:3072
	ds_read_b128 v[182:185], v160
	ds_read_b128 v[186:189], v160 offset:1024
	ds_read_b128 v[190:193], v159
	ds_read_b128 v[194:197], v159 offset:1024
	ds_read_b128 v[198:201], v158
	ds_read_b128 v[202:205], v158 offset:1024
	ds_read_b128 v[206:209], v157
	ds_read_b128 v[210:213], v157 offset:1024
	global_load_lds_dwordx4 v[132:133], off
	v_lshl_add_u64 v[132:133], v[134:135], 0, s[30:31]
	s_mov_b32 m0, s41
	s_nop 0
	global_load_lds_dwordx4 v[132:133], off
	s_barrier
	s_waitcnt lgkmcnt(0)
	s_waitcnt lgkmcnt(0)
	v_mfma_f32_16x16x32_bf16 v[124:127], v[136:139], v[182:185], v[124:127]
	v_mfma_f32_16x16x32_bf16 v[120:123], v[166:169], v[182:185], v[120:123]
	v_mfma_f32_16x16x32_bf16 v[116:119], v[136:139], v[190:193], v[116:119]
	v_mfma_f32_16x16x32_bf16 v[108:111], v[136:139], v[198:201], v[108:111]
	v_mfma_f32_16x16x32_bf16 v[100:103], v[136:139], v[206:209], v[100:103]
	v_mfma_f32_16x16x32_bf16 v[124:127], v[140:143], v[186:189], v[124:127]
	v_mfma_f32_16x16x32_bf16 v[120:123], v[178:181], v[186:189], v[120:123]
	v_mfma_f32_16x16x32_bf16 v[116:119], v[140:143], v[194:197], v[116:119]
	v_mfma_f32_16x16x32_bf16 v[112:115], v[166:169], v[190:193], v[112:115]
	v_mfma_f32_16x16x32_bf16 v[108:111], v[140:143], v[202:205], v[108:111]
	v_mfma_f32_16x16x32_bf16 v[104:107], v[166:169], v[198:201], v[104:107]
	v_mfma_f32_16x16x32_bf16 v[100:103], v[140:143], v[210:213], v[100:103]
	v_mfma_f32_16x16x32_bf16 v[96:99], v[166:169], v[206:209], v[96:99]
	v_mfma_f32_16x16x32_bf16 v[132:135], v[178:181], v[194:197], v[112:115]
	v_mfma_f32_16x16x32_bf16 v[174:177], v[178:181], v[202:205], v[104:107]
	v_mfma_f32_16x16x32_bf16 v[214:217], v[178:181], v[210:213], v[96:99]
	s_barrier
	s_nop 2
	ds_read_b128 v[96:99], v172
	ds_read_b128 v[104:107], v172 offset:1024
	ds_read_b128 v[112:115], v172 offset:2048
	ds_read_b128 v[170:173], v172 offset:3072
	s_barrier
	s_waitcnt lgkmcnt(0)
	s_waitcnt lgkmcnt(0)
	v_mfma_f32_16x16x32_bf16 v[92:95], v[96:99], v[182:185], v[92:95]
	v_mfma_f32_16x16x32_bf16 v[88:91], v[112:115], v[182:185], v[88:91]
	v_mfma_f32_16x16x32_bf16 v[84:87], v[96:99], v[190:193], v[84:87]
	v_mfma_f32_16x16x32_bf16 v[76:79], v[96:99], v[198:201], v[76:79]
	v_mfma_f32_16x16x32_bf16 v[68:71], v[96:99], v[206:209], v[68:71]
	v_mfma_f32_16x16x32_bf16 v[92:95], v[104:107], v[186:189], v[92:95]
	v_mfma_f32_16x16x32_bf16 v[88:91], v[170:173], v[186:189], v[88:91]
	v_mfma_f32_16x16x32_bf16 v[84:87], v[104:107], v[194:197], v[84:87]
	v_mfma_f32_16x16x32_bf16 v[80:83], v[112:115], v[190:193], v[80:83]
	v_mfma_f32_16x16x32_bf16 v[76:79], v[104:107], v[202:205], v[76:79]
	v_mfma_f32_16x16x32_bf16 v[72:75], v[112:115], v[198:201], v[72:75]
	v_mfma_f32_16x16x32_bf16 v[68:71], v[104:107], v[210:213], v[68:71]
	v_mfma_f32_16x16x32_bf16 v[64:67], v[112:115], v[206:209], v[64:67]
	v_mfma_f32_16x16x32_bf16 v[182:185], v[170:173], v[194:197], v[80:83]
	v_mfma_f32_16x16x32_bf16 v[186:189], v[170:173], v[202:205], v[72:75]
	v_mfma_f32_16x16x32_bf16 v[190:193], v[170:173], v[210:213], v[64:67]
	s_barrier
	s_nop 2
	ds_read_b128 v[64:67], v160 offset:16384
	ds_read_b128 v[72:75], v160 offset:17408
	ds_read_b128 v[80:83], v159 offset:16384
	ds_read_b128 v[194:197], v159 offset:17408
	ds_read_b128 v[198:201], v158 offset:16384
	ds_read_b128 v[202:205], v158 offset:17408
	ds_read_b128 v[206:209], v157 offset:16384
	ds_read_b128 v[210:213], v157 offset:17408
	s_waitcnt vmcnt(4)
	s_barrier
	s_waitcnt lgkmcnt(0)
	s_waitcnt lgkmcnt(0)
	v_mfma_f32_16x16x32_bf16 v[60:63], v[136:139], v[64:67], v[60:63]
	v_mfma_f32_16x16x32_bf16 v[56:59], v[166:169], v[64:67], v[56:59]
	v_mfma_f32_16x16x32_bf16 v[52:55], v[136:139], v[80:83], v[52:55]
	v_mfma_f32_16x16x32_bf16 v[44:47], v[136:139], v[198:201], v[44:47]
	v_mfma_f32_16x16x32_bf16 v[36:39], v[136:139], v[206:209], v[36:39]
	v_mfma_f32_16x16x32_bf16 v[60:63], v[140:143], v[72:75], v[60:63]
	v_mfma_f32_16x16x32_bf16 v[56:59], v[178:181], v[72:75], v[56:59]
	v_mfma_f32_16x16x32_bf16 v[52:55], v[140:143], v[194:197], v[52:55]
	v_mfma_f32_16x16x32_bf16 v[48:51], v[166:169], v[80:83], v[48:51]
	v_mfma_f32_16x16x32_bf16 v[44:47], v[140:143], v[202:205], v[44:47]
	v_mfma_f32_16x16x32_bf16 v[40:43], v[166:169], v[198:201], v[40:43]
	v_mfma_f32_16x16x32_bf16 v[36:39], v[140:143], v[210:213], v[36:39]
	v_mfma_f32_16x16x32_bf16 v[32:35], v[166:169], v[206:209], v[32:35]
	v_mfma_f32_16x16x32_bf16 v[218:221], v[178:181], v[194:197], v[48:51]
	v_mfma_f32_16x16x32_bf16 v[222:225], v[178:181], v[202:205], v[40:43]
	v_mfma_f32_16x16x32_bf16 v[136:139], v[178:181], v[210:213], v[32:35]
	v_mfma_f32_16x16x32_bf16 v[28:31], v[96:99], v[64:67], v[28:31]
	v_mfma_f32_16x16x32_bf16 v[24:27], v[112:115], v[64:67], v[24:27]
	v_mfma_f32_16x16x32_bf16 v[20:23], v[96:99], v[80:83], v[20:23]
	v_mfma_f32_16x16x32_bf16 v[12:15], v[96:99], v[198:201], v[12:15]
	v_mfma_f32_16x16x32_bf16 v[4:7], v[96:99], v[206:209], v[4:7]
	v_mfma_f32_16x16x32_bf16 v[28:31], v[104:107], v[72:75], v[28:31]
	v_mfma_f32_16x16x32_bf16 v[24:27], v[170:173], v[72:75], v[24:27]
	v_mfma_f32_16x16x32_bf16 v[20:23], v[104:107], v[194:197], v[20:23]
	v_mfma_f32_16x16x32_bf16 v[16:19], v[112:115], v[80:83], v[16:19]
	v_mfma_f32_16x16x32_bf16 v[12:15], v[104:107], v[202:205], v[12:15]
	v_mfma_f32_16x16x32_bf16 v[8:11], v[112:115], v[198:201], v[8:11]
	v_mfma_f32_16x16x32_bf16 v[4:7], v[104:107], v[210:213], v[4:7]
	v_mfma_f32_16x16x32_bf16 v[0:3], v[112:115], v[206:209], v[0:3]
	v_mfma_f32_16x16x32_bf16 v[140:143], v[170:173], v[194:197], v[16:19]
	v_mfma_f32_16x16x32_bf16 v[166:169], v[170:173], v[202:205], v[8:11]
	v_mfma_f32_16x16x32_bf16 v[170:173], v[170:173], v[210:213], v[0:3]
	s_barrier
	s_nop 2
	ds_read_b128 v[0:3], v164
	ds_read_b128 v[8:11], v164 offset:1024
	ds_read_b128 v[16:19], v164 offset:2048
	ds_read_b128 v[162:165], v164 offset:3072
	ds_read_b128 v[32:35], v160 offset:32768
	ds_read_b128 v[40:43], v160 offset:33792
	ds_read_b128 v[48:51], v159 offset:32768
	ds_read_b128 v[64:67], v159 offset:33792
	ds_read_b128 v[178:181], v158 offset:32768
	ds_read_b128 v[194:197], v158 offset:33792
	ds_read_b128 v[198:201], v157 offset:32768
	ds_read_b128 v[202:205], v157 offset:33792
	s_waitcnt vmcnt(2)
	s_barrier
	s_waitcnt lgkmcnt(0)
	s_waitcnt lgkmcnt(0)
	v_mfma_f32_16x16x32_bf16 v[72:75], v[0:3], v[32:35], v[124:127]
	v_mfma_f32_16x16x32_bf16 v[124:127], v[8:11], v[40:43], v[72:75]
	v_mfma_f32_16x16x32_bf16 v[72:75], v[16:19], v[32:35], v[120:123]
	v_mfma_f32_16x16x32_bf16 v[120:123], v[162:165], v[40:43], v[72:75]
	v_mfma_f32_16x16x32_bf16 v[72:75], v[0:3], v[48:51], v[116:119]
	v_mfma_f32_16x16x32_bf16 v[112:115], v[8:11], v[64:67], v[72:75]
	v_mfma_f32_16x16x32_bf16 v[72:75], v[16:19], v[48:51], v[132:135]
	v_mfma_f32_16x16x32_bf16 v[116:119], v[162:165], v[64:67], v[72:75]
	v_mfma_f32_16x16x32_bf16 v[72:75], v[0:3], v[178:181], v[108:111]
	v_mfma_f32_16x16x32_bf16 v[104:107], v[8:11], v[194:197], v[72:75]
	v_mfma_f32_16x16x32_bf16 v[72:75], v[16:19], v[178:181], v[174:177]
	v_mfma_f32_16x16x32_bf16 v[108:111], v[162:165], v[194:197], v[72:75]
	v_mfma_f32_16x16x32_bf16 v[72:75], v[0:3], v[198:201], v[100:103]
	v_mfma_f32_16x16x32_bf16 v[96:99], v[8:11], v[202:205], v[72:75]
	v_mfma_f32_16x16x32_bf16 v[72:75], v[16:19], v[198:201], v[214:217]
	v_mfma_f32_16x16x32_bf16 v[100:103], v[162:165], v[202:205], v[72:75]
	s_barrier
	ds_read_b128 v[132:135], v161
	ds_read_b128 v[174:177], v161 offset:1024
	ds_read_b128 v[206:209], v161 offset:2048
	ds_read_b128 v[210:213], v161 offset:3072
	s_waitcnt vmcnt(0)
	s_barrier
	s_waitcnt lgkmcnt(0)
	s_waitcnt lgkmcnt(0)
	v_mfma_f32_16x16x32_bf16 v[72:75], v[132:135], v[32:35], v[92:95]
	v_mfma_f32_16x16x32_bf16 v[32:35], v[206:209], v[32:35], v[88:91]
	v_mfma_f32_16x16x32_bf16 v[88:91], v[210:213], v[40:43], v[32:35]
	v_mfma_f32_16x16x32_bf16 v[32:35], v[132:135], v[48:51], v[84:87]
	v_mfma_f32_16x16x32_bf16 v[80:83], v[174:177], v[64:67], v[32:35]
	v_mfma_f32_16x16x32_bf16 v[32:35], v[206:209], v[48:51], v[182:185]
	v_mfma_f32_16x16x32_bf16 v[84:87], v[210:213], v[64:67], v[32:35]
	v_mfma_f32_16x16x32_bf16 v[32:35], v[132:135], v[178:181], v[76:79]
	v_mfma_f32_16x16x32_bf16 v[92:95], v[174:177], v[40:43], v[72:75]
	v_mfma_f32_16x16x32_bf16 v[72:75], v[174:177], v[194:197], v[32:35]
	v_mfma_f32_16x16x32_bf16 v[32:35], v[206:209], v[178:181], v[186:189]
	v_mfma_f32_16x16x32_bf16 v[76:79], v[210:213], v[194:197], v[32:35]
	v_mfma_f32_16x16x32_bf16 v[32:35], v[132:135], v[198:201], v[68:71]
	v_mfma_f32_16x16x32_bf16 v[64:67], v[174:177], v[202:205], v[32:35]
	v_mfma_f32_16x16x32_bf16 v[32:35], v[206:209], v[198:201], v[190:193]
	v_mfma_f32_16x16x32_bf16 v[68:71], v[210:213], v[202:205], v[32:35]
	s_barrier
	ds_read_b128 v[178:181], v160 offset:49152
	ds_read_b128 v[182:185], v160 offset:50176
	ds_read_b128 v[186:189], v159 offset:49152
	ds_read_b128 v[190:193], v159 offset:50176
	ds_read_b128 v[194:197], v158 offset:49152
	ds_read_b128 v[158:161], v158 offset:50176
	ds_read_b128 v[198:201], v157 offset:49152
	ds_read_b128 v[202:205], v157 offset:50176
	s_barrier
	s_waitcnt lgkmcnt(0)
	s_waitcnt lgkmcnt(0)
	v_mfma_f32_16x16x32_bf16 v[32:35], v[0:3], v[178:181], v[60:63]
	v_mfma_f32_16x16x32_bf16 v[60:63], v[8:11], v[182:185], v[32:35]
	v_mfma_f32_16x16x32_bf16 v[32:35], v[16:19], v[178:181], v[56:59]
	v_mfma_f32_16x16x32_bf16 v[56:59], v[162:165], v[182:185], v[32:35]
	v_mfma_f32_16x16x32_bf16 v[32:35], v[0:3], v[186:189], v[52:55]
	v_mfma_f32_16x16x32_bf16 v[48:51], v[8:11], v[190:193], v[32:35]
	v_mfma_f32_16x16x32_bf16 v[32:35], v[16:19], v[186:189], v[218:221]
	v_mfma_f32_16x16x32_bf16 v[52:55], v[162:165], v[190:193], v[32:35]
	v_mfma_f32_16x16x32_bf16 v[32:35], v[0:3], v[194:197], v[44:47]
	v_mfma_f32_16x16x32_bf16 v[40:43], v[8:11], v[158:161], v[32:35]
	v_mfma_f32_16x16x32_bf16 v[32:35], v[16:19], v[194:197], v[222:225]
	v_mfma_f32_16x16x32_bf16 v[0:3], v[0:3], v[198:201], v[36:39]
	v_mfma_f32_16x16x32_bf16 v[44:47], v[162:165], v[158:161], v[32:35]
	v_mfma_f32_16x16x32_bf16 v[32:35], v[8:11], v[202:205], v[0:3]
	v_mfma_f32_16x16x32_bf16 v[0:3], v[16:19], v[198:201], v[136:139]
	v_mfma_f32_16x16x32_bf16 v[36:39], v[162:165], v[202:205], v[0:3]
	v_mfma_f32_16x16x32_bf16 v[0:3], v[132:135], v[178:181], v[28:31]
	v_mfma_f32_16x16x32_bf16 v[28:31], v[174:177], v[182:185], v[0:3]
	v_mfma_f32_16x16x32_bf16 v[0:3], v[206:209], v[178:181], v[24:27]
	v_mfma_f32_16x16x32_bf16 v[24:27], v[210:213], v[182:185], v[0:3]
	v_mfma_f32_16x16x32_bf16 v[0:3], v[132:135], v[186:189], v[20:23]
	v_mfma_f32_16x16x32_bf16 v[16:19], v[174:177], v[190:193], v[0:3]
	v_mfma_f32_16x16x32_bf16 v[0:3], v[206:209], v[186:189], v[140:143]
	v_mfma_f32_16x16x32_bf16 v[20:23], v[210:213], v[190:193], v[0:3]
	v_mfma_f32_16x16x32_bf16 v[0:3], v[132:135], v[194:197], v[12:15]
	v_mfma_f32_16x16x32_bf16 v[8:11], v[174:177], v[158:161], v[0:3]
	v_mfma_f32_16x16x32_bf16 v[0:3], v[206:209], v[194:197], v[166:169]
	v_mfma_f32_16x16x32_bf16 v[12:15], v[210:213], v[158:161], v[0:3]
	v_mfma_f32_16x16x32_bf16 v[0:3], v[132:135], v[198:201], v[4:7]
	v_mfma_f32_16x16x32_bf16 v[4:7], v[206:209], v[198:201], v[170:173]
	v_mfma_f32_16x16x32_bf16 v[0:3], v[174:177], v[202:205], v[0:3]
	v_mfma_f32_16x16x32_bf16 v[4:7], v[210:213], v[202:205], v[4:7]
	v_cmp_gt_u32_e32 vcc, s57, v130
	s_barrier
	s_and_saveexec_b64 s[44:45], vcc
	s_cbranch_execz .LBB0_1682
	s_barrier
	s_branch .LBB0_1682

.LBB0_1806:
	ds_read_b128 v[178:181], v174
	ds_read_b128 v[182:185], v174 offset:1024
	ds_read_b128 v[186:189], v174 offset:2048
	ds_read_b128 v[190:193], v174 offset:3072
	v_add_u32_e32 v175, 0xc000, v161
	v_lshl_add_u64 v[242:243], s[4:5], 0, v[136:137]
	v_readfirstlane_b32 s38, v175
	v_lshl_add_u64 v[176:177], v[242:243], 0, s[10:11]
	s_mov_b32 m0, s38
	ds_read_b128 v[194:197], v159
	ds_read_b128 v[198:201], v159 offset:1024
	ds_read_b128 v[202:205], v158
	ds_read_b128 v[206:209], v158 offset:1024
	ds_read_b128 v[210:213], v157
	ds_read_b128 v[214:217], v157 offset:1024
	ds_read_b128 v[218:221], v156
	ds_read_b128 v[222:225], v156 offset:1024
	global_load_lds_dwordx4 v[176:177], off
	v_add_u32_e32 v176, 0xe000, v161
	v_lshl_add_u64 v[244:245], s[4:5], 0, v[134:135]
	v_readfirstlane_b32 s38, v176
	v_lshl_add_u64 v[226:227], v[244:245], 0, s[10:11]
	s_mov_b32 m0, s38
	s_nop 0
	global_load_lds_dwordx4 v[226:227], off
	s_waitcnt lgkmcnt(8)
	s_barrier
	s_waitcnt lgkmcnt(0)
	s_waitcnt lgkmcnt(0)
	v_mfma_f32_16x16x32_bf16 v[124:127], v[178:181], v[194:197], v[124:127]
	v_mfma_f32_16x16x32_bf16 v[120:123], v[186:189], v[194:197], v[120:123]
	v_mfma_f32_16x16x32_bf16 v[116:119], v[178:181], v[202:205], v[116:119]
	v_mfma_f32_16x16x32_bf16 v[112:115], v[186:189], v[202:205], v[112:115]
	v_mfma_f32_16x16x32_bf16 v[108:111], v[178:181], v[210:213], v[108:111]
	v_mfma_f32_16x16x32_bf16 v[104:107], v[186:189], v[210:213], v[104:107]
	v_mfma_f32_16x16x32_bf16 v[100:103], v[178:181], v[218:221], v[100:103]
	v_mfma_f32_16x16x32_bf16 v[96:99], v[186:189], v[218:221], v[96:99]
	v_mfma_f32_16x16x32_bf16 v[124:127], v[182:185], v[198:201], v[124:127]
	v_mfma_f32_16x16x32_bf16 v[120:123], v[190:193], v[198:201], v[120:123]
	v_mfma_f32_16x16x32_bf16 v[116:119], v[182:185], v[206:209], v[116:119]
	v_mfma_f32_16x16x32_bf16 v[112:115], v[190:193], v[206:209], v[112:115]
	v_mfma_f32_16x16x32_bf16 v[108:111], v[182:185], v[214:217], v[108:111]
	v_mfma_f32_16x16x32_bf16 v[104:107], v[190:193], v[214:217], v[104:107]
	v_mfma_f32_16x16x32_bf16 v[100:103], v[182:185], v[222:225], v[100:103]
	v_mfma_f32_16x16x32_bf16 v[96:99], v[190:193], v[222:225], v[96:99]
	s_barrier
	v_lshl_add_u64 v[246:247], s[4:5], 0, v[140:141]
	v_readfirstlane_b32 s38, v155
	v_lshl_add_u64 v[248:249], v[246:247], 0, s[12:13]
	s_mov_b32 m0, s38
	v_add_u32_e32 v177, 0x2000, v155
	ds_read_b128 v[226:229], v171
	ds_read_b128 v[230:233], v171 offset:1024
	ds_read_b128 v[234:237], v171 offset:2048
	ds_read_b128 v[238:241], v171 offset:3072
	global_load_lds_dwordx4 v[248:249], off
	v_lshl_add_u64 v[248:249], s[4:5], 0, v[138:139]
	v_readfirstlane_b32 s38, v177
	v_lshl_add_u64 v[250:251], v[248:249], 0, s[12:13]
	s_mov_b32 m0, s38
	s_nop 0
	global_load_lds_dwordx4 v[250:251], off
	s_barrier
	s_waitcnt lgkmcnt(0)
	s_waitcnt lgkmcnt(0)
	v_mfma_f32_16x16x32_bf16 v[92:95], v[226:229], v[194:197], v[92:95]
	v_mfma_f32_16x16x32_bf16 v[88:91], v[234:237], v[194:197], v[88:91]
	v_mfma_f32_16x16x32_bf16 v[84:87], v[226:229], v[202:205], v[84:87]
	v_mfma_f32_16x16x32_bf16 v[80:83], v[234:237], v[202:205], v[80:83]
	v_mfma_f32_16x16x32_bf16 v[76:79], v[226:229], v[210:213], v[76:79]
	v_mfma_f32_16x16x32_bf16 v[72:75], v[234:237], v[210:213], v[72:75]
	v_mfma_f32_16x16x32_bf16 v[68:71], v[226:229], v[218:221], v[68:71]
	v_mfma_f32_16x16x32_bf16 v[64:67], v[234:237], v[218:221], v[64:67]
	v_mfma_f32_16x16x32_bf16 v[92:95], v[230:233], v[198:201], v[92:95]
	v_mfma_f32_16x16x32_bf16 v[88:91], v[238:241], v[198:201], v[88:91]
	v_mfma_f32_16x16x32_bf16 v[84:87], v[230:233], v[206:209], v[84:87]
	v_mfma_f32_16x16x32_bf16 v[80:83], v[238:241], v[206:209], v[80:83]
	v_mfma_f32_16x16x32_bf16 v[76:79], v[230:233], v[214:217], v[76:79]
	v_mfma_f32_16x16x32_bf16 v[72:75], v[238:241], v[214:217], v[72:75]
	v_mfma_f32_16x16x32_bf16 v[68:71], v[230:233], v[222:225], v[68:71]
	v_mfma_f32_16x16x32_bf16 v[64:67], v[238:241], v[222:225], v[64:67]
	v_readfirstlane_b32 s38, v161
	v_lshl_add_u64 v[250:251], v[242:243], 0, s[14:15]
	s_mov_b32 m0, s38
	v_readfirstlane_b32 s38, v162
	s_barrier
	ds_read_b128 v[194:197], v159 offset:16384
	ds_read_b128 v[198:201], v159 offset:17408
	ds_read_b128 v[202:205], v158 offset:16384
	ds_read_b128 v[206:209], v158 offset:17408
	ds_read_b128 v[210:213], v157 offset:16384
	ds_read_b128 v[214:217], v157 offset:17408
	ds_read_b128 v[218:221], v156 offset:16384
	ds_read_b128 v[222:225], v156 offset:17408
	global_load_lds_dwordx4 v[250:251], off
	v_lshl_add_u64 v[250:251], v[244:245], 0, s[14:15]
	s_mov_b32 m0, s38
	s_nop 0
	global_load_lds_dwordx4 v[250:251], off
	s_barrier
	s_waitcnt lgkmcnt(0)
	s_waitcnt lgkmcnt(0)
	v_mfma_f32_16x16x32_bf16 v[60:63], v[178:181], v[194:197], v[60:63]
	v_mfma_f32_16x16x32_bf16 v[56:59], v[186:189], v[194:197], v[56:59]
	v_mfma_f32_16x16x32_bf16 v[52:55], v[178:181], v[202:205], v[52:55]
	v_mfma_f32_16x16x32_bf16 v[48:51], v[186:189], v[202:205], v[48:51]
	v_mfma_f32_16x16x32_bf16 v[44:47], v[178:181], v[210:213], v[44:47]
	v_mfma_f32_16x16x32_bf16 v[40:43], v[186:189], v[210:213], v[40:43]
	v_mfma_f32_16x16x32_bf16 v[36:39], v[178:181], v[218:221], v[36:39]
	v_mfma_f32_16x16x32_bf16 v[32:35], v[186:189], v[218:221], v[32:35]
	v_mfma_f32_16x16x32_bf16 v[60:63], v[182:185], v[198:201], v[60:63]
	v_mfma_f32_16x16x32_bf16 v[56:59], v[190:193], v[198:201], v[56:59]
	v_mfma_f32_16x16x32_bf16 v[52:55], v[182:185], v[206:209], v[52:55]
	v_mfma_f32_16x16x32_bf16 v[48:51], v[190:193], v[206:209], v[48:51]
	v_mfma_f32_16x16x32_bf16 v[44:47], v[182:185], v[214:217], v[44:47]
	v_mfma_f32_16x16x32_bf16 v[40:43], v[190:193], v[214:217], v[40:43]
	v_mfma_f32_16x16x32_bf16 v[36:39], v[182:185], v[222:225], v[36:39]
	v_mfma_f32_16x16x32_bf16 v[32:35], v[190:193], v[222:225], v[32:35]
	s_barrier
	v_readfirstlane_b32 s38, v164
	v_add_u32_e32 v177, 0x2000, v164
	v_lshl_add_u64 v[178:179], v[246:247], 0, s[16:17]
	s_mov_b32 m0, s38
	v_readfirstlane_b32 s38, v177
	global_load_lds_dwordx4 v[178:179], off
	v_lshl_add_u64 v[178:179], v[248:249], 0, s[16:17]
	s_mov_b32 m0, s38
	s_nop 0
	global_load_lds_dwordx4 v[178:179], off
	s_waitcnt vmcnt(6)
	s_barrier
	v_mfma_f32_16x16x32_bf16 v[28:31], v[226:229], v[194:197], v[28:31]
	v_mfma_f32_16x16x32_bf16 v[24:27], v[234:237], v[194:197], v[24:27]
	v_mfma_f32_16x16x32_bf16 v[20:23], v[226:229], v[202:205], v[20:23]
	v_mfma_f32_16x16x32_bf16 v[16:19], v[234:237], v[202:205], v[16:19]
	v_mfma_f32_16x16x32_bf16 v[12:15], v[226:229], v[210:213], v[12:15]
	v_mfma_f32_16x16x32_bf16 v[8:11], v[234:237], v[210:213], v[8:11]
	v_mfma_f32_16x16x32_bf16 v[4:7], v[226:229], v[218:221], v[4:7]
	v_mfma_f32_16x16x32_bf16 v[0:3], v[234:237], v[218:221], v[0:3]
	v_mfma_f32_16x16x32_bf16 v[28:31], v[230:233], v[198:201], v[28:31]
	v_mfma_f32_16x16x32_bf16 v[24:27], v[238:241], v[198:201], v[24:27]
	v_mfma_f32_16x16x32_bf16 v[20:23], v[230:233], v[206:209], v[20:23]
	v_mfma_f32_16x16x32_bf16 v[16:19], v[238:241], v[206:209], v[16:19]
	v_mfma_f32_16x16x32_bf16 v[12:15], v[230:233], v[214:217], v[12:15]
	v_mfma_f32_16x16x32_bf16 v[8:11], v[238:241], v[214:217], v[8:11]
	v_mfma_f32_16x16x32_bf16 v[4:7], v[230:233], v[222:225], v[4:7]
	v_mfma_f32_16x16x32_bf16 v[0:3], v[238:241], v[222:225], v[0:3]
	s_barrier
	ds_read_b128 v[178:181], v163
	ds_read_b128 v[182:185], v163 offset:1024
	ds_read_b128 v[186:189], v163 offset:2048
	ds_read_b128 v[190:193], v163 offset:3072
	v_readfirstlane_b32 s38, v165
	v_lshl_add_u64 v[226:227], v[242:243], 0, s[18:19]
	s_mov_b32 m0, s38
	v_readfirstlane_b32 s38, v166
	ds_read_b128 v[194:197], v159 offset:32768
	ds_read_b128 v[198:201], v159 offset:33792
	ds_read_b128 v[202:205], v158 offset:32768
	ds_read_b128 v[206:209], v158 offset:33792
	ds_read_b128 v[210:213], v157 offset:32768
	ds_read_b128 v[214:217], v157 offset:33792
	ds_read_b128 v[218:221], v156 offset:32768
	ds_read_b128 v[222:225], v156 offset:33792
	global_load_lds_dwordx4 v[226:227], off
	v_lshl_add_u64 v[226:227], v[244:245], 0, s[18:19]
	s_mov_b32 m0, s38
	s_nop 0
	global_load_lds_dwordx4 v[226:227], off
	s_waitcnt lgkmcnt(8)
	s_barrier
	s_waitcnt lgkmcnt(0)
	s_waitcnt lgkmcnt(0)
	v_mfma_f32_16x16x32_bf16 v[124:127], v[178:181], v[194:197], v[124:127]
	v_mfma_f32_16x16x32_bf16 v[120:123], v[186:189], v[194:197], v[120:123]
	v_mfma_f32_16x16x32_bf16 v[116:119], v[178:181], v[202:205], v[116:119]
	v_mfma_f32_16x16x32_bf16 v[112:115], v[186:189], v[202:205], v[112:115]
	v_mfma_f32_16x16x32_bf16 v[108:111], v[178:181], v[210:213], v[108:111]
	v_mfma_f32_16x16x32_bf16 v[104:107], v[186:189], v[210:213], v[104:107]
	v_mfma_f32_16x16x32_bf16 v[100:103], v[178:181], v[218:221], v[100:103]
	v_mfma_f32_16x16x32_bf16 v[96:99], v[186:189], v[218:221], v[96:99]
	v_mfma_f32_16x16x32_bf16 v[124:127], v[182:185], v[198:201], v[124:127]
	v_mfma_f32_16x16x32_bf16 v[120:123], v[190:193], v[198:201], v[120:123]
	v_mfma_f32_16x16x32_bf16 v[116:119], v[182:185], v[206:209], v[116:119]
	v_mfma_f32_16x16x32_bf16 v[112:115], v[190:193], v[206:209], v[112:115]
	v_mfma_f32_16x16x32_bf16 v[108:111], v[182:185], v[214:217], v[108:111]
	v_mfma_f32_16x16x32_bf16 v[104:107], v[190:193], v[214:217], v[104:107]
	v_mfma_f32_16x16x32_bf16 v[100:103], v[182:185], v[222:225], v[100:103]
	v_mfma_f32_16x16x32_bf16 v[96:99], v[190:193], v[222:225], v[96:99]
	s_barrier
	v_readfirstlane_b32 s38, v167
	v_lshl_add_u64 v[250:251], v[246:247], 0, s[20:21]
	s_mov_b32 m0, s38
	v_readfirstlane_b32 s38, v168
	ds_read_b128 v[226:229], v160
	ds_read_b128 v[230:233], v160 offset:1024
	ds_read_b128 v[234:237], v160 offset:2048
	ds_read_b128 v[238:241], v160 offset:3072
	global_load_lds_dwordx4 v[250:251], off
	v_lshl_add_u64 v[250:251], v[248:249], 0, s[20:21]
	s_mov_b32 m0, s38
	s_nop 0
	global_load_lds_dwordx4 v[250:251], off
	s_barrier
	s_waitcnt lgkmcnt(0)
	s_waitcnt lgkmcnt(0)
	v_mfma_f32_16x16x32_bf16 v[92:95], v[226:229], v[194:197], v[92:95]
	v_mfma_f32_16x16x32_bf16 v[88:91], v[234:237], v[194:197], v[88:91]
	v_mfma_f32_16x16x32_bf16 v[84:87], v[226:229], v[202:205], v[84:87]
	v_mfma_f32_16x16x32_bf16 v[80:83], v[234:237], v[202:205], v[80:83]
	v_mfma_f32_16x16x32_bf16 v[76:79], v[226:229], v[210:213], v[76:79]
	v_mfma_f32_16x16x32_bf16 v[72:75], v[234:237], v[210:213], v[72:75]
	v_mfma_f32_16x16x32_bf16 v[68:71], v[226:229], v[218:221], v[68:71]
	v_mfma_f32_16x16x32_bf16 v[64:67], v[234:237], v[218:221], v[64:67]
	v_mfma_f32_16x16x32_bf16 v[92:95], v[230:233], v[198:201], v[92:95]
	v_mfma_f32_16x16x32_bf16 v[88:91], v[238:241], v[198:201], v[88:91]
	v_mfma_f32_16x16x32_bf16 v[84:87], v[230:233], v[206:209], v[84:87]
	v_mfma_f32_16x16x32_bf16 v[80:83], v[238:241], v[206:209], v[80:83]
	v_mfma_f32_16x16x32_bf16 v[76:79], v[230:233], v[214:217], v[76:79]
	v_mfma_f32_16x16x32_bf16 v[72:75], v[238:241], v[214:217], v[72:75]
	v_mfma_f32_16x16x32_bf16 v[68:71], v[230:233], v[222:225], v[68:71]
	v_mfma_f32_16x16x32_bf16 v[64:67], v[238:241], v[222:225], v[64:67]
	v_readfirstlane_b32 s38, v169
	v_lshl_add_u64 v[242:243], v[242:243], 0, s[22:23]
	s_mov_b32 m0, s38
	v_readfirstlane_b32 s38, v170
	s_barrier
	ds_read_b128 v[194:197], v159 offset:49152
	ds_read_b128 v[198:201], v159 offset:50176
	ds_read_b128 v[202:205], v158 offset:49152
	ds_read_b128 v[206:209], v158 offset:50176
	ds_read_b128 v[210:213], v157 offset:49152
	ds_read_b128 v[214:217], v157 offset:50176
	ds_read_b128 v[218:221], v156 offset:49152
	ds_read_b128 v[222:225], v156 offset:50176
	global_load_lds_dwordx4 v[242:243], off
	v_lshl_add_u64 v[242:243], v[244:245], 0, s[22:23]
	s_mov_b32 m0, s38
	s_nop 0
	global_load_lds_dwordx4 v[242:243], off
	s_barrier
	s_waitcnt lgkmcnt(0)
	s_waitcnt lgkmcnt(0)
	v_mfma_f32_16x16x32_bf16 v[60:63], v[178:181], v[194:197], v[60:63]
	v_mfma_f32_16x16x32_bf16 v[56:59], v[186:189], v[194:197], v[56:59]
	v_mfma_f32_16x16x32_bf16 v[52:55], v[178:181], v[202:205], v[52:55]
	v_mfma_f32_16x16x32_bf16 v[48:51], v[186:189], v[202:205], v[48:51]
	v_mfma_f32_16x16x32_bf16 v[44:47], v[178:181], v[210:213], v[44:47]
	v_mfma_f32_16x16x32_bf16 v[40:43], v[186:189], v[210:213], v[40:43]
	v_mfma_f32_16x16x32_bf16 v[36:39], v[178:181], v[218:221], v[36:39]
	v_mfma_f32_16x16x32_bf16 v[32:35], v[186:189], v[218:221], v[32:35]
	v_mfma_f32_16x16x32_bf16 v[60:63], v[182:185], v[198:201], v[60:63]
	v_mfma_f32_16x16x32_bf16 v[56:59], v[190:193], v[198:201], v[56:59]
	v_mfma_f32_16x16x32_bf16 v[52:55], v[182:185], v[206:209], v[52:55]
	v_mfma_f32_16x16x32_bf16 v[48:51], v[190:193], v[206:209], v[48:51]
	v_mfma_f32_16x16x32_bf16 v[44:47], v[182:185], v[214:217], v[44:47]
	v_mfma_f32_16x16x32_bf16 v[40:43], v[190:193], v[214:217], v[40:43]
	v_mfma_f32_16x16x32_bf16 v[36:39], v[182:185], v[222:225], v[36:39]
	v_mfma_f32_16x16x32_bf16 v[32:35], v[190:193], v[222:225], v[32:35]
	s_barrier
	v_readfirstlane_b32 s38, v172
	v_lshl_add_u64 v[178:179], v[246:247], 0, s[24:25]
	s_mov_b32 m0, s38
	v_readfirstlane_b32 s38, v173
	global_load_lds_dwordx4 v[178:179], off
	v_lshl_add_u64 v[178:179], v[248:249], 0, s[24:25]
	s_mov_b32 m0, s38
	s_nop 0
	global_load_lds_dwordx4 v[178:179], off
	s_waitcnt vmcnt(6)
	s_barrier
	v_mfma_f32_16x16x32_bf16 v[28:31], v[226:229], v[194:197], v[28:31]
	v_mfma_f32_16x16x32_bf16 v[24:27], v[234:237], v[194:197], v[24:27]
	v_mfma_f32_16x16x32_bf16 v[20:23], v[226:229], v[202:205], v[20:23]
	v_mfma_f32_16x16x32_bf16 v[16:19], v[234:237], v[202:205], v[16:19]
	v_mfma_f32_16x16x32_bf16 v[12:15], v[226:229], v[210:213], v[12:15]
	v_mfma_f32_16x16x32_bf16 v[8:11], v[234:237], v[210:213], v[8:11]
	v_mfma_f32_16x16x32_bf16 v[4:7], v[226:229], v[218:221], v[4:7]
	v_mfma_f32_16x16x32_bf16 v[0:3], v[234:237], v[218:221], v[0:3]
	v_mfma_f32_16x16x32_bf16 v[28:31], v[230:233], v[198:201], v[28:31]
	v_mfma_f32_16x16x32_bf16 v[24:27], v[238:241], v[198:201], v[24:27]
	v_mfma_f32_16x16x32_bf16 v[20:23], v[230:233], v[206:209], v[20:23]
	v_mfma_f32_16x16x32_bf16 v[16:19], v[238:241], v[206:209], v[16:19]
	v_mfma_f32_16x16x32_bf16 v[12:15], v[230:233], v[214:217], v[12:15]
	v_mfma_f32_16x16x32_bf16 v[8:11], v[238:241], v[214:217], v[8:11]
	v_mfma_f32_16x16x32_bf16 v[4:7], v[230:233], v[222:225], v[4:7]
	v_mfma_f32_16x16x32_bf16 v[0:3], v[238:241], v[222:225], v[0:3]
	s_add_i32 s31, s31, 2
	v_lshl_add_u64 v[134:135], v[134:135], 0, s[26:27]
	v_lshl_add_u64 v[136:137], v[136:137], 0, s[26:27]
	v_lshl_add_u64 v[138:139], v[138:139], 0, s[26:27]
	s_cmp_lt_u32 s31, 12
	v_lshl_add_u64 v[140:141], v[140:141], 0, s[26:27]
	s_barrier
	s_cbranch_scc1 .LBB0_1806
	v_readfirstlane_b32 s31, v175
	v_lshl_add_u64 v[130:131], v[130:131], 0, s[28:29]
	s_mov_b32 m0, s31
	v_readfirstlane_b32 s31, v176
	ds_read_b128 v[134:137], v174
	ds_read_b128 v[138:141], v174 offset:1024
	ds_read_b128 v[164:167], v174 offset:2048
	ds_read_b128 v[178:181], v174 offset:3072
	ds_read_b128 v[182:185], v159
	ds_read_b128 v[186:189], v159 offset:1024
	ds_read_b128 v[190:193], v158
	ds_read_b128 v[194:197], v158 offset:1024
	ds_read_b128 v[198:201], v157
	ds_read_b128 v[202:205], v157 offset:1024
	ds_read_b128 v[206:209], v156
	ds_read_b128 v[210:213], v156 offset:1024
	global_load_lds_dwordx4 v[130:131], off
	v_lshl_add_u64 v[130:131], v[132:133], 0, s[28:29]
	s_mov_b32 m0, s31
	s_nop 0
	global_load_lds_dwordx4 v[130:131], off
	s_barrier
	s_waitcnt lgkmcnt(0)
	s_waitcnt lgkmcnt(0)
	v_mfma_f32_16x16x32_bf16 v[124:127], v[134:137], v[182:185], v[124:127]
	v_mfma_f32_16x16x32_bf16 v[120:123], v[164:167], v[182:185], v[120:123]
	v_mfma_f32_16x16x32_bf16 v[116:119], v[134:137], v[190:193], v[116:119]
	v_mfma_f32_16x16x32_bf16 v[112:115], v[164:167], v[190:193], v[112:115]
	v_mfma_f32_16x16x32_bf16 v[108:111], v[134:137], v[198:201], v[108:111]
	v_mfma_f32_16x16x32_bf16 v[104:107], v[164:167], v[198:201], v[104:107]
	v_mfma_f32_16x16x32_bf16 v[100:103], v[134:137], v[206:209], v[100:103]
	v_mfma_f32_16x16x32_bf16 v[96:99], v[164:167], v[206:209], v[96:99]
	v_mfma_f32_16x16x32_bf16 v[124:127], v[138:141], v[186:189], v[124:127]
	v_mfma_f32_16x16x32_bf16 v[120:123], v[178:181], v[186:189], v[120:123]
	v_mfma_f32_16x16x32_bf16 v[116:119], v[138:141], v[194:197], v[116:119]
	v_mfma_f32_16x16x32_bf16 v[112:115], v[178:181], v[194:197], v[112:115]
	v_mfma_f32_16x16x32_bf16 v[108:111], v[138:141], v[202:205], v[108:111]
	v_mfma_f32_16x16x32_bf16 v[104:107], v[178:181], v[202:205], v[104:107]
	v_mfma_f32_16x16x32_bf16 v[100:103], v[138:141], v[210:213], v[100:103]
	v_mfma_f32_16x16x32_bf16 v[96:99], v[178:181], v[210:213], v[96:99]
	s_barrier
	ds_read_b128 v[130:133], v171
	ds_read_b128 v[172:175], v171 offset:1024
	ds_read_b128 v[214:217], v171 offset:2048
	ds_read_b128 v[168:171], v171 offset:3072
	s_barrier
	s_waitcnt lgkmcnt(0)
	s_waitcnt lgkmcnt(0)
	v_mfma_f32_16x16x32_bf16 v[92:95], v[130:133], v[182:185], v[92:95]
	v_mfma_f32_16x16x32_bf16 v[88:91], v[214:217], v[182:185], v[88:91]
	v_mfma_f32_16x16x32_bf16 v[84:87], v[130:133], v[190:193], v[84:87]
	v_mfma_f32_16x16x32_bf16 v[80:83], v[214:217], v[190:193], v[80:83]
	v_mfma_f32_16x16x32_bf16 v[76:79], v[130:133], v[198:201], v[76:79]
	v_mfma_f32_16x16x32_bf16 v[72:75], v[214:217], v[198:201], v[72:75]
	v_mfma_f32_16x16x32_bf16 v[68:71], v[130:133], v[206:209], v[68:71]
	v_mfma_f32_16x16x32_bf16 v[64:67], v[214:217], v[206:209], v[64:67]
	v_mfma_f32_16x16x32_bf16 v[92:95], v[172:175], v[186:189], v[92:95]
	v_mfma_f32_16x16x32_bf16 v[88:91], v[168:171], v[186:189], v[88:91]
	v_mfma_f32_16x16x32_bf16 v[84:87], v[172:175], v[194:197], v[84:87]
	v_mfma_f32_16x16x32_bf16 v[80:83], v[168:171], v[194:197], v[80:83]
	v_mfma_f32_16x16x32_bf16 v[76:79], v[172:175], v[202:205], v[76:79]
	v_mfma_f32_16x16x32_bf16 v[72:75], v[168:171], v[202:205], v[72:75]
	v_mfma_f32_16x16x32_bf16 v[68:71], v[172:175], v[210:213], v[68:71]
	v_mfma_f32_16x16x32_bf16 v[64:67], v[168:171], v[210:213], v[64:67]
	s_barrier
	ds_read_b128 v[182:185], v159 offset:16384
	ds_read_b128 v[186:189], v159 offset:17408
	ds_read_b128 v[190:193], v158 offset:16384
	ds_read_b128 v[194:197], v158 offset:17408
	ds_read_b128 v[198:201], v157 offset:16384
	ds_read_b128 v[202:205], v157 offset:17408
	ds_read_b128 v[206:209], v156 offset:16384
	ds_read_b128 v[210:213], v156 offset:17408
	s_waitcnt vmcnt(4)
	s_barrier
	s_waitcnt lgkmcnt(0)
	s_waitcnt lgkmcnt(0)
	v_mfma_f32_16x16x32_bf16 v[60:63], v[134:137], v[182:185], v[60:63]
	v_mfma_f32_16x16x32_bf16 v[56:59], v[164:167], v[182:185], v[56:59]
	v_mfma_f32_16x16x32_bf16 v[52:55], v[134:137], v[190:193], v[52:55]
	v_mfma_f32_16x16x32_bf16 v[48:51], v[164:167], v[190:193], v[48:51]
	v_mfma_f32_16x16x32_bf16 v[44:47], v[134:137], v[198:201], v[44:47]
	v_mfma_f32_16x16x32_bf16 v[40:43], v[164:167], v[198:201], v[40:43]
	v_mfma_f32_16x16x32_bf16 v[36:39], v[134:137], v[206:209], v[36:39]
	v_mfma_f32_16x16x32_bf16 v[32:35], v[164:167], v[206:209], v[32:35]
	v_mfma_f32_16x16x32_bf16 v[60:63], v[138:141], v[186:189], v[60:63]
	v_mfma_f32_16x16x32_bf16 v[56:59], v[178:181], v[186:189], v[56:59]
	v_mfma_f32_16x16x32_bf16 v[52:55], v[138:141], v[194:197], v[52:55]
	v_mfma_f32_16x16x32_bf16 v[48:51], v[178:181], v[194:197], v[48:51]
	v_mfma_f32_16x16x32_bf16 v[44:47], v[138:141], v[202:205], v[44:47]
	v_mfma_f32_16x16x32_bf16 v[40:43], v[178:181], v[202:205], v[40:43]
	v_mfma_f32_16x16x32_bf16 v[36:39], v[138:141], v[210:213], v[36:39]
	v_mfma_f32_16x16x32_bf16 v[32:35], v[178:181], v[210:213], v[32:35]
	v_mfma_f32_16x16x32_bf16 v[28:31], v[130:133], v[182:185], v[28:31]
	v_mfma_f32_16x16x32_bf16 v[24:27], v[214:217], v[182:185], v[24:27]
	v_mfma_f32_16x16x32_bf16 v[20:23], v[130:133], v[190:193], v[20:23]
	v_mfma_f32_16x16x32_bf16 v[16:19], v[214:217], v[190:193], v[16:19]
	v_mfma_f32_16x16x32_bf16 v[12:15], v[130:133], v[198:201], v[12:15]
	v_mfma_f32_16x16x32_bf16 v[8:11], v[214:217], v[198:201], v[8:11]
	v_mfma_f32_16x16x32_bf16 v[4:7], v[130:133], v[206:209], v[4:7]
	v_mfma_f32_16x16x32_bf16 v[0:3], v[214:217], v[206:209], v[0:3]
	v_mfma_f32_16x16x32_bf16 v[28:31], v[172:175], v[186:189], v[28:31]
	v_mfma_f32_16x16x32_bf16 v[24:27], v[168:171], v[186:189], v[24:27]
	v_mfma_f32_16x16x32_bf16 v[20:23], v[172:175], v[194:197], v[20:23]
	v_mfma_f32_16x16x32_bf16 v[16:19], v[168:171], v[194:197], v[16:19]
	v_mfma_f32_16x16x32_bf16 v[12:15], v[172:175], v[202:205], v[12:15]
	v_mfma_f32_16x16x32_bf16 v[8:11], v[168:171], v[202:205], v[8:11]
	v_mfma_f32_16x16x32_bf16 v[4:7], v[172:175], v[210:213], v[4:7]
	v_mfma_f32_16x16x32_bf16 v[0:3], v[168:171], v[210:213], v[0:3]
	s_barrier
	ds_read_b128 v[130:133], v163
	ds_read_b128 v[134:137], v163 offset:1024
	ds_read_b128 v[138:141], v163 offset:2048
	ds_read_b128 v[162:165], v163 offset:3072
	ds_read_b128 v[166:169], v159 offset:32768
	ds_read_b128 v[170:173], v159 offset:33792
	ds_read_b128 v[174:177], v158 offset:32768
	ds_read_b128 v[178:181], v158 offset:33792
	ds_read_b128 v[182:185], v157 offset:32768
	ds_read_b128 v[186:189], v157 offset:33792
	ds_read_b128 v[190:193], v156 offset:32768
	ds_read_b128 v[194:197], v156 offset:33792
	s_waitcnt vmcnt(2)
	s_barrier
	s_waitcnt lgkmcnt(0)
	s_waitcnt lgkmcnt(0)
	v_mfma_f32_16x16x32_bf16 v[124:127], v[130:133], v[166:169], v[124:127]
	v_mfma_f32_16x16x32_bf16 v[120:123], v[138:141], v[166:169], v[120:123]
	v_mfma_f32_16x16x32_bf16 v[116:119], v[130:133], v[174:177], v[116:119]
	v_mfma_f32_16x16x32_bf16 v[112:115], v[138:141], v[174:177], v[112:115]
	v_mfma_f32_16x16x32_bf16 v[108:111], v[130:133], v[182:185], v[108:111]
	v_mfma_f32_16x16x32_bf16 v[104:107], v[138:141], v[182:185], v[104:107]
	v_mfma_f32_16x16x32_bf16 v[100:103], v[130:133], v[190:193], v[100:103]
	v_mfma_f32_16x16x32_bf16 v[96:99], v[138:141], v[190:193], v[96:99]
	v_mfma_f32_16x16x32_bf16 v[124:127], v[134:137], v[170:173], v[124:127]
	v_mfma_f32_16x16x32_bf16 v[120:123], v[162:165], v[170:173], v[120:123]
	v_mfma_f32_16x16x32_bf16 v[116:119], v[134:137], v[178:181], v[116:119]
	v_mfma_f32_16x16x32_bf16 v[112:115], v[162:165], v[178:181], v[112:115]
	v_mfma_f32_16x16x32_bf16 v[108:111], v[134:137], v[186:189], v[108:111]
	v_mfma_f32_16x16x32_bf16 v[104:107], v[162:165], v[186:189], v[104:107]
	v_mfma_f32_16x16x32_bf16 v[100:103], v[134:137], v[194:197], v[100:103]
	v_mfma_f32_16x16x32_bf16 v[96:99], v[162:165], v[194:197], v[96:99]
	s_barrier
	ds_read_b128 v[198:201], v160
	ds_read_b128 v[202:205], v160 offset:1024
	ds_read_b128 v[206:209], v160 offset:2048
	ds_read_b128 v[210:213], v160 offset:3072
	s_waitcnt vmcnt(0)
	s_barrier
	s_waitcnt lgkmcnt(0)
	s_waitcnt lgkmcnt(0)
	v_mfma_f32_16x16x32_bf16 v[92:95], v[198:201], v[166:169], v[92:95]
	v_mfma_f32_16x16x32_bf16 v[88:91], v[206:209], v[166:169], v[88:91]
	v_mfma_f32_16x16x32_bf16 v[84:87], v[198:201], v[174:177], v[84:87]
	v_mfma_f32_16x16x32_bf16 v[80:83], v[206:209], v[174:177], v[80:83]
	v_mfma_f32_16x16x32_bf16 v[76:79], v[198:201], v[182:185], v[76:79]
	v_mfma_f32_16x16x32_bf16 v[72:75], v[206:209], v[182:185], v[72:75]
	v_mfma_f32_16x16x32_bf16 v[68:71], v[198:201], v[190:193], v[68:71]
	v_mfma_f32_16x16x32_bf16 v[64:67], v[206:209], v[190:193], v[64:67]
	v_mfma_f32_16x16x32_bf16 v[92:95], v[202:205], v[170:173], v[92:95]
	v_mfma_f32_16x16x32_bf16 v[88:91], v[210:213], v[170:173], v[88:91]
	v_mfma_f32_16x16x32_bf16 v[84:87], v[202:205], v[178:181], v[84:87]
	v_mfma_f32_16x16x32_bf16 v[80:83], v[210:213], v[178:181], v[80:83]
	v_mfma_f32_16x16x32_bf16 v[76:79], v[202:205], v[186:189], v[76:79]
	v_mfma_f32_16x16x32_bf16 v[72:75], v[210:213], v[186:189], v[72:75]
	v_mfma_f32_16x16x32_bf16 v[68:71], v[202:205], v[194:197], v[68:71]
	v_mfma_f32_16x16x32_bf16 v[64:67], v[210:213], v[194:197], v[64:67]
	s_barrier
	ds_read_b128 v[166:169], v159 offset:49152
	ds_read_b128 v[170:173], v159 offset:50176
	ds_read_b128 v[174:177], v158 offset:49152
	ds_read_b128 v[158:161], v158 offset:50176
	ds_read_b128 v[178:181], v157 offset:49152
	ds_read_b128 v[182:185], v157 offset:50176
	ds_read_b128 v[186:189], v156 offset:49152
	ds_read_b128 v[190:193], v156 offset:50176
	s_barrier
	s_waitcnt lgkmcnt(0)
	s_waitcnt lgkmcnt(0)
	v_mfma_f32_16x16x32_bf16 v[60:63], v[130:133], v[166:169], v[60:63]
	v_mfma_f32_16x16x32_bf16 v[56:59], v[138:141], v[166:169], v[56:59]
	v_mfma_f32_16x16x32_bf16 v[52:55], v[130:133], v[174:177], v[52:55]
	v_mfma_f32_16x16x32_bf16 v[48:51], v[138:141], v[174:177], v[48:51]
	v_mfma_f32_16x16x32_bf16 v[44:47], v[130:133], v[178:181], v[44:47]
	v_mfma_f32_16x16x32_bf16 v[40:43], v[138:141], v[178:181], v[40:43]
	v_mfma_f32_16x16x32_bf16 v[36:39], v[130:133], v[186:189], v[36:39]
	v_mfma_f32_16x16x32_bf16 v[32:35], v[138:141], v[186:189], v[32:35]
	v_mfma_f32_16x16x32_bf16 v[60:63], v[134:137], v[170:173], v[60:63]
	v_mfma_f32_16x16x32_bf16 v[56:59], v[162:165], v[170:173], v[56:59]
	v_mfma_f32_16x16x32_bf16 v[52:55], v[134:137], v[158:161], v[52:55]
	v_mfma_f32_16x16x32_bf16 v[48:51], v[162:165], v[158:161], v[48:51]
	v_mfma_f32_16x16x32_bf16 v[44:47], v[134:137], v[182:185], v[44:47]
	v_mfma_f32_16x16x32_bf16 v[40:43], v[162:165], v[182:185], v[40:43]
	v_mfma_f32_16x16x32_bf16 v[36:39], v[134:137], v[190:193], v[36:39]
	v_mfma_f32_16x16x32_bf16 v[32:35], v[162:165], v[190:193], v[32:35]
	v_mfma_f32_16x16x32_bf16 v[28:31], v[198:201], v[166:169], v[28:31]
	v_mfma_f32_16x16x32_bf16 v[24:27], v[206:209], v[166:169], v[24:27]
	v_mfma_f32_16x16x32_bf16 v[20:23], v[198:201], v[174:177], v[20:23]
	v_mfma_f32_16x16x32_bf16 v[16:19], v[206:209], v[174:177], v[16:19]
	v_mfma_f32_16x16x32_bf16 v[12:15], v[198:201], v[178:181], v[12:15]
	v_mfma_f32_16x16x32_bf16 v[8:11], v[206:209], v[178:181], v[8:11]
	v_mfma_f32_16x16x32_bf16 v[4:7], v[198:201], v[186:189], v[4:7]
	v_mfma_f32_16x16x32_bf16 v[0:3], v[206:209], v[186:189], v[0:3]
	v_mfma_f32_16x16x32_bf16 v[28:31], v[202:205], v[170:173], v[28:31]
	v_mfma_f32_16x16x32_bf16 v[24:27], v[210:213], v[170:173], v[24:27]
	v_mfma_f32_16x16x32_bf16 v[20:23], v[202:205], v[158:161], v[20:23]
	v_mfma_f32_16x16x32_bf16 v[16:19], v[210:213], v[158:161], v[16:19]
	v_mfma_f32_16x16x32_bf16 v[12:15], v[202:205], v[182:185], v[12:15]
	v_mfma_f32_16x16x32_bf16 v[8:11], v[210:213], v[182:185], v[8:11]
	v_mfma_f32_16x16x32_bf16 v[4:7], v[202:205], v[190:193], v[4:7]
	v_mfma_f32_16x16x32_bf16 v[0:3], v[210:213], v[190:193], v[0:3]
	v_cmp_gt_u32_e32 vcc, s52, v143
	s_barrier
	s_and_saveexec_b64 s[38:39], vcc
	s_cbranch_execz .LBB0_1800
	s_barrier
	s_branch .LBB0_1800

.LBB0_1869:
	ds_read_b128 v[180:183], v177
	ds_read_b128 v[184:187], v177 offset:1024
	ds_read_b128 v[188:191], v177 offset:2048
	ds_read_b128 v[192:195], v177 offset:3072
	v_add_u32_e32 v178, 0xc000, v164
	v_lshl_add_u64 v[244:245], s[4:5], 0, v[144:145]
	v_readfirstlane_b32 s41, v178
	v_add_u32_e32 v179, 0xe000, v164
	v_lshl_add_u64 v[228:229], v[244:245], 0, s[12:13]
	s_mov_b32 m0, s41
	v_lshl_add_u64 v[246:247], s[4:5], 0, v[142:143]
	v_readfirstlane_b32 s41, v179
	ds_read_b128 v[196:199], v161
	ds_read_b128 v[200:203], v161 offset:1024
	ds_read_b128 v[204:207], v160
	ds_read_b128 v[208:211], v160 offset:1024
	ds_read_b128 v[212:215], v159
	ds_read_b128 v[216:219], v159 offset:1024
	ds_read_b128 v[220:223], v158
	ds_read_b128 v[224:227], v158 offset:1024
	global_load_lds_dwordx4 v[228:229], off
	v_lshl_add_u64 v[228:229], v[246:247], 0, s[12:13]
	s_mov_b32 m0, s41
	s_nop 0
	global_load_lds_dwordx4 v[228:229], off
	s_waitcnt lgkmcnt(8)
	s_barrier
	s_waitcnt lgkmcnt(0)
	s_waitcnt lgkmcnt(0)
	v_mfma_f32_16x16x32_bf16 v[124:127], v[180:183], v[196:199], v[124:127]
	v_mfma_f32_16x16x32_bf16 v[120:123], v[188:191], v[196:199], v[120:123]
	v_mfma_f32_16x16x32_bf16 v[116:119], v[180:183], v[204:207], v[116:119]
	v_mfma_f32_16x16x32_bf16 v[112:115], v[188:191], v[204:207], v[112:115]
	v_mfma_f32_16x16x32_bf16 v[108:111], v[180:183], v[212:215], v[108:111]
	v_mfma_f32_16x16x32_bf16 v[104:107], v[188:191], v[212:215], v[104:107]
	v_mfma_f32_16x16x32_bf16 v[100:103], v[180:183], v[220:223], v[100:103]
	v_mfma_f32_16x16x32_bf16 v[96:99], v[188:191], v[220:223], v[96:99]
	v_mfma_f32_16x16x32_bf16 v[124:127], v[184:187], v[200:203], v[124:127]
	v_mfma_f32_16x16x32_bf16 v[120:123], v[192:195], v[200:203], v[120:123]
	v_mfma_f32_16x16x32_bf16 v[116:119], v[184:187], v[208:211], v[116:119]
	v_mfma_f32_16x16x32_bf16 v[112:115], v[192:195], v[208:211], v[112:115]
	v_mfma_f32_16x16x32_bf16 v[108:111], v[184:187], v[216:219], v[108:111]
	v_mfma_f32_16x16x32_bf16 v[104:107], v[192:195], v[216:219], v[104:107]
	v_mfma_f32_16x16x32_bf16 v[100:103], v[184:187], v[224:227], v[100:103]
	v_mfma_f32_16x16x32_bf16 v[96:99], v[192:195], v[224:227], v[96:99]
	s_barrier
	v_lshl_add_u64 v[248:249], s[4:5], 0, v[140:141]
	v_readfirstlane_b32 s41, v162
	v_lshl_add_u64 v[250:251], v[248:249], 0, s[14:15]
	s_mov_b32 m0, s41
	v_add_u32_e32 v254, 0x2000, v162
	ds_read_b128 v[228:231], v173
	ds_read_b128 v[232:235], v173 offset:1024
	ds_read_b128 v[236:239], v173 offset:2048
	ds_read_b128 v[240:243], v173 offset:3072
	global_load_lds_dwordx4 v[250:251], off
	v_lshl_add_u64 v[250:251], s[4:5], 0, v[138:139]
	v_readfirstlane_b32 s41, v254
	v_lshl_add_u64 v[252:253], v[250:251], 0, s[14:15]
	s_mov_b32 m0, s41
	s_nop 0
	global_load_lds_dwordx4 v[252:253], off
	s_barrier
	s_waitcnt lgkmcnt(0)
	s_waitcnt lgkmcnt(0)
	v_mfma_f32_16x16x32_bf16 v[92:95], v[228:231], v[196:199], v[92:95]
	v_mfma_f32_16x16x32_bf16 v[88:91], v[236:239], v[196:199], v[88:91]
	v_mfma_f32_16x16x32_bf16 v[84:87], v[228:231], v[204:207], v[84:87]
	v_mfma_f32_16x16x32_bf16 v[80:83], v[236:239], v[204:207], v[80:83]
	v_mfma_f32_16x16x32_bf16 v[76:79], v[228:231], v[212:215], v[76:79]
	v_mfma_f32_16x16x32_bf16 v[72:75], v[236:239], v[212:215], v[72:75]
	v_mfma_f32_16x16x32_bf16 v[68:71], v[228:231], v[220:223], v[68:71]
	v_mfma_f32_16x16x32_bf16 v[64:67], v[236:239], v[220:223], v[64:67]
	v_mfma_f32_16x16x32_bf16 v[92:95], v[232:235], v[200:203], v[92:95]
	v_mfma_f32_16x16x32_bf16 v[88:91], v[240:243], v[200:203], v[88:91]
	v_mfma_f32_16x16x32_bf16 v[84:87], v[232:235], v[208:211], v[84:87]
	v_mfma_f32_16x16x32_bf16 v[80:83], v[240:243], v[208:211], v[80:83]
	v_mfma_f32_16x16x32_bf16 v[76:79], v[232:235], v[216:219], v[76:79]
	v_mfma_f32_16x16x32_bf16 v[72:75], v[240:243], v[216:219], v[72:75]
	v_mfma_f32_16x16x32_bf16 v[68:71], v[232:235], v[224:227], v[68:71]
	v_mfma_f32_16x16x32_bf16 v[64:67], v[240:243], v[224:227], v[64:67]
	v_readfirstlane_b32 s41, v164
	v_lshl_add_u64 v[252:253], v[244:245], 0, s[16:17]
	s_mov_b32 m0, s41
	v_readfirstlane_b32 s41, v165
	s_barrier
	ds_read_b128 v[196:199], v161 offset:16384
	ds_read_b128 v[200:203], v161 offset:17408
	ds_read_b128 v[204:207], v160 offset:16384
	ds_read_b128 v[208:211], v160 offset:17408
	ds_read_b128 v[212:215], v159 offset:16384
	ds_read_b128 v[216:219], v159 offset:17408
	ds_read_b128 v[220:223], v158 offset:16384
	ds_read_b128 v[224:227], v158 offset:17408
	global_load_lds_dwordx4 v[252:253], off
	v_lshl_add_u64 v[252:253], v[246:247], 0, s[16:17]
	s_mov_b32 m0, s41
	s_nop 0
	global_load_lds_dwordx4 v[252:253], off
	s_barrier
	s_waitcnt lgkmcnt(0)
	s_waitcnt lgkmcnt(0)
	v_mfma_f32_16x16x32_bf16 v[60:63], v[180:183], v[196:199], v[60:63]
	v_mfma_f32_16x16x32_bf16 v[56:59], v[188:191], v[196:199], v[56:59]
	v_mfma_f32_16x16x32_bf16 v[52:55], v[180:183], v[204:207], v[52:55]
	v_mfma_f32_16x16x32_bf16 v[48:51], v[188:191], v[204:207], v[48:51]
	v_mfma_f32_16x16x32_bf16 v[44:47], v[180:183], v[212:215], v[44:47]
	v_mfma_f32_16x16x32_bf16 v[40:43], v[188:191], v[212:215], v[40:43]
	v_mfma_f32_16x16x32_bf16 v[36:39], v[180:183], v[220:223], v[36:39]
	v_mfma_f32_16x16x32_bf16 v[32:35], v[188:191], v[220:223], v[32:35]
	v_mfma_f32_16x16x32_bf16 v[60:63], v[184:187], v[200:203], v[60:63]
	v_mfma_f32_16x16x32_bf16 v[56:59], v[192:195], v[200:203], v[56:59]
	v_mfma_f32_16x16x32_bf16 v[52:55], v[184:187], v[208:211], v[52:55]
	v_mfma_f32_16x16x32_bf16 v[48:51], v[192:195], v[208:211], v[48:51]
	v_mfma_f32_16x16x32_bf16 v[44:47], v[184:187], v[216:219], v[44:47]
	v_mfma_f32_16x16x32_bf16 v[40:43], v[192:195], v[216:219], v[40:43]
	v_mfma_f32_16x16x32_bf16 v[36:39], v[184:187], v[224:227], v[36:39]
	v_mfma_f32_16x16x32_bf16 v[32:35], v[192:195], v[224:227], v[32:35]
	s_barrier
	v_readfirstlane_b32 s41, v167
	v_add_u32_e32 v182, 0x2000, v167
	v_lshl_add_u64 v[180:181], v[248:249], 0, s[18:19]
	s_mov_b32 m0, s41
	v_readfirstlane_b32 s41, v182
	global_load_lds_dwordx4 v[180:181], off
	v_lshl_add_u64 v[180:181], v[250:251], 0, s[18:19]
	s_mov_b32 m0, s41
	s_nop 0
	global_load_lds_dwordx4 v[180:181], off
	s_waitcnt vmcnt(6)
	s_barrier
	v_mfma_f32_16x16x32_bf16 v[28:31], v[228:231], v[196:199], v[28:31]
	v_mfma_f32_16x16x32_bf16 v[24:27], v[236:239], v[196:199], v[24:27]
	v_mfma_f32_16x16x32_bf16 v[20:23], v[228:231], v[204:207], v[20:23]
	v_mfma_f32_16x16x32_bf16 v[16:19], v[236:239], v[204:207], v[16:19]
	v_mfma_f32_16x16x32_bf16 v[12:15], v[228:231], v[212:215], v[12:15]
	v_mfma_f32_16x16x32_bf16 v[8:11], v[236:239], v[212:215], v[8:11]
	v_mfma_f32_16x16x32_bf16 v[4:7], v[228:231], v[220:223], v[4:7]
	v_mfma_f32_16x16x32_bf16 v[0:3], v[236:239], v[220:223], v[0:3]
	v_mfma_f32_16x16x32_bf16 v[28:31], v[232:235], v[200:203], v[28:31]
	v_mfma_f32_16x16x32_bf16 v[24:27], v[240:243], v[200:203], v[24:27]
	v_mfma_f32_16x16x32_bf16 v[20:23], v[232:235], v[208:211], v[20:23]
	v_mfma_f32_16x16x32_bf16 v[16:19], v[240:243], v[208:211], v[16:19]
	v_mfma_f32_16x16x32_bf16 v[12:15], v[232:235], v[216:219], v[12:15]
	v_mfma_f32_16x16x32_bf16 v[8:11], v[240:243], v[216:219], v[8:11]
	v_mfma_f32_16x16x32_bf16 v[4:7], v[232:235], v[224:227], v[4:7]
	v_mfma_f32_16x16x32_bf16 v[0:3], v[240:243], v[224:227], v[0:3]
	s_barrier
	ds_read_b128 v[180:183], v166
	ds_read_b128 v[184:187], v166 offset:1024
	ds_read_b128 v[188:191], v166 offset:2048
	ds_read_b128 v[192:195], v166 offset:3072
	v_readfirstlane_b32 s41, v168
	v_lshl_add_u64 v[228:229], v[244:245], 0, s[20:21]
	s_mov_b32 m0, s41
	v_readfirstlane_b32 s41, v169
	ds_read_b128 v[196:199], v161 offset:32768
	ds_read_b128 v[200:203], v161 offset:33792
	ds_read_b128 v[204:207], v160 offset:32768
	ds_read_b128 v[208:211], v160 offset:33792
	ds_read_b128 v[212:215], v159 offset:32768
	ds_read_b128 v[216:219], v159 offset:33792
	ds_read_b128 v[220:223], v158 offset:32768
	ds_read_b128 v[224:227], v158 offset:33792
	global_load_lds_dwordx4 v[228:229], off
	v_lshl_add_u64 v[228:229], v[246:247], 0, s[20:21]
	s_mov_b32 m0, s41
	s_nop 0
	global_load_lds_dwordx4 v[228:229], off
	s_waitcnt lgkmcnt(8)
	s_barrier
	s_waitcnt lgkmcnt(0)
	s_waitcnt lgkmcnt(0)
	v_mfma_f32_16x16x32_bf16 v[124:127], v[180:183], v[196:199], v[124:127]
	v_mfma_f32_16x16x32_bf16 v[120:123], v[188:191], v[196:199], v[120:123]
	v_mfma_f32_16x16x32_bf16 v[116:119], v[180:183], v[204:207], v[116:119]
	v_mfma_f32_16x16x32_bf16 v[112:115], v[188:191], v[204:207], v[112:115]
	v_mfma_f32_16x16x32_bf16 v[108:111], v[180:183], v[212:215], v[108:111]
	v_mfma_f32_16x16x32_bf16 v[104:107], v[188:191], v[212:215], v[104:107]
	v_mfma_f32_16x16x32_bf16 v[100:103], v[180:183], v[220:223], v[100:103]
	v_mfma_f32_16x16x32_bf16 v[96:99], v[188:191], v[220:223], v[96:99]
	v_mfma_f32_16x16x32_bf16 v[124:127], v[184:187], v[200:203], v[124:127]
	v_mfma_f32_16x16x32_bf16 v[120:123], v[192:195], v[200:203], v[120:123]
	v_mfma_f32_16x16x32_bf16 v[116:119], v[184:187], v[208:211], v[116:119]
	v_mfma_f32_16x16x32_bf16 v[112:115], v[192:195], v[208:211], v[112:115]
	v_mfma_f32_16x16x32_bf16 v[108:111], v[184:187], v[216:219], v[108:111]
	v_mfma_f32_16x16x32_bf16 v[104:107], v[192:195], v[216:219], v[104:107]
	v_mfma_f32_16x16x32_bf16 v[100:103], v[184:187], v[224:227], v[100:103]
	v_mfma_f32_16x16x32_bf16 v[96:99], v[192:195], v[224:227], v[96:99]
	s_barrier
	v_readfirstlane_b32 s41, v170
	v_lshl_add_u64 v[252:253], v[248:249], 0, s[22:23]
	s_mov_b32 m0, s41
	v_readfirstlane_b32 s41, v171
	ds_read_b128 v[228:231], v163
	ds_read_b128 v[232:235], v163 offset:1024
	ds_read_b128 v[236:239], v163 offset:2048
	ds_read_b128 v[240:243], v163 offset:3072
	global_load_lds_dwordx4 v[252:253], off
	v_lshl_add_u64 v[252:253], v[250:251], 0, s[22:23]
	s_mov_b32 m0, s41
	s_nop 0
	global_load_lds_dwordx4 v[252:253], off
	s_barrier
	s_waitcnt lgkmcnt(0)
	s_waitcnt lgkmcnt(0)
	v_mfma_f32_16x16x32_bf16 v[92:95], v[228:231], v[196:199], v[92:95]
	v_mfma_f32_16x16x32_bf16 v[88:91], v[236:239], v[196:199], v[88:91]
	v_mfma_f32_16x16x32_bf16 v[84:87], v[228:231], v[204:207], v[84:87]
	v_mfma_f32_16x16x32_bf16 v[80:83], v[236:239], v[204:207], v[80:83]
	v_mfma_f32_16x16x32_bf16 v[76:79], v[228:231], v[212:215], v[76:79]
	v_mfma_f32_16x16x32_bf16 v[72:75], v[236:239], v[212:215], v[72:75]
	v_mfma_f32_16x16x32_bf16 v[68:71], v[228:231], v[220:223], v[68:71]
	v_mfma_f32_16x16x32_bf16 v[64:67], v[236:239], v[220:223], v[64:67]
	v_mfma_f32_16x16x32_bf16 v[92:95], v[232:235], v[200:203], v[92:95]
	v_mfma_f32_16x16x32_bf16 v[88:91], v[240:243], v[200:203], v[88:91]
	v_mfma_f32_16x16x32_bf16 v[84:87], v[232:235], v[208:211], v[84:87]
	v_mfma_f32_16x16x32_bf16 v[80:83], v[240:243], v[208:211], v[80:83]
	v_mfma_f32_16x16x32_bf16 v[76:79], v[232:235], v[216:219], v[76:79]
	v_mfma_f32_16x16x32_bf16 v[72:75], v[240:243], v[216:219], v[72:75]
	v_mfma_f32_16x16x32_bf16 v[68:71], v[232:235], v[224:227], v[68:71]
	v_mfma_f32_16x16x32_bf16 v[64:67], v[240:243], v[224:227], v[64:67]
	v_readfirstlane_b32 s41, v172
	v_lshl_add_u64 v[244:245], v[244:245], 0, s[24:25]
	s_mov_b32 m0, s41
	v_readfirstlane_b32 s41, v174
	s_barrier
	ds_read_b128 v[196:199], v161 offset:49152
	ds_read_b128 v[200:203], v161 offset:50176
	ds_read_b128 v[204:207], v160 offset:49152
	ds_read_b128 v[208:211], v160 offset:50176
	ds_read_b128 v[212:215], v159 offset:49152
	ds_read_b128 v[216:219], v159 offset:50176
	ds_read_b128 v[220:223], v158 offset:49152
	ds_read_b128 v[224:227], v158 offset:50176
	global_load_lds_dwordx4 v[244:245], off
	v_lshl_add_u64 v[244:245], v[246:247], 0, s[24:25]
	s_mov_b32 m0, s41
	s_nop 0
	global_load_lds_dwordx4 v[244:245], off
	s_barrier
	s_waitcnt lgkmcnt(0)
	s_waitcnt lgkmcnt(0)
	v_mfma_f32_16x16x32_bf16 v[60:63], v[180:183], v[196:199], v[60:63]
	v_mfma_f32_16x16x32_bf16 v[56:59], v[188:191], v[196:199], v[56:59]
	v_mfma_f32_16x16x32_bf16 v[52:55], v[180:183], v[204:207], v[52:55]
	v_mfma_f32_16x16x32_bf16 v[48:51], v[188:191], v[204:207], v[48:51]
	v_mfma_f32_16x16x32_bf16 v[44:47], v[180:183], v[212:215], v[44:47]
	v_mfma_f32_16x16x32_bf16 v[40:43], v[188:191], v[212:215], v[40:43]
	v_mfma_f32_16x16x32_bf16 v[36:39], v[180:183], v[220:223], v[36:39]
	v_mfma_f32_16x16x32_bf16 v[32:35], v[188:191], v[220:223], v[32:35]
	v_mfma_f32_16x16x32_bf16 v[60:63], v[184:187], v[200:203], v[60:63]
	v_mfma_f32_16x16x32_bf16 v[56:59], v[192:195], v[200:203], v[56:59]
	v_mfma_f32_16x16x32_bf16 v[52:55], v[184:187], v[208:211], v[52:55]
	v_mfma_f32_16x16x32_bf16 v[48:51], v[192:195], v[208:211], v[48:51]
	v_mfma_f32_16x16x32_bf16 v[44:47], v[184:187], v[216:219], v[44:47]
	v_mfma_f32_16x16x32_bf16 v[40:43], v[192:195], v[216:219], v[40:43]
	v_mfma_f32_16x16x32_bf16 v[36:39], v[184:187], v[224:227], v[36:39]
	v_mfma_f32_16x16x32_bf16 v[32:35], v[192:195], v[224:227], v[32:35]
	s_barrier
	v_readfirstlane_b32 s41, v175
	v_lshl_add_u64 v[180:181], v[248:249], 0, s[26:27]
	s_mov_b32 m0, s41
	v_readfirstlane_b32 s41, v176
	global_load_lds_dwordx4 v[180:181], off
	v_lshl_add_u64 v[180:181], v[250:251], 0, s[26:27]
	s_mov_b32 m0, s41
	s_nop 0
	global_load_lds_dwordx4 v[180:181], off
	s_waitcnt vmcnt(6)
	s_barrier
	v_mfma_f32_16x16x32_bf16 v[28:31], v[228:231], v[196:199], v[28:31]
	v_mfma_f32_16x16x32_bf16 v[24:27], v[236:239], v[196:199], v[24:27]
	v_mfma_f32_16x16x32_bf16 v[20:23], v[228:231], v[204:207], v[20:23]
	v_mfma_f32_16x16x32_bf16 v[16:19], v[236:239], v[204:207], v[16:19]
	v_mfma_f32_16x16x32_bf16 v[12:15], v[228:231], v[212:215], v[12:15]
	v_mfma_f32_16x16x32_bf16 v[8:11], v[236:239], v[212:215], v[8:11]
	v_mfma_f32_16x16x32_bf16 v[4:7], v[228:231], v[220:223], v[4:7]
	v_mfma_f32_16x16x32_bf16 v[0:3], v[236:239], v[220:223], v[0:3]
	v_mfma_f32_16x16x32_bf16 v[28:31], v[232:235], v[200:203], v[28:31]
	v_mfma_f32_16x16x32_bf16 v[24:27], v[240:243], v[200:203], v[24:27]
	v_mfma_f32_16x16x32_bf16 v[20:23], v[232:235], v[208:211], v[20:23]
	v_mfma_f32_16x16x32_bf16 v[16:19], v[240:243], v[208:211], v[16:19]
	v_mfma_f32_16x16x32_bf16 v[12:15], v[232:235], v[216:219], v[12:15]
	v_mfma_f32_16x16x32_bf16 v[8:11], v[240:243], v[216:219], v[8:11]
	v_mfma_f32_16x16x32_bf16 v[4:7], v[232:235], v[224:227], v[4:7]
	v_mfma_f32_16x16x32_bf16 v[0:3], v[240:243], v[224:227], v[0:3]
	s_add_i32 s40, s40, 2
	v_lshl_add_u64 v[138:139], v[138:139], 0, s[28:29]
	v_lshl_add_u64 v[140:141], v[140:141], 0, s[28:29]
	v_lshl_add_u64 v[142:143], v[142:143], 0, s[28:29]
	s_cmp_lt_u32 s40, 40
	v_lshl_add_u64 v[144:145], v[144:145], 0, s[28:29]
	s_barrier
	s_cbranch_scc1 .LBB0_1869
	s_add_u32 s38, s38, 0x1580
	s_addc_u32 s39, s39, 0
	v_lshl_add_u64 v[132:133], v[132:133], 1, s[38:39]
	v_readfirstlane_b32 s40, v178
	v_lshl_add_u64 v[130:131], v[130:131], 1, v[132:133]
	s_mov_b32 m0, s40
	ds_read_b128 v[138:141], v177
	ds_read_b128 v[142:145], v177 offset:1024
	ds_read_b128 v[168:171], v177 offset:2048
	ds_read_b128 v[174:177], v177 offset:3072
	ds_read_b128 v[180:183], v161
	ds_read_b128 v[184:187], v161 offset:1024
	ds_read_b128 v[188:191], v160
	ds_read_b128 v[192:195], v160 offset:1024
	ds_read_b128 v[196:199], v159
	ds_read_b128 v[200:203], v159 offset:1024
	ds_read_b128 v[204:207], v158
	ds_read_b128 v[208:211], v158 offset:1024
	global_load_lds_dwordx4 v[130:131], off
	v_lshl_add_u64 v[130:131], v[136:137], 1, s[38:39]
	v_readfirstlane_b32 s38, v179
	v_lshl_add_u64 v[130:131], v[134:135], 1, v[130:131]
	s_mov_b32 m0, s38
	s_nop 0
	global_load_lds_dwordx4 v[130:131], off
	s_barrier
	s_waitcnt lgkmcnt(0)
	s_waitcnt lgkmcnt(0)
	v_mfma_f32_16x16x32_bf16 v[124:127], v[138:141], v[180:183], v[124:127]
	v_mfma_f32_16x16x32_bf16 v[120:123], v[168:171], v[180:183], v[120:123]
	v_mfma_f32_16x16x32_bf16 v[116:119], v[138:141], v[188:191], v[116:119]
	v_mfma_f32_16x16x32_bf16 v[108:111], v[138:141], v[196:199], v[108:111]
	v_mfma_f32_16x16x32_bf16 v[100:103], v[138:141], v[204:207], v[100:103]
	v_mfma_f32_16x16x32_bf16 v[124:127], v[142:145], v[184:187], v[124:127]
	v_mfma_f32_16x16x32_bf16 v[120:123], v[174:177], v[184:187], v[120:123]
	v_mfma_f32_16x16x32_bf16 v[116:119], v[142:145], v[192:195], v[116:119]
	v_mfma_f32_16x16x32_bf16 v[112:115], v[168:171], v[188:191], v[112:115]
	v_mfma_f32_16x16x32_bf16 v[108:111], v[142:145], v[200:203], v[108:111]
	v_mfma_f32_16x16x32_bf16 v[104:107], v[168:171], v[196:199], v[104:107]
	v_mfma_f32_16x16x32_bf16 v[100:103], v[142:145], v[208:211], v[100:103]
	v_mfma_f32_16x16x32_bf16 v[96:99], v[168:171], v[204:207], v[96:99]
	v_mfma_f32_16x16x32_bf16 v[130:133], v[174:177], v[192:195], v[112:115]
	v_mfma_f32_16x16x32_bf16 v[134:137], v[174:177], v[200:203], v[104:107]
	v_mfma_f32_16x16x32_bf16 v[212:215], v[174:177], v[208:211], v[96:99]
	s_barrier
	s_nop 2
	ds_read_b128 v[96:99], v173
	ds_read_b128 v[104:107], v173 offset:1024
	ds_read_b128 v[112:115], v173 offset:2048
	ds_read_b128 v[216:219], v173 offset:3072
	s_barrier
	s_waitcnt lgkmcnt(0)
	s_waitcnt lgkmcnt(0)
	v_mfma_f32_16x16x32_bf16 v[92:95], v[96:99], v[180:183], v[92:95]
	v_mfma_f32_16x16x32_bf16 v[88:91], v[112:115], v[180:183], v[88:91]
	v_mfma_f32_16x16x32_bf16 v[84:87], v[96:99], v[188:191], v[84:87]
	v_mfma_f32_16x16x32_bf16 v[76:79], v[96:99], v[196:199], v[76:79]
	v_mfma_f32_16x16x32_bf16 v[68:71], v[96:99], v[204:207], v[68:71]
	v_mfma_f32_16x16x32_bf16 v[92:95], v[104:107], v[184:187], v[92:95]
	v_mfma_f32_16x16x32_bf16 v[88:91], v[216:219], v[184:187], v[88:91]
	v_mfma_f32_16x16x32_bf16 v[84:87], v[104:107], v[192:195], v[84:87]
	v_mfma_f32_16x16x32_bf16 v[80:83], v[112:115], v[188:191], v[80:83]
	v_mfma_f32_16x16x32_bf16 v[76:79], v[104:107], v[200:203], v[76:79]
	v_mfma_f32_16x16x32_bf16 v[72:75], v[112:115], v[196:199], v[72:75]
	v_mfma_f32_16x16x32_bf16 v[68:71], v[104:107], v[208:211], v[68:71]
	v_mfma_f32_16x16x32_bf16 v[64:67], v[112:115], v[204:207], v[64:67]
	v_mfma_f32_16x16x32_bf16 v[178:181], v[216:219], v[192:195], v[80:83]
	v_mfma_f32_16x16x32_bf16 v[182:185], v[216:219], v[200:203], v[72:75]
	v_mfma_f32_16x16x32_bf16 v[186:189], v[216:219], v[208:211], v[64:67]
	s_barrier
	s_nop 2
	ds_read_b128 v[64:67], v161 offset:16384
	ds_read_b128 v[72:75], v161 offset:17408
	ds_read_b128 v[80:83], v160 offset:16384
	ds_read_b128 v[190:193], v160 offset:17408
	ds_read_b128 v[194:197], v159 offset:16384
	ds_read_b128 v[198:201], v159 offset:17408
	ds_read_b128 v[202:205], v158 offset:16384
	ds_read_b128 v[206:209], v158 offset:17408
	s_waitcnt vmcnt(4)
	s_barrier
	s_waitcnt lgkmcnt(0)
	s_waitcnt lgkmcnt(0)
	v_mfma_f32_16x16x32_bf16 v[60:63], v[138:141], v[64:67], v[60:63]
	v_mfma_f32_16x16x32_bf16 v[56:59], v[168:171], v[64:67], v[56:59]
	v_mfma_f32_16x16x32_bf16 v[52:55], v[138:141], v[80:83], v[52:55]
	v_mfma_f32_16x16x32_bf16 v[44:47], v[138:141], v[194:197], v[44:47]
	v_mfma_f32_16x16x32_bf16 v[36:39], v[138:141], v[202:205], v[36:39]
	v_mfma_f32_16x16x32_bf16 v[60:63], v[142:145], v[72:75], v[60:63]
	v_mfma_f32_16x16x32_bf16 v[56:59], v[174:177], v[72:75], v[56:59]
	v_mfma_f32_16x16x32_bf16 v[52:55], v[142:145], v[190:193], v[52:55]
	v_mfma_f32_16x16x32_bf16 v[48:51], v[168:171], v[80:83], v[48:51]
	v_mfma_f32_16x16x32_bf16 v[44:47], v[142:145], v[198:201], v[44:47]
	v_mfma_f32_16x16x32_bf16 v[40:43], v[168:171], v[194:197], v[40:43]
	v_mfma_f32_16x16x32_bf16 v[36:39], v[142:145], v[206:209], v[36:39]
	v_mfma_f32_16x16x32_bf16 v[32:35], v[168:171], v[202:205], v[32:35]
	v_mfma_f32_16x16x32_bf16 v[220:223], v[174:177], v[190:193], v[48:51]
	v_mfma_f32_16x16x32_bf16 v[224:227], v[174:177], v[198:201], v[40:43]
	v_mfma_f32_16x16x32_bf16 v[138:141], v[174:177], v[206:209], v[32:35]
	v_mfma_f32_16x16x32_bf16 v[28:31], v[96:99], v[64:67], v[28:31]
	v_mfma_f32_16x16x32_bf16 v[24:27], v[112:115], v[64:67], v[24:27]
	v_mfma_f32_16x16x32_bf16 v[20:23], v[96:99], v[80:83], v[20:23]
	v_mfma_f32_16x16x32_bf16 v[12:15], v[96:99], v[194:197], v[12:15]
	v_mfma_f32_16x16x32_bf16 v[4:7], v[96:99], v[202:205], v[4:7]
	v_mfma_f32_16x16x32_bf16 v[28:31], v[104:107], v[72:75], v[28:31]
	v_mfma_f32_16x16x32_bf16 v[24:27], v[216:219], v[72:75], v[24:27]
	v_mfma_f32_16x16x32_bf16 v[20:23], v[104:107], v[190:193], v[20:23]
	v_mfma_f32_16x16x32_bf16 v[16:19], v[112:115], v[80:83], v[16:19]
	v_mfma_f32_16x16x32_bf16 v[12:15], v[104:107], v[198:201], v[12:15]
	v_mfma_f32_16x16x32_bf16 v[8:11], v[112:115], v[194:197], v[8:11]
	v_mfma_f32_16x16x32_bf16 v[4:7], v[104:107], v[206:209], v[4:7]
	v_mfma_f32_16x16x32_bf16 v[0:3], v[112:115], v[202:205], v[0:3]
	v_mfma_f32_16x16x32_bf16 v[142:145], v[216:219], v[190:193], v[16:19]
	v_mfma_f32_16x16x32_bf16 v[168:171], v[216:219], v[198:201], v[8:11]
	v_mfma_f32_16x16x32_bf16 v[172:175], v[216:219], v[206:209], v[0:3]
	s_barrier
	s_nop 2
	ds_read_b128 v[0:3], v166
	ds_read_b128 v[8:11], v166 offset:1024
	ds_read_b128 v[16:19], v166 offset:2048
	ds_read_b128 v[164:167], v166 offset:3072
	ds_read_b128 v[32:35], v161 offset:32768
	ds_read_b128 v[40:43], v161 offset:33792
	ds_read_b128 v[48:51], v160 offset:32768
	ds_read_b128 v[64:67], v160 offset:33792
	ds_read_b128 v[190:193], v159 offset:32768
	ds_read_b128 v[194:197], v159 offset:33792
	ds_read_b128 v[198:201], v158 offset:32768
	ds_read_b128 v[202:205], v158 offset:33792
	s_waitcnt vmcnt(2)
	s_barrier
	s_waitcnt lgkmcnt(0)
	s_waitcnt lgkmcnt(0)
	v_mfma_f32_16x16x32_bf16 v[72:75], v[0:3], v[32:35], v[124:127]
	v_mfma_f32_16x16x32_bf16 v[124:127], v[8:11], v[40:43], v[72:75]
	v_mfma_f32_16x16x32_bf16 v[72:75], v[16:19], v[32:35], v[120:123]
	v_mfma_f32_16x16x32_bf16 v[120:123], v[164:167], v[40:43], v[72:75]
	v_mfma_f32_16x16x32_bf16 v[72:75], v[0:3], v[48:51], v[116:119]
	v_mfma_f32_16x16x32_bf16 v[112:115], v[8:11], v[64:67], v[72:75]
	v_mfma_f32_16x16x32_bf16 v[72:75], v[16:19], v[48:51], v[130:133]
	v_mfma_f32_16x16x32_bf16 v[116:119], v[164:167], v[64:67], v[72:75]
	v_mfma_f32_16x16x32_bf16 v[72:75], v[0:3], v[190:193], v[108:111]
	v_mfma_f32_16x16x32_bf16 v[104:107], v[8:11], v[194:197], v[72:75]
	v_mfma_f32_16x16x32_bf16 v[72:75], v[16:19], v[190:193], v[134:137]
	v_mfma_f32_16x16x32_bf16 v[108:111], v[164:167], v[194:197], v[72:75]
	v_mfma_f32_16x16x32_bf16 v[72:75], v[0:3], v[198:201], v[100:103]
	v_mfma_f32_16x16x32_bf16 v[96:99], v[8:11], v[202:205], v[72:75]
	v_mfma_f32_16x16x32_bf16 v[72:75], v[16:19], v[198:201], v[212:215]
	v_mfma_f32_16x16x32_bf16 v[100:103], v[164:167], v[202:205], v[72:75]
	s_barrier
	ds_read_b128 v[130:133], v163
	ds_read_b128 v[134:137], v163 offset:1024
	ds_read_b128 v[206:209], v163 offset:2048
	ds_read_b128 v[210:213], v163 offset:3072
	s_waitcnt vmcnt(0)
	s_barrier
	s_waitcnt lgkmcnt(0)
	s_waitcnt lgkmcnt(0)
	v_mfma_f32_16x16x32_bf16 v[72:75], v[130:133], v[32:35], v[92:95]
	v_mfma_f32_16x16x32_bf16 v[32:35], v[206:209], v[32:35], v[88:91]
	v_mfma_f32_16x16x32_bf16 v[88:91], v[210:213], v[40:43], v[32:35]
	v_mfma_f32_16x16x32_bf16 v[32:35], v[130:133], v[48:51], v[84:87]
	v_mfma_f32_16x16x32_bf16 v[80:83], v[134:137], v[64:67], v[32:35]
	v_mfma_f32_16x16x32_bf16 v[32:35], v[206:209], v[48:51], v[178:181]
	v_mfma_f32_16x16x32_bf16 v[84:87], v[210:213], v[64:67], v[32:35]
	v_mfma_f32_16x16x32_bf16 v[32:35], v[130:133], v[190:193], v[76:79]
	v_mfma_f32_16x16x32_bf16 v[92:95], v[134:137], v[40:43], v[72:75]
	v_mfma_f32_16x16x32_bf16 v[72:75], v[134:137], v[194:197], v[32:35]
	v_mfma_f32_16x16x32_bf16 v[32:35], v[206:209], v[190:193], v[182:185]
	v_mfma_f32_16x16x32_bf16 v[76:79], v[210:213], v[194:197], v[32:35]
	v_mfma_f32_16x16x32_bf16 v[32:35], v[130:133], v[198:201], v[68:71]
	v_mfma_f32_16x16x32_bf16 v[64:67], v[134:137], v[202:205], v[32:35]
	v_mfma_f32_16x16x32_bf16 v[32:35], v[206:209], v[198:201], v[186:189]
	v_mfma_f32_16x16x32_bf16 v[68:71], v[210:213], v[202:205], v[32:35]
	s_barrier
	ds_read_b128 v[176:179], v161 offset:49152
	ds_read_b128 v[180:183], v161 offset:50176
	ds_read_b128 v[184:187], v160 offset:49152
	ds_read_b128 v[160:163], v160 offset:50176
	ds_read_b128 v[188:191], v159 offset:49152
	ds_read_b128 v[192:195], v159 offset:50176
	ds_read_b128 v[196:199], v158 offset:49152
	ds_read_b128 v[200:203], v158 offset:50176
	s_barrier
	s_waitcnt lgkmcnt(0)
	s_waitcnt lgkmcnt(0)
	v_mfma_f32_16x16x32_bf16 v[32:35], v[0:3], v[176:179], v[60:63]
	v_mfma_f32_16x16x32_bf16 v[60:63], v[8:11], v[180:183], v[32:35]
	v_mfma_f32_16x16x32_bf16 v[32:35], v[16:19], v[176:179], v[56:59]
	v_mfma_f32_16x16x32_bf16 v[56:59], v[164:167], v[180:183], v[32:35]
	v_mfma_f32_16x16x32_bf16 v[32:35], v[0:3], v[184:187], v[52:55]
	v_mfma_f32_16x16x32_bf16 v[48:51], v[8:11], v[160:163], v[32:35]
	v_mfma_f32_16x16x32_bf16 v[32:35], v[16:19], v[184:187], v[220:223]
	v_mfma_f32_16x16x32_bf16 v[52:55], v[164:167], v[160:163], v[32:35]
	v_mfma_f32_16x16x32_bf16 v[32:35], v[0:3], v[188:191], v[44:47]
	v_mfma_f32_16x16x32_bf16 v[40:43], v[8:11], v[192:195], v[32:35]
	v_mfma_f32_16x16x32_bf16 v[32:35], v[16:19], v[188:191], v[224:227]
	v_mfma_f32_16x16x32_bf16 v[0:3], v[0:3], v[196:199], v[36:39]
	v_mfma_f32_16x16x32_bf16 v[44:47], v[164:167], v[192:195], v[32:35]
	v_mfma_f32_16x16x32_bf16 v[32:35], v[8:11], v[200:203], v[0:3]
	v_mfma_f32_16x16x32_bf16 v[0:3], v[16:19], v[196:199], v[138:141]
	v_mfma_f32_16x16x32_bf16 v[36:39], v[164:167], v[200:203], v[0:3]
	v_mfma_f32_16x16x32_bf16 v[0:3], v[130:133], v[176:179], v[28:31]
	v_mfma_f32_16x16x32_bf16 v[28:31], v[134:137], v[180:183], v[0:3]
	v_mfma_f32_16x16x32_bf16 v[0:3], v[206:209], v[176:179], v[24:27]
	v_mfma_f32_16x16x32_bf16 v[24:27], v[210:213], v[180:183], v[0:3]
	v_mfma_f32_16x16x32_bf16 v[0:3], v[130:133], v[184:187], v[20:23]
	v_mfma_f32_16x16x32_bf16 v[16:19], v[134:137], v[160:163], v[0:3]
	v_mfma_f32_16x16x32_bf16 v[0:3], v[206:209], v[184:187], v[142:145]
	v_mfma_f32_16x16x32_bf16 v[20:23], v[210:213], v[160:163], v[0:3]
	v_mfma_f32_16x16x32_bf16 v[0:3], v[130:133], v[188:191], v[12:15]
	v_mfma_f32_16x16x32_bf16 v[8:11], v[134:137], v[192:195], v[0:3]
	v_mfma_f32_16x16x32_bf16 v[0:3], v[206:209], v[188:191], v[168:171]
	v_mfma_f32_16x16x32_bf16 v[12:15], v[210:213], v[192:195], v[0:3]
	v_mfma_f32_16x16x32_bf16 v[0:3], v[130:133], v[196:199], v[4:7]
	v_mfma_f32_16x16x32_bf16 v[4:7], v[206:209], v[196:199], v[172:175]
	v_mfma_f32_16x16x32_bf16 v[0:3], v[134:137], v[200:203], v[0:3]
	v_mfma_f32_16x16x32_bf16 v[4:7], v[210:213], v[200:203], v[4:7]
	v_cmp_gt_u32_e32 vcc, s55, v128
	s_barrier
	s_and_saveexec_b64 s[38:39], vcc
	s_cbranch_execz .LBB0_1863
	s_barrier
	s_branch .LBB0_1863
